# cache policy: nt hint on once-read streaming loads (xconvert, weight prep, LayerNorm inputs, GLA finish inputs, gate x rows); code addresses unchanged (stacked on v17)
# speedup vs baseline: 1.0018x; 1.0018x over previous
; DI unsigned pk2(float lo, float hi) { f32x2 f = {lo, hi}; bf2_t v = __builtin_convertvector(f, bf2_t); return __builtin_bit_cast(unsigned, v); }
; DI int mk_tid(int wv) { int w = wv; asm volatile("" : "+s"(w)); int l = __builtin_amdgcn_mbcnt_hi(~0u, __builtin_amdgcn_mbcnt_lo(~0u, 0u)); asm volatile("" : "+v"(l)); return w * 64 + l; }
; DI int opaque_bid() { int b = blockIdx.x; asm volatile("" : "+s"(b)); return b; }
; DI void xconvert(int wv, const float* x, bf16_t* xb) {
;     ...
;     for (size_t i = (size_t)opaque_bid() * 512 + mk_tid(wv); i < n8; i += 4 * st_) {
;         f32x4 a[4], b[4];
; #pragma unroll
;         for (int u = 0; u < 4; ++u) { const size_t j = (i + u * st_ < n8) ? i + u * st_ : i; a[u] = ((const f32x4*)x)[2 * j]; b[u] = ((const f32x4*)x)[2 * j + 1]; }
; #pragma unroll
;         for (int u = 0; u < 4; ++u) if (i + u * st_ < n8) { u32x4 w; w.x = pk2(a[u].x, a[u].y); w.y = pk2(a[u].z, a[u].w); w.z = pk2(b[u].x, b[u].y); w.w = pk2(b[u].z, b[u].w);
;             ((u32x4*)xb)[i + u * st_] = w; }
;     }
.LBB0_8:
	v_lshl_add_u64 v[36:37], v[6:7], 0, s[18:19]
	v_cmp_gt_u64_e64 s[4:5], s[10:11], v[36:37]
	s_nop 1
	v_cndmask_b32_e64 v3, v7, v37, s[4:5]
	v_cndmask_b32_e64 v2, v6, v36, s[4:5]
	v_lshlrev_b64 v[2:3], 5, v[2:3]
	v_lshl_add_u64 v[2:3], s[14:15], 0, v[2:3]
	global_load_dwordx4 v[18:21], v[2:3], off offset:16 nt
	global_load_dwordx4 v[22:25], v[2:3], off nt
	v_lshl_add_u64 v[2:3], s[24:25], 0, v[6:7]
	v_cmp_gt_u64_e32 vcc, s[10:11], v[2:3]
	s_nop 1
	v_cndmask_b32_e32 v3, v7, v3, vcc
	v_cndmask_b32_e32 v2, v6, v2, vcc
	v_lshlrev_b64 v[2:3], 5, v[2:3]
	v_lshl_add_u64 v[8:9], s[14:15], 0, v[2:3]
	global_load_dwordx4 v[2:5], v[8:9], off offset:16 nt
	global_load_dwordx4 v[10:13], v[8:9], off nt
	v_lshl_add_u64 v[8:9], s[26:27], 0, v[6:7]
	v_cmp_gt_u64_e64 s[0:1], s[10:11], v[8:9]
	global_load_dwordx4 v[40:43], v[30:31], off nt
	global_load_dwordx4 v[44:47], v[30:31], off offset:-16 nt
	v_cndmask_b32_e64 v7, v7, v9, s[0:1]
	v_cndmask_b32_e64 v6, v6, v8, s[0:1]
	v_lshlrev_b64 v[6:7], 5, v[6:7]
	v_lshl_add_u64 v[48:49], s[14:15], 0, v[6:7]
	global_load_dwordx4 v[6:9], v[48:49], off offset:16 nt
	global_load_dwordx4 v[14:17], v[48:49], off nt
	s_waitcnt vmcnt(2)
	v_cvt_pk_bf16_f32 v44, v44, v45
	v_cvt_pk_bf16_f32 v45, v46, v47
	v_cvt_pk_bf16_f32 v46, v40, v41
	v_cvt_pk_bf16_f32 v47, v42, v43
	v_lshl_add_u64 v[40:41], s[16:17], 0, v[28:29]
	global_store_dwordx4 v[40:41], v[44:47], off
	s_and_saveexec_b64 s[30:31], s[4:5]
	s_cbranch_execz .LBB0_11
	v_cvt_pk_bf16_f32 v22, v22, v23
	v_cvt_pk_bf16_f32 v23, v24, v25
	v_cvt_pk_bf16_f32 v24, v18, v19
	v_cvt_pk_bf16_f32 v25, v20, v21
	v_lshl_add_u64 v[18:19], s[16:17], 0, v[26:27]
	global_store_dwordx4 v[18:19], v[22:25], off
	s_or_b64 exec, exec, s[30:31]
	s_and_saveexec_b64 s[4:5], vcc
	s_cbranch_execnz .LBB0_12

; #define LAS __attribute__((address_space(3)))
; #define scr (p.ws + opq_off(SCR_OFF))
; DI void transpose_item(const float* W, int K, int ldw, int nblk, bf16_t* WT, LAS float* scr, int item, int lane) {
;     const int kb = item / nblk, nb = item % nblk, k0 = 64 * kb, n0 = 32 * nb;
;     float wv_[32];
; #pragma unroll
;     for (int i = 0; i < 32; ++i) { const int kk = 2 * i + (lane >> 5); wv_[i] = W[(size_t)(k0 + kk) * ldw + n0 + (lane & 31)]; }
; #pragma unroll
;     for (int i = 0; i < 32; ++i) { const int kk = 2 * i + (lane >> 5); scr[kk * 33 + (lane & 31)] = wv_[i]; }
; DI void wprep_layer(int wv, LAS unsigned char* lds, const Params& p, int layer, bf16_t* wb) {
;     ...
;         if (r < I0) { transpose_item(w_in, 1024, ldw_in, nin / 32, wb, scr, r, lane); continue; } r -= I0;
;         if (r < I1) { transpose_item(w_out, 1024, 1024, 32, wb_out, scr, r, lane); continue; } r -= I1;
;         if (r < I2) { transpose_item(w1, 1024, 4096, 128, wb_1, scr, r, lane); continue; } r -= I2;
;         transpose_item(w2, 4096, 1024, 32, wb_2, scr, r, lane);
.LBB0_17:
	v_cmp_lt_i32_e32 vcc, s18, v21
	s_and_saveexec_b64 s[8:9], vcc
	s_xor_b64 s[8:9], exec, s[8:9]
	s_cbranch_execz .LBB0_27
	v_add_u32_e32 v2, 0xfffffa00, v21
	v_cmp_lt_u32_e32 vcc, s19, v2
	s_and_saveexec_b64 s[10:11], vcc
	s_xor_b64 s[10:11], exec, s[10:11]
	s_cbranch_execz .LBB0_24
	v_cmp_lt_u32_e32 vcc, s20, v2
	s_and_saveexec_b64 s[12:13], vcc
	s_xor_b64 s[12:13], exec, s[12:13]
	s_cbranch_execz .LBB0_21
	v_and_b32_e32 v2, 0x7fffffc0, v31
	v_add_u32_e32 v22, 0xffffec00, v2
	v_and_b32_e32 v62, 0x3e0, v20
	v_or_b32_e32 v40, v22, v24
	v_lshlrev_b32_e32 v2, 2, v62
	v_lshl_add_u64 v[42:43], v[4:5], 0, v[2:3]
	v_or_b32_e32 v2, 2, v40
	v_lshlrev_b64 v[46:47], 12, v[2:3]
	v_or_b32_e32 v2, 4, v40
	v_lshlrev_b64 v[48:49], 12, v[2:3]
	v_or_b32_e32 v2, 6, v40
	v_lshlrev_b64 v[50:51], 12, v[2:3]
	v_or_b32_e32 v2, 8, v40
	v_lshlrev_b64 v[52:53], 12, v[2:3]
	v_or_b32_e32 v2, 10, v40
	v_mov_b32_e32 v41, v3
	v_lshlrev_b64 v[54:55], 12, v[2:3]
	v_or_b32_e32 v2, 12, v40
	v_lshlrev_b64 v[44:45], 12, v[40:41]
	v_lshlrev_b64 v[56:57], 12, v[2:3]
	v_or_b32_e32 v2, 14, v40
	v_lshl_add_u64 v[44:45], v[42:43], 0, v[44:45]
	v_lshlrev_b64 v[58:59], 12, v[2:3]
	v_or_b32_e32 v2, 16, v40
	v_lshl_add_u64 v[46:47], v[42:43], 0, v[46:47]
	v_lshl_add_u64 v[48:49], v[42:43], 0, v[48:49]
	v_lshl_add_u64 v[50:51], v[42:43], 0, v[50:51]
	v_lshl_add_u64 v[52:53], v[42:43], 0, v[52:53]
	v_lshl_add_u64 v[54:55], v[42:43], 0, v[54:55]
	v_lshl_add_u64 v[56:57], v[42:43], 0, v[56:57]
	v_lshl_add_u64 v[58:59], v[42:43], 0, v[58:59]
	global_load_dword v23, v[44:45], off nt
	global_load_dword v60, v[46:47], off nt
	global_load_dword v61, v[48:49], off nt
	global_load_dword v63, v[50:51], off nt
	global_load_dword v64, v[52:53], off nt
	global_load_dword v65, v[54:55], off nt
	global_load_dword v66, v[56:57], off nt
	global_load_dword v67, v[58:59], off nt
	v_lshlrev_b64 v[44:45], 12, v[2:3]
	v_or_b32_e32 v2, 18, v40
	v_lshlrev_b64 v[46:47], 12, v[2:3]
	v_or_b32_e32 v2, 20, v40
	v_lshlrev_b64 v[48:49], 12, v[2:3]
	v_or_b32_e32 v2, 22, v40
	v_lshlrev_b64 v[50:51], 12, v[2:3]
	v_or_b32_e32 v2, 24, v40
	v_lshlrev_b64 v[52:53], 12, v[2:3]
	v_or_b32_e32 v2, 26, v40
	v_lshlrev_b64 v[54:55], 12, v[2:3]
	v_or_b32_e32 v2, 28, v40
	v_lshlrev_b64 v[56:57], 12, v[2:3]
	v_or_b32_e32 v2, 30, v40
	v_lshl_add_u64 v[44:45], v[42:43], 0, v[44:45]
	v_lshlrev_b64 v[58:59], 12, v[2:3]
	v_or_b32_e32 v2, 32, v40
	v_lshl_add_u64 v[46:47], v[42:43], 0, v[46:47]
	v_lshl_add_u64 v[48:49], v[42:43], 0, v[48:49]
	v_lshl_add_u64 v[50:51], v[42:43], 0, v[50:51]
	v_lshl_add_u64 v[52:53], v[42:43], 0, v[52:53]
	v_lshl_add_u64 v[54:55], v[42:43], 0, v[54:55]
	v_lshl_add_u64 v[56:57], v[42:43], 0, v[56:57]
	v_lshl_add_u64 v[58:59], v[42:43], 0, v[58:59]
	global_load_dword v68, v[44:45], off nt
	global_load_dword v69, v[46:47], off nt
	global_load_dword v70, v[48:49], off nt
	global_load_dword v71, v[50:51], off nt
	global_load_dword v72, v[52:53], off nt
	global_load_dword v73, v[54:55], off nt
	global_load_dword v74, v[56:57], off nt
	global_load_dword v75, v[58:59], off nt
	v_lshlrev_b64 v[44:45], 12, v[2:3]
	v_or_b32_e32 v2, 34, v40
	v_lshlrev_b64 v[46:47], 12, v[2:3]
	v_or_b32_e32 v2, 36, v40
	v_lshlrev_b64 v[48:49], 12, v[2:3]
	v_or_b32_e32 v2, 38, v40
	v_lshlrev_b64 v[50:51], 12, v[2:3]
	v_or_b32_e32 v2, 40, v40
	v_lshlrev_b64 v[52:53], 12, v[2:3]
	v_or_b32_e32 v2, 42, v40
	v_lshlrev_b64 v[54:55], 12, v[2:3]
	v_or_b32_e32 v2, 44, v40
	v_lshlrev_b64 v[56:57], 12, v[2:3]
	v_or_b32_e32 v2, 46, v40
	v_lshl_add_u64 v[44:45], v[42:43], 0, v[44:45]
	v_lshlrev_b64 v[58:59], 12, v[2:3]
	v_or_b32_e32 v2, 48, v40
	v_lshl_add_u64 v[46:47], v[42:43], 0, v[46:47]
	v_lshl_add_u64 v[48:49], v[42:43], 0, v[48:49]
	v_lshl_add_u64 v[50:51], v[42:43], 0, v[50:51]
	v_lshl_add_u64 v[52:53], v[42:43], 0, v[52:53]
	v_lshl_add_u64 v[54:55], v[42:43], 0, v[54:55]
	v_lshl_add_u64 v[56:57], v[42:43], 0, v[56:57]
	v_lshl_add_u64 v[58:59], v[42:43], 0, v[58:59]
	global_load_dword v76, v[44:45], off nt
	global_load_dword v77, v[46:47], off nt
	global_load_dword v78, v[48:49], off nt
	global_load_dword v79, v[50:51], off nt
	global_load_dword v80, v[52:53], off nt
	global_load_dword v81, v[54:55], off nt
	global_load_dword v82, v[56:57], off nt
	global_load_dword v83, v[58:59], off nt
	v_lshlrev_b64 v[44:45], 12, v[2:3]
	v_or_b32_e32 v2, 50, v40
	v_lshlrev_b64 v[46:47], 12, v[2:3]
	v_or_b32_e32 v2, 52, v40
	v_lshlrev_b64 v[48:49], 12, v[2:3]
	v_or_b32_e32 v2, 54, v40
	v_lshlrev_b64 v[50:51], 12, v[2:3]
	v_or_b32_e32 v2, 56, v40
	v_lshlrev_b64 v[52:53], 12, v[2:3]
	v_or_b32_e32 v2, 58, v40
	v_lshlrev_b64 v[54:55], 12, v[2:3]
	v_or_b32_e32 v2, 60, v40
	v_lshlrev_b64 v[56:57], 12, v[2:3]
	v_or_b32_e32 v2, 62, v40
	v_lshl_add_u64 v[44:45], v[42:43], 0, v[44:45]
	v_lshlrev_b64 v[40:41], 12, v[2:3]
	v_lshl_add_u64 v[46:47], v[42:43], 0, v[46:47]
	v_lshl_add_u64 v[48:49], v[42:43], 0, v[48:49]
	v_lshl_add_u64 v[50:51], v[42:43], 0, v[50:51]
	v_lshl_add_u64 v[52:53], v[42:43], 0, v[52:53]
	v_lshl_add_u64 v[54:55], v[42:43], 0, v[54:55]
	v_lshl_add_u64 v[56:57], v[42:43], 0, v[56:57]
	v_lshl_add_u64 v[40:41], v[42:43], 0, v[40:41]
	global_load_dword v2, v[44:45], off nt
	global_load_dword v42, v[46:47], off nt
	global_load_dword v43, v[48:49], off nt
	global_load_dword v58, v[50:51], off nt
	global_load_dword v59, v[52:53], off nt
	global_load_dword v84, v[54:55], off nt
	global_load_dword v85, v[56:57], off nt
	global_load_dword v86, v[40:41], off nt
	s_waitcnt vmcnt(30)
	ds_write2_b32 v25, v23, v60 offset1:66
	s_waitcnt vmcnt(28)
	ds_write2_b32 v25, v61, v63 offset0:132 offset1:198
	s_waitcnt vmcnt(26)
; #define LAS __attribute__((address_space(3)))
; DI unsigned pk2(float lo, float hi) { f32x2 f = {lo, hi}; bf2_t v = __builtin_convertvector(f, bf2_t); return __builtin_bit_cast(unsigned, v); }
; #define scr (p.ws + opq_off(SCR_OFF))
; DI void transpose_item(const float* W, int K, int ldw, int nblk, bf16_t* WT, LAS float* scr, int item, int lane) {
;     ...
;     for (int i = 0; i < 32; ++i) { const int kk = 2 * i + (lane >> 5); wv_[i] = W[(size_t)(k0 + kk) * ldw + n0 + (lane & 31)]; }
; #pragma unroll
;     for (int i = 0; i < 32; ++i) { const int kk = 2 * i + (lane >> 5); scr[kk * 33 + (lane & 31)] = wv_[i]; }
;     asm volatile("s_waitcnt lgkmcnt(0)" ::: "memory");
;     const int c = lane & 7;
; #pragma unroll
;     for (int j = 0; j < 4; ++j) { const int n = (lane >> 3) + 8 * j; const LAS float* s = scr + (8 * c) * 33 + n;
;         u32x4 o; o.x = pk2(s[0 * 33], s[1 * 33]); o.y = pk2(s[2 * 33], s[3 * 33]); o.z = pk2(s[4 * 33], s[5 * 33]); o.w = pk2(s[6 * 33], s[7 * 33]);
;         *(u32x4*)(WT + (size_t)(n0 + n) * K + k0 + 8 * c) = o; }
	ds_write2_b32 v32, v64, v65 offset0:8 offset1:74
	s_waitcnt vmcnt(24)
	ds_write2_b32 v32, v66, v67 offset0:140 offset1:206
	s_waitcnt vmcnt(22)
	ds_write2_b32 v33, v68, v69 offset0:16 offset1:82
	s_waitcnt vmcnt(20)
	ds_write2_b32 v33, v70, v71 offset0:148 offset1:214
	s_waitcnt vmcnt(18)
	ds_write2_b32 v34, v72, v73 offset0:24 offset1:90
	s_waitcnt vmcnt(16)
	ds_write2_b32 v34, v74, v75 offset0:156 offset1:222
	s_waitcnt vmcnt(14)
	ds_write2_b32 v35, v76, v77 offset0:32 offset1:98
	s_waitcnt vmcnt(12)
	ds_write2_b32 v35, v78, v79 offset0:164 offset1:230
	s_waitcnt vmcnt(10)
	ds_write2_b32 v36, v80, v81 offset0:40 offset1:106
	s_waitcnt vmcnt(8)
	ds_write2_b32 v36, v82, v83 offset0:172 offset1:238
	s_waitcnt vmcnt(6)
	ds_write2_b32 v37, v2, v42 offset0:48 offset1:114
	s_waitcnt vmcnt(4)
	ds_write2_b32 v37, v43, v58 offset0:180 offset1:246
	s_waitcnt vmcnt(2)
	ds_write2_b32 v39, v59, v84 offset0:56 offset1:122
	s_waitcnt vmcnt(0)
	ds_write2_b32 v39, v85, v86 offset0:188 offset1:254
	s_waitcnt lgkmcnt(0)
	ds_read2_b32 v[44:45], v27 offset0:33 offset1:41
	ds_read2_b32 v[46:47], v27 offset1:8
	ds_read2_b32 v[48:49], v27 offset0:66 offset1:74
	ds_read2_b32 v[50:51], v27 offset0:99 offset1:107
	ds_read2_b32 v[52:53], v27 offset0:132 offset1:140
	ds_read2_b32 v[54:55], v27 offset0:165 offset1:173
	ds_read2_b32 v[56:57], v27 offset0:198 offset1:206
	ds_read2_b32 v[58:59], v27 offset0:231 offset1:239
	v_mov_b32_e32 v23, v3
	v_or_b32_e32 v2, v62, v26
	v_lshl_add_u64 v[22:23], v[22:23], 1, v[8:9]
	v_lshlrev_b32_e32 v2, 13, v2
	s_waitcnt lgkmcnt(6)
	v_cvt_pk_bf16_f32 v40, v46, v44
	s_waitcnt lgkmcnt(4)
	v_cvt_pk_bf16_f32 v41, v48, v50
	s_waitcnt lgkmcnt(2)
	v_cvt_pk_bf16_f32 v42, v52, v54
	s_waitcnt lgkmcnt(0)
	v_cvt_pk_bf16_f32 v43, v56, v58
	v_lshl_add_u64 v[60:61], v[22:23], 0, v[2:3]
	global_store_dwordx4 v[60:61], v[40:43], off
	v_or_b32_e32 v2, v62, v28
	v_lshlrev_b32_e32 v2, 13, v2
	v_cvt_pk_bf16_f32 v40, v47, v45
	v_cvt_pk_bf16_f32 v41, v49, v51
	v_cvt_pk_bf16_f32 v42, v53, v55
	v_cvt_pk_bf16_f32 v43, v57, v59
	ds_read2_b32 v[46:47], v27 offset0:49 offset1:57
	ds_read2_b32 v[48:49], v27 offset0:16 offset1:24
	ds_read2_b32 v[50:51], v27 offset0:82 offset1:90
	ds_read2_b32 v[52:53], v27 offset0:115 offset1:123
	ds_read2_b32 v[54:55], v27 offset0:148 offset1:156
	ds_read2_b32 v[56:57], v27 offset0:181 offset1:189
	ds_read2_b32 v[58:59], v27 offset0:214 offset1:222
	ds_read2_b32 v[60:61], v27 offset0:247 offset1:255
	v_lshl_add_u64 v[44:45], v[22:23], 0, v[2:3]
	v_or_b32_e32 v2, v62, v29
	v_lshlrev_b32_e32 v2, 13, v2
	global_store_dwordx4 v[44:45], v[40:43], off
	v_lshl_add_u64 v[44:45], v[22:23], 0, v[2:3]
	v_or_b32_e32 v2, v62, v30
	s_waitcnt lgkmcnt(6)
	v_cvt_pk_bf16_f32 v40, v48, v46
	s_waitcnt lgkmcnt(4)
	v_cvt_pk_bf16_f32 v41, v50, v52
	s_waitcnt lgkmcnt(2)
	v_cvt_pk_bf16_f32 v42, v54, v56
	s_waitcnt lgkmcnt(0)
	v_cvt_pk_bf16_f32 v43, v58, v60
	v_lshlrev_b32_e32 v2, 13, v2
	global_store_dwordx4 v[44:45], v[40:43], off
	v_lshl_add_u64 v[22:23], v[22:23], 0, v[2:3]
	s_nop 0
	v_cvt_pk_bf16_f32 v40, v49, v47
	v_cvt_pk_bf16_f32 v41, v51, v53
	v_cvt_pk_bf16_f32 v42, v55, v57
	v_cvt_pk_bf16_f32 v43, v59, v61
	global_store_dwordx4 v[22:23], v[40:43], off
	s_waitcnt lgkmcnt(0)
.LBB0_21:
	s_andn2_saveexec_b64 s[12:13], s[12:13]
	s_cbranch_execz .LBB0_23
	v_add_u32_e32 v2, 0xf800, v21
	v_lshrrev_b32_e32 v2, 1, v2
	v_and_b32_e32 v56, 0x7fc0, v2
	v_and_b32_e32 v62, 0xfe0, v20
	v_or_b32_e32 v40, v56, v24
	v_lshlrev_b32_e32 v2, 2, v62
	v_lshl_add_u64 v[22:23], v[10:11], 0, v[2:3]
	v_lshlrev_b32_e32 v2, 14, v40
	v_lshl_add_u64 v[22:23], v[22:23], 0, v[2:3]
	v_add_co_u32_e32 v40, vcc, 0x8000, v22
	s_nop 1
	v_addc_co_u32_e32 v41, vcc, 0, v23, vcc
	v_add_co_u32_e32 v42, vcc, 0x10000, v22
	s_nop 1
	v_addc_co_u32_e32 v43, vcc, 0, v23, vcc
	v_add_co_u32_e32 v44, vcc, 0x18000, v22
	s_nop 1
	v_addc_co_u32_e32 v45, vcc, 0, v23, vcc
	v_add_co_u32_e32 v46, vcc, 0x20000, v22
	s_nop 1
	v_addc_co_u32_e32 v47, vcc, 0, v23, vcc
	v_add_co_u32_e32 v48, vcc, 0x28000, v22
	s_nop 1
	v_addc_co_u32_e32 v49, vcc, 0, v23, vcc
	v_add_co_u32_e32 v50, vcc, 0x30000, v22
	s_nop 1
	v_addc_co_u32_e32 v51, vcc, 0, v23, vcc
	v_add_co_u32_e32 v52, vcc, 0x38000, v22
	s_nop 1
	v_addc_co_u32_e32 v53, vcc, 0, v23, vcc
	global_load_dword v2, v[22:23], off nt
	global_load_dword v57, v[40:41], off nt
	global_load_dword v58, v[42:43], off nt
	global_load_dword v59, v[44:45], off nt
	global_load_dword v60, v[46:47], off nt
	global_load_dword v61, v[48:49], off nt
	global_load_dword v63, v[50:51], off nt
	global_load_dword v64, v[52:53], off nt
	v_add_co_u32_e32 v40, vcc, 0x40000, v22
	s_nop 1
	v_addc_co_u32_e32 v41, vcc, 0, v23, vcc
	v_add_co_u32_e32 v42, vcc, 0x48000, v22
	s_nop 1
	v_addc_co_u32_e32 v43, vcc, 0, v23, vcc
	v_add_co_u32_e32 v44, vcc, 0x50000, v22
	s_nop 1
	v_addc_co_u32_e32 v45, vcc, 0, v23, vcc
	v_add_co_u32_e32 v46, vcc, 0x58000, v22
	s_nop 1
	v_addc_co_u32_e32 v47, vcc, 0, v23, vcc
	v_add_co_u32_e32 v48, vcc, 0x60000, v22
	s_nop 1
	v_addc_co_u32_e32 v49, vcc, 0, v23, vcc
	v_add_co_u32_e32 v50, vcc, 0x68000, v22
	s_nop 1
	v_addc_co_u32_e32 v51, vcc, 0, v23, vcc
	v_add_co_u32_e32 v52, vcc, 0x70000, v22
	s_nop 1
	v_addc_co_u32_e32 v53, vcc, 0, v23, vcc
	v_add_co_u32_e32 v54, vcc, 0x78000, v22
	s_nop 1
	v_addc_co_u32_e32 v55, vcc, 0, v23, vcc
	global_load_dword v65, v[40:41], off nt
	global_load_dword v66, v[42:43], off nt
	global_load_dword v67, v[44:45], off nt
	global_load_dword v68, v[46:47], off nt
	global_load_dword v69, v[48:49], off nt
	global_load_dword v70, v[50:51], off nt
; #define LAS __attribute__((address_space(3)))
; DI unsigned pk2(float lo, float hi) { f32x2 f = {lo, hi}; bf2_t v = __builtin_convertvector(f, bf2_t); return __builtin_bit_cast(unsigned, v); }
; #define scr (p.ws + opq_off(SCR_OFF))
; DI void transpose_item(const float* W, int K, int ldw, int nblk, bf16_t* WT, LAS float* scr, int item, int lane) {
;     ...
;     for (int i = 0; i < 32; ++i) { const int kk = 2 * i + (lane >> 5); wv_[i] = W[(size_t)(k0 + kk) * ldw + n0 + (lane & 31)]; }
; #pragma unroll
;     for (int i = 0; i < 32; ++i) { const int kk = 2 * i + (lane >> 5); scr[kk * 33 + (lane & 31)] = wv_[i]; }
;     asm volatile("s_waitcnt lgkmcnt(0)" ::: "memory");
;     const int c = lane & 7;
; #pragma unroll
;     for (int j = 0; j < 4; ++j) { const int n = (lane >> 3) + 8 * j; const LAS float* s = scr + (8 * c) * 33 + n;
;         u32x4 o; o.x = pk2(s[0 * 33], s[1 * 33]); o.y = pk2(s[2 * 33], s[3 * 33]); o.z = pk2(s[4 * 33], s[5 * 33]); o.w = pk2(s[6 * 33], s[7 * 33]);
;         *(u32x4*)(WT + (size_t)(n0 + n) * K + k0 + 8 * c) = o; }
	global_load_dword v71, v[52:53], off nt
	global_load_dword v72, v[54:55], off nt
	v_add_co_u32_e32 v40, vcc, 0x80000, v22
	s_nop 1
	v_addc_co_u32_e32 v41, vcc, 0, v23, vcc
	v_add_co_u32_e32 v42, vcc, 0x88000, v22
	s_nop 1
	v_addc_co_u32_e32 v43, vcc, 0, v23, vcc
	v_add_co_u32_e32 v44, vcc, 0x90000, v22
	s_nop 1
	v_addc_co_u32_e32 v45, vcc, 0, v23, vcc
	v_add_co_u32_e32 v46, vcc, 0x98000, v22
	s_nop 1
	v_addc_co_u32_e32 v47, vcc, 0, v23, vcc
	v_add_co_u32_e32 v48, vcc, 0xa0000, v22
	s_nop 1
	v_addc_co_u32_e32 v49, vcc, 0, v23, vcc
	v_add_co_u32_e32 v50, vcc, 0xa8000, v22
	s_nop 1
	v_addc_co_u32_e32 v51, vcc, 0, v23, vcc
	v_add_co_u32_e32 v52, vcc, 0xb0000, v22
	s_nop 1
	v_addc_co_u32_e32 v53, vcc, 0, v23, vcc
	v_add_co_u32_e32 v54, vcc, 0xb8000, v22
	s_nop 1
	v_addc_co_u32_e32 v55, vcc, 0, v23, vcc
	global_load_dword v73, v[40:41], off nt
	global_load_dword v74, v[42:43], off nt
	global_load_dword v75, v[44:45], off nt
	global_load_dword v76, v[46:47], off nt
	global_load_dword v77, v[48:49], off nt
	global_load_dword v78, v[50:51], off nt
	global_load_dword v79, v[52:53], off nt
	global_load_dword v80, v[54:55], off nt
	v_add_co_u32_e32 v40, vcc, 0xc0000, v22
	s_nop 1
	v_addc_co_u32_e32 v41, vcc, 0, v23, vcc
	v_add_co_u32_e32 v42, vcc, 0xc8000, v22
	s_nop 1
	v_addc_co_u32_e32 v43, vcc, 0, v23, vcc
	v_add_co_u32_e32 v44, vcc, 0xd0000, v22
	s_nop 1
	v_addc_co_u32_e32 v45, vcc, 0, v23, vcc
	v_add_co_u32_e32 v46, vcc, 0xd8000, v22
	s_nop 1
	v_addc_co_u32_e32 v47, vcc, 0, v23, vcc
	v_add_co_u32_e32 v48, vcc, 0xe0000, v22
	s_nop 1
	v_addc_co_u32_e32 v49, vcc, 0, v23, vcc
	v_add_co_u32_e32 v50, vcc, 0xe8000, v22
	s_nop 1
	v_addc_co_u32_e32 v51, vcc, 0, v23, vcc
	v_add_co_u32_e32 v52, vcc, 0xf0000, v22
	s_nop 1
	v_addc_co_u32_e32 v53, vcc, 0, v23, vcc
	v_add_co_u32_e32 v22, vcc, 0xf8000, v22
	s_nop 1
	v_addc_co_u32_e32 v23, vcc, 0, v23, vcc
	global_load_dword v54, v[40:41], off nt
	global_load_dword v55, v[42:43], off nt
	global_load_dword v81, v[44:45], off nt
	global_load_dword v82, v[46:47], off nt
	global_load_dword v83, v[48:49], off nt
	global_load_dword v84, v[50:51], off nt
	global_load_dword v85, v[52:53], off nt
	global_load_dword v86, v[22:23], off nt
	s_waitcnt vmcnt(30)
	ds_write2_b32 v25, v2, v57 offset1:66
	s_waitcnt vmcnt(28)
	ds_write2_b32 v25, v58, v59 offset0:132 offset1:198
	s_waitcnt vmcnt(26)
	ds_write2_b32 v32, v60, v61 offset0:8 offset1:74
	s_waitcnt vmcnt(24)
	ds_write2_b32 v32, v63, v64 offset0:140 offset1:206
	s_waitcnt vmcnt(22)
	ds_write2_b32 v33, v65, v66 offset0:16 offset1:82
	s_waitcnt vmcnt(20)
	ds_write2_b32 v33, v67, v68 offset0:148 offset1:214
	s_waitcnt vmcnt(18)
	ds_write2_b32 v34, v69, v70 offset0:24 offset1:90
	s_waitcnt vmcnt(16)
	ds_write2_b32 v34, v71, v72 offset0:156 offset1:222
	s_waitcnt vmcnt(14)
	ds_write2_b32 v35, v73, v74 offset0:32 offset1:98
	s_waitcnt vmcnt(12)
	ds_write2_b32 v35, v75, v76 offset0:164 offset1:230
	s_waitcnt vmcnt(10)
	ds_write2_b32 v36, v77, v78 offset0:40 offset1:106
	s_waitcnt vmcnt(8)
	ds_write2_b32 v36, v79, v80 offset0:172 offset1:238
	s_waitcnt vmcnt(6)
	ds_write2_b32 v37, v54, v55 offset0:48 offset1:114
	s_waitcnt vmcnt(4)
	ds_write2_b32 v37, v81, v82 offset0:180 offset1:246
	s_waitcnt vmcnt(2)
	ds_write2_b32 v39, v83, v84 offset0:56 offset1:122
	s_waitcnt vmcnt(0)
	ds_write2_b32 v39, v85, v86 offset0:188 offset1:254
	s_waitcnt lgkmcnt(0)
	v_lshlrev_b32_e32 v2, 1, v56
	ds_read2_b32 v[22:23], v27 offset0:33 offset1:41
	ds_read2_b32 v[44:45], v27 offset1:8
	ds_read2_b32 v[46:47], v27 offset0:66 offset1:74
	ds_read2_b32 v[48:49], v27 offset0:99 offset1:107
	ds_read2_b32 v[50:51], v27 offset0:132 offset1:140
	ds_read2_b32 v[52:53], v27 offset0:165 offset1:173
	ds_read2_b32 v[54:55], v27 offset0:198 offset1:206
	ds_read2_b32 v[56:57], v27 offset0:231 offset1:239
	v_lshl_add_u64 v[58:59], v[12:13], 0, v[2:3]
	v_or_b32_e32 v2, v62, v26
	v_lshlrev_b32_e32 v2, 11, v2
	s_waitcnt lgkmcnt(6)
	v_cvt_pk_bf16_f32 v40, v44, v22
	s_waitcnt lgkmcnt(4)
	v_cvt_pk_bf16_f32 v41, v46, v48
	s_waitcnt lgkmcnt(2)
	v_cvt_pk_bf16_f32 v42, v50, v52
	s_waitcnt lgkmcnt(0)
	v_cvt_pk_bf16_f32 v43, v54, v56
	v_lshl_add_u64 v[60:61], v[58:59], 0, v[2:3]
	global_store_dwordx4 v[60:61], v[40:43], off
	v_or_b32_e32 v2, v62, v28
	v_lshlrev_b32_e32 v2, 11, v2
	v_cvt_pk_bf16_f32 v40, v45, v23
	v_cvt_pk_bf16_f32 v41, v47, v49
	v_cvt_pk_bf16_f32 v42, v51, v53
	v_cvt_pk_bf16_f32 v43, v55, v57
	ds_read2_b32 v[44:45], v27 offset0:49 offset1:57
	ds_read2_b32 v[46:47], v27 offset0:16 offset1:24
	ds_read2_b32 v[48:49], v27 offset0:82 offset1:90
	ds_read2_b32 v[50:51], v27 offset0:115 offset1:123
	ds_read2_b32 v[52:53], v27 offset0:148 offset1:156
	ds_read2_b32 v[54:55], v27 offset0:181 offset1:189
	ds_read2_b32 v[56:57], v27 offset0:214 offset1:222
	ds_read2_b32 v[60:61], v27 offset0:247 offset1:255
	v_lshl_add_u64 v[22:23], v[58:59], 0, v[2:3]
	v_or_b32_e32 v2, v62, v29
	v_lshlrev_b32_e32 v2, 11, v2
	global_store_dwordx4 v[22:23], v[40:43], off
	v_lshl_add_u64 v[22:23], v[58:59], 0, v[2:3]
	v_or_b32_e32 v2, v62, v30
	s_waitcnt lgkmcnt(6)
	v_cvt_pk_bf16_f32 v40, v46, v44
	s_waitcnt lgkmcnt(4)
	v_cvt_pk_bf16_f32 v41, v48, v50
	s_waitcnt lgkmcnt(2)
	v_cvt_pk_bf16_f32 v42, v52, v54
	s_waitcnt lgkmcnt(0)
	v_cvt_pk_bf16_f32 v43, v56, v60
	v_lshlrev_b32_e32 v2, 11, v2
	global_store_dwordx4 v[22:23], v[40:43], off
	v_lshl_add_u64 v[22:23], v[58:59], 0, v[2:3]
	s_nop 0
	v_cvt_pk_bf16_f32 v40, v47, v45
	v_cvt_pk_bf16_f32 v41, v49, v51
	v_cvt_pk_bf16_f32 v42, v53, v55
	v_cvt_pk_bf16_f32 v43, v57, v61
	global_store_dwordx4 v[22:23], v[40:43], off
	s_waitcnt lgkmcnt(0)

; #define scr (p.ws + opq_off(SCR_OFF))
; DI void transpose_item(const float* W, int K, int ldw, int nblk, bf16_t* WT, LAS float* scr, int item, int lane) {
;     ...
;     for (int i = 0; i < 32; ++i) { const int kk = 2 * i + (lane >> 5); wv_[i] = W[(size_t)(k0 + kk) * ldw + n0 + (lane & 31)]; }
; #pragma unroll
;     for (int i = 0; i < 32; ++i) { const int kk = 2 * i + (lane >> 5); scr[kk * 33 + (lane & 31)] = wv_[i]; }
.LBB0_24:
	s_andn2_saveexec_b64 s[10:11], s[10:11]
	s_cbranch_execz .LBB0_26
	v_and_b32_e32 v56, 0x3c0, v31
	v_and_b32_e32 v62, 0x3e0, v20
	v_or_b32_e32 v40, v56, v24
	v_lshlrev_b32_e32 v2, 2, v62
	v_lshl_add_u64 v[22:23], v[14:15], 0, v[2:3]
	v_lshlrev_b32_e32 v2, 12, v40
	v_lshl_add_u64 v[22:23], v[22:23], 0, v[2:3]
	v_add_co_u32_e32 v40, vcc, 0x2000, v22
	s_nop 1
	v_addc_co_u32_e32 v41, vcc, 0, v23, vcc
	v_add_co_u32_e32 v42, vcc, 0x4000, v22
	s_nop 1
	v_addc_co_u32_e32 v43, vcc, 0, v23, vcc
	v_add_co_u32_e32 v44, vcc, 0x6000, v22
	s_nop 1
	v_addc_co_u32_e32 v45, vcc, 0, v23, vcc
	v_add_co_u32_e32 v46, vcc, s21, v22
	s_nop 1
	v_addc_co_u32_e32 v47, vcc, 0, v23, vcc
	v_add_co_u32_e32 v48, vcc, 0xa000, v22
	s_nop 1
	v_addc_co_u32_e32 v49, vcc, 0, v23, vcc
	v_add_co_u32_e32 v50, vcc, 0xc000, v22
	s_nop 1
	v_addc_co_u32_e32 v51, vcc, 0, v23, vcc
	v_add_co_u32_e32 v52, vcc, 0xe000, v22
	s_nop 1
	v_addc_co_u32_e32 v53, vcc, 0, v23, vcc
	global_load_dword v2, v[22:23], off nt
	global_load_dword v57, v[40:41], off nt
	global_load_dword v58, v[42:43], off nt
	global_load_dword v59, v[44:45], off nt
	global_load_dword v60, v[46:47], off nt
	global_load_dword v61, v[48:49], off nt
	global_load_dword v63, v[50:51], off nt
	global_load_dword v64, v[52:53], off nt
	v_add_co_u32_e32 v40, vcc, s22, v22
	s_nop 1
	v_addc_co_u32_e32 v41, vcc, 0, v23, vcc
	v_add_co_u32_e32 v42, vcc, 0x12000, v22
	s_nop 1
	v_addc_co_u32_e32 v43, vcc, 0, v23, vcc
	v_add_co_u32_e32 v44, vcc, 0x14000, v22
	s_nop 1
	v_addc_co_u32_e32 v45, vcc, 0, v23, vcc
	v_add_co_u32_e32 v46, vcc, 0x16000, v22
	s_nop 1
	v_addc_co_u32_e32 v47, vcc, 0, v23, vcc
	v_add_co_u32_e32 v48, vcc, s23, v22
	s_nop 1
	v_addc_co_u32_e32 v49, vcc, 0, v23, vcc
	v_add_co_u32_e32 v50, vcc, 0x1a000, v22
	s_nop 1
	v_addc_co_u32_e32 v51, vcc, 0, v23, vcc
	v_add_co_u32_e32 v52, vcc, 0x1c000, v22
	s_nop 1
	v_addc_co_u32_e32 v53, vcc, 0, v23, vcc
	v_add_co_u32_e32 v54, vcc, 0x1e000, v22
	s_nop 1
	v_addc_co_u32_e32 v55, vcc, 0, v23, vcc
	global_load_dword v65, v[40:41], off nt
	global_load_dword v66, v[42:43], off nt
	global_load_dword v67, v[44:45], off nt
	global_load_dword v68, v[46:47], off nt
	global_load_dword v69, v[48:49], off nt
	global_load_dword v70, v[50:51], off nt
	global_load_dword v71, v[52:53], off nt
	global_load_dword v72, v[54:55], off nt
	v_add_co_u32_e32 v40, vcc, s24, v22
	s_nop 1
	v_addc_co_u32_e32 v41, vcc, 0, v23, vcc
	v_add_co_u32_e32 v42, vcc, 0x22000, v22
	s_nop 1
	v_addc_co_u32_e32 v43, vcc, 0, v23, vcc
	v_add_co_u32_e32 v44, vcc, 0x24000, v22
	s_nop 1
	v_addc_co_u32_e32 v45, vcc, 0, v23, vcc
	v_add_co_u32_e32 v46, vcc, 0x26000, v22
	s_nop 1
	v_addc_co_u32_e32 v47, vcc, 0, v23, vcc
	v_add_co_u32_e32 v48, vcc, s25, v22
	s_nop 1
	v_addc_co_u32_e32 v49, vcc, 0, v23, vcc
	v_add_co_u32_e32 v50, vcc, 0x2a000, v22
	s_nop 1
	v_addc_co_u32_e32 v51, vcc, 0, v23, vcc
	v_add_co_u32_e32 v52, vcc, 0x2c000, v22
	s_nop 1
	v_addc_co_u32_e32 v53, vcc, 0, v23, vcc
	v_add_co_u32_e32 v54, vcc, 0x2e000, v22
	s_nop 1
	v_addc_co_u32_e32 v55, vcc, 0, v23, vcc
	global_load_dword v73, v[40:41], off nt
	global_load_dword v74, v[42:43], off nt
	global_load_dword v75, v[44:45], off nt
	global_load_dword v76, v[46:47], off nt
	global_load_dword v77, v[48:49], off nt
	global_load_dword v78, v[50:51], off nt
	global_load_dword v79, v[52:53], off nt
	global_load_dword v80, v[54:55], off nt
	v_add_co_u32_e32 v40, vcc, s26, v22
	s_nop 1
	v_addc_co_u32_e32 v41, vcc, 0, v23, vcc
	v_add_co_u32_e32 v42, vcc, 0x32000, v22
	s_nop 1
	v_addc_co_u32_e32 v43, vcc, 0, v23, vcc
	v_add_co_u32_e32 v44, vcc, 0x34000, v22
	s_nop 1
	v_addc_co_u32_e32 v45, vcc, 0, v23, vcc
	v_add_co_u32_e32 v46, vcc, 0x36000, v22
	s_nop 1
	v_addc_co_u32_e32 v47, vcc, 0, v23, vcc
	v_add_co_u32_e32 v48, vcc, s27, v22
	s_nop 1
	v_addc_co_u32_e32 v49, vcc, 0, v23, vcc
	v_add_co_u32_e32 v50, vcc, 0x3a000, v22
	s_nop 1
	v_addc_co_u32_e32 v51, vcc, 0, v23, vcc
	v_add_co_u32_e32 v52, vcc, 0x3c000, v22
	s_nop 1
	v_addc_co_u32_e32 v53, vcc, 0, v23, vcc
	v_add_co_u32_e32 v22, vcc, 0x3e000, v22
	s_nop 1
	v_addc_co_u32_e32 v23, vcc, 0, v23, vcc
	global_load_dword v54, v[40:41], off nt
	global_load_dword v55, v[42:43], off nt
	global_load_dword v81, v[44:45], off nt
	global_load_dword v82, v[46:47], off nt
	global_load_dword v83, v[48:49], off nt
	global_load_dword v84, v[50:51], off nt
	global_load_dword v85, v[52:53], off nt
	global_load_dword v86, v[22:23], off nt
	s_waitcnt vmcnt(30)
; #define LAS __attribute__((address_space(3)))
; DI unsigned pk2(float lo, float hi) { f32x2 f = {lo, hi}; bf2_t v = __builtin_convertvector(f, bf2_t); return __builtin_bit_cast(unsigned, v); }
; #define scr (p.ws + opq_off(SCR_OFF))
; DI void transpose_item(const float* W, int K, int ldw, int nblk, bf16_t* WT, LAS float* scr, int item, int lane) {
;     ...
;     for (int i = 0; i < 32; ++i) { const int kk = 2 * i + (lane >> 5); scr[kk * 33 + (lane & 31)] = wv_[i]; }
;     asm volatile("s_waitcnt lgkmcnt(0)" ::: "memory");
;     const int c = lane & 7;
; #pragma unroll
;     for (int j = 0; j < 4; ++j) { const int n = (lane >> 3) + 8 * j; const LAS float* s = scr + (8 * c) * 33 + n;
;         u32x4 o; o.x = pk2(s[0 * 33], s[1 * 33]); o.y = pk2(s[2 * 33], s[3 * 33]); o.z = pk2(s[4 * 33], s[5 * 33]); o.w = pk2(s[6 * 33], s[7 * 33]);
;         *(u32x4*)(WT + (size_t)(n0 + n) * K + k0 + 8 * c) = o; }
;     asm volatile("s_waitcnt lgkmcnt(0)" ::: "memory");
	ds_write2_b32 v25, v2, v57 offset1:66
	s_waitcnt vmcnt(28)
	ds_write2_b32 v25, v58, v59 offset0:132 offset1:198
	s_waitcnt vmcnt(26)
	ds_write2_b32 v32, v60, v61 offset0:8 offset1:74
	s_waitcnt vmcnt(24)
	ds_write2_b32 v32, v63, v64 offset0:140 offset1:206
	s_waitcnt vmcnt(22)
	ds_write2_b32 v33, v65, v66 offset0:16 offset1:82
	s_waitcnt vmcnt(20)
	ds_write2_b32 v33, v67, v68 offset0:148 offset1:214
	s_waitcnt vmcnt(18)
	ds_write2_b32 v34, v69, v70 offset0:24 offset1:90
	s_waitcnt vmcnt(16)
	ds_write2_b32 v34, v71, v72 offset0:156 offset1:222
	s_waitcnt vmcnt(14)
	ds_write2_b32 v35, v73, v74 offset0:32 offset1:98
	s_waitcnt vmcnt(12)
	ds_write2_b32 v35, v75, v76 offset0:164 offset1:230
	s_waitcnt vmcnt(10)
	ds_write2_b32 v36, v77, v78 offset0:40 offset1:106
	s_waitcnt vmcnt(8)
	ds_write2_b32 v36, v79, v80 offset0:172 offset1:238
	s_waitcnt vmcnt(6)
	ds_write2_b32 v37, v54, v55 offset0:48 offset1:114
	s_waitcnt vmcnt(4)
	ds_write2_b32 v37, v81, v82 offset0:180 offset1:246
	s_waitcnt vmcnt(2)
	ds_write2_b32 v39, v83, v84 offset0:56 offset1:122
	s_waitcnt vmcnt(0)
	ds_write2_b32 v39, v85, v86 offset0:188 offset1:254
	s_waitcnt lgkmcnt(0)
	v_lshlrev_b32_e32 v2, 1, v56
	ds_read2_b32 v[22:23], v27 offset0:33 offset1:41
	ds_read2_b32 v[44:45], v27 offset1:8
	ds_read2_b32 v[46:47], v27 offset0:66 offset1:74
	ds_read2_b32 v[48:49], v27 offset0:99 offset1:107
	ds_read2_b32 v[50:51], v27 offset0:132 offset1:140
	ds_read2_b32 v[52:53], v27 offset0:165 offset1:173
	ds_read2_b32 v[54:55], v27 offset0:198 offset1:206
	ds_read2_b32 v[56:57], v27 offset0:231 offset1:239
	v_lshl_add_u64 v[58:59], v[16:17], 0, v[2:3]
	v_or_b32_e32 v2, v62, v26
	v_lshlrev_b32_e32 v2, 11, v2
	s_waitcnt lgkmcnt(6)
	v_cvt_pk_bf16_f32 v40, v44, v22
	s_waitcnt lgkmcnt(4)
	v_cvt_pk_bf16_f32 v41, v46, v48
	s_waitcnt lgkmcnt(2)
	v_cvt_pk_bf16_f32 v42, v50, v52
	s_waitcnt lgkmcnt(0)
	v_cvt_pk_bf16_f32 v43, v54, v56
	v_lshl_add_u64 v[60:61], v[58:59], 0, v[2:3]
	global_store_dwordx4 v[60:61], v[40:43], off
	v_or_b32_e32 v2, v62, v28
	v_lshlrev_b32_e32 v2, 11, v2
	v_cvt_pk_bf16_f32 v40, v45, v23
	v_cvt_pk_bf16_f32 v41, v47, v49
	v_cvt_pk_bf16_f32 v42, v51, v53
	v_cvt_pk_bf16_f32 v43, v55, v57
	ds_read2_b32 v[44:45], v27 offset0:49 offset1:57
	ds_read2_b32 v[46:47], v27 offset0:16 offset1:24
	ds_read2_b32 v[48:49], v27 offset0:82 offset1:90
	ds_read2_b32 v[50:51], v27 offset0:115 offset1:123
	ds_read2_b32 v[52:53], v27 offset0:148 offset1:156
	ds_read2_b32 v[54:55], v27 offset0:181 offset1:189
	ds_read2_b32 v[56:57], v27 offset0:214 offset1:222
	ds_read2_b32 v[60:61], v27 offset0:247 offset1:255
	v_lshl_add_u64 v[22:23], v[58:59], 0, v[2:3]
	v_or_b32_e32 v2, v62, v29
	v_lshlrev_b32_e32 v2, 11, v2
	global_store_dwordx4 v[22:23], v[40:43], off
	v_lshl_add_u64 v[22:23], v[58:59], 0, v[2:3]
	v_or_b32_e32 v2, v62, v30
	s_waitcnt lgkmcnt(6)
	v_cvt_pk_bf16_f32 v40, v46, v44
	s_waitcnt lgkmcnt(4)
	v_cvt_pk_bf16_f32 v41, v48, v50
	s_waitcnt lgkmcnt(2)
	v_cvt_pk_bf16_f32 v42, v52, v54
	s_waitcnt lgkmcnt(0)
	v_cvt_pk_bf16_f32 v43, v56, v60
	v_lshlrev_b32_e32 v2, 11, v2
	global_store_dwordx4 v[22:23], v[40:43], off
	v_lshl_add_u64 v[22:23], v[58:59], 0, v[2:3]
	s_nop 0
	v_cvt_pk_bf16_f32 v40, v47, v45
	v_cvt_pk_bf16_f32 v41, v49, v51
	v_cvt_pk_bf16_f32 v42, v53, v55
	v_cvt_pk_bf16_f32 v43, v57, v61
	global_store_dwordx4 v[22:23], v[40:43], off
	s_waitcnt lgkmcnt(0)

; #define scr (p.ws + opq_off(SCR_OFF))
; DI void transpose_item(const float* W, int K, int ldw, int nblk, bf16_t* WT, LAS float* scr, int item, int lane) {
;     const int kb = item / nblk, nb = item % nblk, k0 = 64 * kb, n0 = 32 * nb;
;     float wv_[32];
; #pragma unroll
;     for (int i = 0; i < 32; ++i) { const int kk = 2 * i + (lane >> 5); wv_[i] = W[(size_t)(k0 + kk) * ldw + n0 + (lane & 31)]; }
; DI void wprep_layer(int wv, LAS unsigned char* lds, const Params& p, int layer, bf16_t* wb) {
;     ...
;         if (r < I0) { transpose_item(w_in, 1024, ldw_in, nin / 32, wb, scr, r, lane); continue; } r -= I0;
.LBB0_27:
	s_andn2_saveexec_b64 s[8:9], s[8:9]
	s_cbranch_execz .LBB0_16
	v_mul_hi_i32 v2, v21, s28
	v_lshrrev_b32_e32 v22, 31, v2
	v_ashrrev_i32_e32 v2, 4, v2
	v_add_u32_e32 v2, v2, v22
	v_lshlrev_b32_e32 v22, 6, v2
	v_mad_u64_u32 v[44:45], s[10:11], v2, s16, v[20:21]
	v_or_b32_e32 v2, v22, v24
	v_ashrrev_i32_e32 v45, 31, v44
	v_lshl_add_u64 v[40:41], v[44:45], 2, v[18:19]
	v_or_b32_e32 v23, 2, v2
	v_mad_i64_i32 v[46:47], s[10:11], v23, s29, v[40:41]
	v_or_b32_e32 v23, 4, v2
	v_mad_i64_i32 v[48:49], s[10:11], v23, s29, v[40:41]
	v_or_b32_e32 v23, 6, v2
	v_mad_i64_i32 v[50:51], s[10:11], v23, s29, v[40:41]
	v_or_b32_e32 v23, 8, v2
	v_mad_i64_i32 v[52:53], s[10:11], v23, s29, v[40:41]
	v_or_b32_e32 v23, 10, v2
	v_mad_i64_i32 v[54:55], s[10:11], v23, s29, v[40:41]
	v_or_b32_e32 v23, 12, v2
	v_mad_i64_i32 v[42:43], s[10:11], v2, s29, v[40:41]
	v_mad_i64_i32 v[56:57], s[10:11], v23, s29, v[40:41]
	v_or_b32_e32 v23, 14, v2
	v_mad_i64_i32 v[58:59], s[10:11], v23, s29, v[40:41]
	global_load_dword v23, v[42:43], off nt
	global_load_dword v45, v[46:47], off nt
	global_load_dword v60, v[48:49], off nt
	global_load_dword v61, v[50:51], off nt
	global_load_dword v62, v[52:53], off nt
	global_load_dword v63, v[54:55], off nt
	global_load_dword v64, v[56:57], off nt
	global_load_dword v65, v[58:59], off nt
	v_or_b32_e32 v42, 16, v2
	v_mad_i64_i32 v[42:43], s[10:11], v42, s29, v[40:41]
	v_or_b32_e32 v46, 18, v2
	v_or_b32_e32 v48, 20, v2
	v_or_b32_e32 v50, 22, v2
	v_or_b32_e32 v52, 24, v2
	v_or_b32_e32 v54, 26, v2
	v_or_b32_e32 v56, 28, v2
	v_or_b32_e32 v58, 30, v2
	v_mad_i64_i32 v[46:47], s[10:11], v46, s29, v[40:41]
	v_mad_i64_i32 v[48:49], s[10:11], v48, s29, v[40:41]
	v_mad_i64_i32 v[50:51], s[10:11], v50, s29, v[40:41]
	v_mad_i64_i32 v[52:53], s[10:11], v52, s29, v[40:41]
	v_mad_i64_i32 v[54:55], s[10:11], v54, s29, v[40:41]
	v_mad_i64_i32 v[56:57], s[10:11], v56, s29, v[40:41]
	v_mad_i64_i32 v[58:59], s[10:11], v58, s29, v[40:41]
	global_load_dword v66, v[42:43], off nt
	global_load_dword v67, v[46:47], off nt
	global_load_dword v68, v[48:49], off nt
	global_load_dword v69, v[50:51], off nt
	global_load_dword v70, v[52:53], off nt
	global_load_dword v71, v[54:55], off nt
	global_load_dword v72, v[56:57], off nt
	global_load_dword v73, v[58:59], off nt
	v_or_b32_e32 v42, 32, v2
	v_mad_i64_i32 v[42:43], s[10:11], v42, s29, v[40:41]
	v_or_b32_e32 v46, 34, v2
	v_or_b32_e32 v48, 36, v2
	v_or_b32_e32 v50, 38, v2
	v_or_b32_e32 v52, 40, v2
	v_or_b32_e32 v54, 42, v2
	v_or_b32_e32 v56, 44, v2
	v_or_b32_e32 v58, 46, v2
	v_mad_i64_i32 v[46:47], s[10:11], v46, s29, v[40:41]
	v_mad_i64_i32 v[48:49], s[10:11], v48, s29, v[40:41]
	v_mad_i64_i32 v[50:51], s[10:11], v50, s29, v[40:41]
	v_mad_i64_i32 v[52:53], s[10:11], v52, s29, v[40:41]
	v_mad_i64_i32 v[54:55], s[10:11], v54, s29, v[40:41]
	v_mad_i64_i32 v[56:57], s[10:11], v56, s29, v[40:41]
	v_mad_i64_i32 v[58:59], s[10:11], v58, s29, v[40:41]
	global_load_dword v74, v[42:43], off nt
	global_load_dword v75, v[46:47], off nt
	global_load_dword v76, v[48:49], off nt
	global_load_dword v77, v[50:51], off nt
	global_load_dword v78, v[52:53], off nt
	global_load_dword v79, v[54:55], off nt
	global_load_dword v80, v[56:57], off nt
	global_load_dword v81, v[58:59], off nt
	v_or_b32_e32 v42, 48, v2
	v_mad_i64_i32 v[42:43], s[10:11], v42, s29, v[40:41]
	v_or_b32_e32 v46, 50, v2
	v_or_b32_e32 v48, 52, v2
	v_or_b32_e32 v50, 54, v2
	v_or_b32_e32 v52, 56, v2
	v_or_b32_e32 v54, 58, v2
	v_or_b32_e32 v56, 60, v2
	v_or_b32_e32 v2, 62, v2
	v_mad_i64_i32 v[46:47], s[10:11], v46, s29, v[40:41]
	v_mad_i64_i32 v[48:49], s[10:11], v48, s29, v[40:41]
	v_mad_i64_i32 v[50:51], s[10:11], v50, s29, v[40:41]
	v_mad_i64_i32 v[52:53], s[10:11], v52, s29, v[40:41]
	v_mad_i64_i32 v[54:55], s[10:11], v54, s29, v[40:41]
	v_mad_i64_i32 v[56:57], s[10:11], v56, s29, v[40:41]
	v_mad_i64_i32 v[40:41], s[10:11], v2, s29, v[40:41]
	global_load_dword v2, v[42:43], off nt
	global_load_dword v58, v[46:47], off nt
	global_load_dword v59, v[48:49], off nt
	global_load_dword v82, v[50:51], off nt
	global_load_dword v83, v[52:53], off nt
	global_load_dword v84, v[54:55], off nt
	global_load_dword v85, v[56:57], off nt
	global_load_dword v86, v[40:41], off nt
	s_waitcnt vmcnt(30)
; #define LAS __attribute__((address_space(3)))
; DI unsigned pk2(float lo, float hi) { f32x2 f = {lo, hi}; bf2_t v = __builtin_convertvector(f, bf2_t); return __builtin_bit_cast(unsigned, v); }
; #define scr (p.ws + opq_off(SCR_OFF))
; DI void transpose_item(const float* W, int K, int ldw, int nblk, bf16_t* WT, LAS float* scr, int item, int lane) {
;     ...
;     for (int i = 0; i < 32; ++i) { const int kk = 2 * i + (lane >> 5); scr[kk * 33 + (lane & 31)] = wv_[i]; }
;     asm volatile("s_waitcnt lgkmcnt(0)" ::: "memory");
;     const int c = lane & 7;
; #pragma unroll
;     for (int j = 0; j < 4; ++j) { const int n = (lane >> 3) + 8 * j; const LAS float* s = scr + (8 * c) * 33 + n;
;         u32x4 o; o.x = pk2(s[0 * 33], s[1 * 33]); o.y = pk2(s[2 * 33], s[3 * 33]); o.z = pk2(s[4 * 33], s[5 * 33]); o.w = pk2(s[6 * 33], s[7 * 33]);
;         *(u32x4*)(WT + (size_t)(n0 + n) * K + k0 + 8 * c) = o; }
;     asm volatile("s_waitcnt lgkmcnt(0)" ::: "memory");
	ds_write2_b32 v25, v23, v45 offset1:66
	s_waitcnt vmcnt(28)
	ds_write2_b32 v25, v60, v61 offset0:132 offset1:198
	s_waitcnt vmcnt(26)
	ds_write2_b32 v32, v62, v63 offset0:8 offset1:74
	s_waitcnt vmcnt(24)
	ds_write2_b32 v32, v64, v65 offset0:140 offset1:206
	s_waitcnt vmcnt(22)
	ds_write2_b32 v33, v66, v67 offset0:16 offset1:82
	s_waitcnt vmcnt(20)
	ds_write2_b32 v33, v68, v69 offset0:148 offset1:214
	s_waitcnt vmcnt(18)
	ds_write2_b32 v34, v70, v71 offset0:24 offset1:90
	s_waitcnt vmcnt(16)
	ds_write2_b32 v34, v72, v73 offset0:156 offset1:222
	s_waitcnt vmcnt(14)
	ds_write2_b32 v35, v74, v75 offset0:32 offset1:98
	s_waitcnt vmcnt(12)
	ds_write2_b32 v35, v76, v77 offset0:164 offset1:230
	s_waitcnt vmcnt(10)
	ds_write2_b32 v36, v78, v79 offset0:40 offset1:106
	s_waitcnt vmcnt(8)
	ds_write2_b32 v36, v80, v81 offset0:172 offset1:238
	s_waitcnt vmcnt(6)
	ds_write2_b32 v37, v2, v58 offset0:48 offset1:114
	s_waitcnt vmcnt(4)
	ds_write2_b32 v37, v59, v82 offset0:180 offset1:246
	s_waitcnt vmcnt(2)
	ds_write2_b32 v39, v83, v84 offset0:56 offset1:122
	s_waitcnt vmcnt(0)
	ds_write2_b32 v39, v85, v86 offset0:188 offset1:254
	s_waitcnt lgkmcnt(0)
	ds_read2_b32 v[46:47], v27 offset0:33 offset1:41
	ds_read2_b32 v[48:49], v27 offset1:8
	ds_read2_b32 v[50:51], v27 offset0:66 offset1:74
	ds_read2_b32 v[52:53], v27 offset0:99 offset1:107
	ds_read2_b32 v[54:55], v27 offset0:132 offset1:140
	ds_read2_b32 v[56:57], v27 offset0:165 offset1:173
	ds_read2_b32 v[58:59], v27 offset0:198 offset1:206
	ds_read2_b32 v[60:61], v27 offset0:231 offset1:239
	v_add_u32_e32 v44, v44, v26
	v_ashrrev_i32_e32 v23, 31, v22
	v_ashrrev_i32_e32 v45, 31, v44
	v_lshl_add_u64 v[22:23], v[22:23], 1, v[6:7]
	v_lshlrev_b64 v[62:63], 11, v[44:45]
	s_waitcnt lgkmcnt(6)
	v_cvt_pk_bf16_f32 v40, v48, v46
	s_waitcnt lgkmcnt(4)
	v_cvt_pk_bf16_f32 v41, v50, v52
	s_waitcnt lgkmcnt(2)
	v_cvt_pk_bf16_f32 v42, v54, v56
	s_waitcnt lgkmcnt(0)
	v_cvt_pk_bf16_f32 v43, v58, v60
	v_lshl_add_u64 v[62:63], v[22:23], 0, v[62:63]
	v_add_u32_e32 v46, 8, v44
	global_store_dwordx4 v[62:63], v[40:43], off
	s_nop 1
	v_cvt_pk_bf16_f32 v40, v49, v47
	v_ashrrev_i32_e32 v47, 31, v46
	v_cvt_pk_bf16_f32 v41, v51, v53
	v_cvt_pk_bf16_f32 v42, v55, v57
	v_cvt_pk_bf16_f32 v43, v59, v61
	v_lshlrev_b64 v[46:47], 11, v[46:47]
	ds_read2_b32 v[48:49], v27 offset0:49 offset1:57
	ds_read2_b32 v[50:51], v27 offset0:16 offset1:24
	ds_read2_b32 v[52:53], v27 offset0:82 offset1:90
	ds_read2_b32 v[54:55], v27 offset0:115 offset1:123
	ds_read2_b32 v[56:57], v27 offset0:148 offset1:156
	ds_read2_b32 v[58:59], v27 offset0:181 offset1:189
	ds_read2_b32 v[60:61], v27 offset0:214 offset1:222
	ds_read2_b32 v[62:63], v27 offset0:247 offset1:255
	v_lshl_add_u64 v[46:47], v[22:23], 0, v[46:47]
	global_store_dwordx4 v[46:47], v[40:43], off
	v_add_u32_e32 v46, 16, v44
	v_ashrrev_i32_e32 v47, 31, v46
	v_add_u32_e32 v44, 24, v44
	v_lshlrev_b64 v[46:47], 11, v[46:47]
	v_ashrrev_i32_e32 v45, 31, v44
	s_waitcnt lgkmcnt(6)
	v_cvt_pk_bf16_f32 v40, v50, v48
	s_waitcnt lgkmcnt(4)
	v_cvt_pk_bf16_f32 v41, v52, v54
	s_waitcnt lgkmcnt(2)
	v_cvt_pk_bf16_f32 v42, v56, v58
	s_waitcnt lgkmcnt(0)
	v_cvt_pk_bf16_f32 v43, v60, v62
	v_lshl_add_u64 v[46:47], v[22:23], 0, v[46:47]
	v_lshlrev_b64 v[44:45], 11, v[44:45]
	global_store_dwordx4 v[46:47], v[40:43], off
	v_lshl_add_u64 v[22:23], v[22:23], 0, v[44:45]
	s_nop 0
	v_cvt_pk_bf16_f32 v40, v51, v49
	v_cvt_pk_bf16_f32 v41, v53, v55
	v_cvt_pk_bf16_f32 v42, v57, v59
	v_cvt_pk_bf16_f32 v43, v61, v63
	global_store_dwordx4 v[22:23], v[40:43], off
	s_waitcnt lgkmcnt(0)
	s_branch .LBB0_16

; #define LAS __attribute__((address_space(3)))
; DI void gla_gate_phase(int wv, LAS unsigned char* lds, const float* x, const float* w_in, const float* w2, const float* bg, const bf16_t* qk1,
;                        bf16_t* qd, bf16_t* ki, bf16_t* kst, float* decay, bf16_t* sbuf) {
;     ...
;             for (int i = 0; i < 16; ++i) { const int k = lane + 64 * i; const float x0 = x[t0 * DM + k], x1 = x[(t0 + 1) * DM + k];
; #pragma unroll
;                 for (int q = 0; q < 4; ++q) { const f32x4 w = *(const LAS f32x4*)(wg + k * 16 + 4 * q);
;                     a0[4 * q] += x0 * w.x; a0[4 * q + 1] += x0 * w.y; a0[4 * q + 2] += x0 * w.z; a0[4 * q + 3] += x0 * w.w;
;                     a1[4 * q] += x1 * w.x; a1[4 * q + 1] += x1 * w.y; a1[4 * q + 2] += x1 * w.z; a1[4 * q + 3] += x1 * w.w; } }
.LBB0_143:
	v_or_b32_e32 v8, v2, v50
	v_mov_b32_e32 v9, v3
	v_lshl_add_u64 v[8:9], v[8:9], 2, s[52:53]
	v_mov_b32_e32 v168, v8
	v_mov_b32_e32 v169, v9
	global_load_dword v176, v[4:5], off nt
	global_load_dword v200, v[168:169], off nt
	global_load_dword v177, v[4:5], off offset:256 nt
	global_load_dword v201, v[168:169], off offset:256 nt
	global_load_dword v178, v[4:5], off offset:512 nt
	global_load_dword v202, v[168:169], off offset:512 nt
	global_load_dword v179, v[4:5], off offset:768 nt
	global_load_dword v203, v[168:169], off offset:768 nt
	global_load_dword v180, v[4:5], off offset:1024 nt
	global_load_dword v204, v[168:169], off offset:1024 nt
	global_load_dword v181, v[4:5], off offset:1280 nt
	global_load_dword v205, v[168:169], off offset:1280 nt
	global_load_dword v182, v[4:5], off offset:1536 nt
	global_load_dword v206, v[168:169], off offset:1536 nt
	global_load_dword v183, v[4:5], off offset:1792 nt
	global_load_dword v207, v[168:169], off offset:1792 nt
	global_load_dword v184, v[4:5], off offset:2048 nt
	global_load_dword v208, v[168:169], off offset:2048 nt
	global_load_dword v185, v[4:5], off offset:2304 nt
	global_load_dword v209, v[168:169], off offset:2304 nt
	global_load_dword v186, v[4:5], off offset:2560 nt
	global_load_dword v210, v[168:169], off offset:2560 nt
	global_load_dword v187, v[4:5], off offset:2816 nt
	global_load_dword v211, v[168:169], off offset:2816 nt
	global_load_dword v188, v[4:5], off offset:3072 nt
	global_load_dword v212, v[168:169], off offset:3072 nt
	global_load_dword v189, v[4:5], off offset:3328 nt
	global_load_dword v213, v[168:169], off offset:3328 nt
	global_load_dword v190, v[4:5], off offset:3584 nt
	global_load_dword v214, v[168:169], off offset:3584 nt
	global_load_dword v191, v[4:5], off offset:3840 nt
	global_load_dword v215, v[168:169], off offset:3840 nt
	s_nop 0
	s_waitcnt lgkmcnt(14)
	s_nop 0
	v_add_u32_e32 v16, 0, v49
	ds_read_b128 v[8:11], v16
	ds_read_b128 v[12:15], v16 offset:16
	ds_read_b128 v[116:119], v16 offset:32
	ds_read_b128 v[120:123], v16 offset:48
	s_waitcnt vmcnt(31) lgkmcnt(1)
	v_fma_f32 v98, v176, v116, 0
	v_fma_f32 v96, v176, v117, 0
	s_waitcnt vmcnt(30)
	v_fma_f32 v97, v200, v116, 0
	v_fma_f32 v95, v200, v117, 0
	v_or_b32_e32 v116, v2, v52
	v_mov_b32_e32 v117, v3
	v_lshl_add_u64 v[116:117], v[116:117], 2, s[52:53]
	v_fma_f32 v114, v176, v8, 0
	v_fma_f32 v112, v176, v9, 0
	v_fma_f32 v110, v176, v10, 0
	v_fma_f32 v108, v176, v11, 0
	v_fma_f32 v113, v200, v8, 0
	v_fma_f32 v111, v200, v9, 0
	v_fma_f32 v109, v200, v10, 0
	v_fma_f32 v107, v200, v11, 0
	v_fma_f32 v106, v176, v12, 0
	v_fma_f32 v104, v176, v13, 0
	v_fma_f32 v102, v176, v14, 0
	v_fma_f32 v100, v176, v15, 0
	v_fma_f32 v105, v200, v12, 0
	v_fma_f32 v103, v200, v13, 0
	v_fma_f32 v101, v200, v14, 0
	v_fma_f32 v99, v200, v15, 0
	v_fma_f32 v93, v176, v118, 0
	v_fma_f32 v16, v176, v119, 0
	v_fma_f32 v17, v200, v118, 0
	v_fma_f32 v15, v200, v119, 0
	s_waitcnt lgkmcnt(0)
	v_fma_f32 v14, v176, v120, 0
	v_fma_f32 v12, v176, v121, 0
	v_fma_f32 v10, v176, v122, 0
	v_fma_f32 v8, v176, v123, 0
	v_fma_f32 v13, v200, v120, 0
	v_fma_f32 v11, v200, v121, 0
	v_fma_f32 v9, v200, v122, 0
	v_fma_f32 v7, v200, v123, 0
	s_nop 0
	s_nop 0
	ds_read_b128 v[116:119], v53
	ds_read_b128 v[120:123], v53 offset:16
	ds_read_b128 v[124:127], v53 offset:32
	ds_read_b128 v[128:131], v53 offset:48
	s_waitcnt vmcnt(29) lgkmcnt(3)
	v_fmac_f32_e32 v114, v177, v116
	v_fmac_f32_e32 v112, v177, v117
	s_waitcnt vmcnt(28)
	v_fmac_f32_e32 v113, v201, v116
	v_fmac_f32_e32 v111, v201, v117
	v_or_b32_e32 v116, v2, v54
	v_mov_b32_e32 v117, v3
	v_lshl_add_u64 v[116:117], v[116:117], 2, s[52:53]
	v_fmac_f32_e32 v110, v177, v118
	v_fmac_f32_e32 v108, v177, v119
	v_fmac_f32_e32 v109, v201, v118
	v_fmac_f32_e32 v107, v201, v119
	s_waitcnt lgkmcnt(2)
	v_fmac_f32_e32 v106, v177, v120
	v_fmac_f32_e32 v104, v177, v121
	v_fmac_f32_e32 v102, v177, v122
	v_fmac_f32_e32 v100, v177, v123
	v_fmac_f32_e32 v105, v201, v120
	v_fmac_f32_e32 v103, v201, v121
	v_fmac_f32_e32 v101, v201, v122
	v_fmac_f32_e32 v99, v201, v123
	s_waitcnt lgkmcnt(1)
	v_fmac_f32_e32 v98, v177, v124
	v_fmac_f32_e32 v96, v177, v125
	v_fmac_f32_e32 v93, v177, v126
	v_fmac_f32_e32 v16, v177, v127
	v_fmac_f32_e32 v97, v201, v124
	v_fmac_f32_e32 v95, v201, v125
	v_fmac_f32_e32 v17, v201, v126
	v_fmac_f32_e32 v15, v201, v127
	s_waitcnt lgkmcnt(0)
	v_fmac_f32_e32 v14, v177, v128
	v_fmac_f32_e32 v12, v177, v129
	v_fmac_f32_e32 v10, v177, v130
	v_fmac_f32_e32 v8, v177, v131
	v_fmac_f32_e32 v13, v201, v128
	v_fmac_f32_e32 v11, v201, v129
	v_fmac_f32_e32 v9, v201, v130
	v_fmac_f32_e32 v7, v201, v131
	s_nop 0
	s_nop 0
	ds_read_b128 v[116:119], v55
	ds_read_b128 v[120:123], v55 offset:16
	ds_read_b128 v[124:127], v55 offset:32
	ds_read_b128 v[128:131], v55 offset:48
	s_waitcnt vmcnt(27) lgkmcnt(3)
	v_fmac_f32_e32 v114, v178, v116
	v_fmac_f32_e32 v112, v178, v117
	s_waitcnt vmcnt(26)
	v_fmac_f32_e32 v113, v202, v116
	v_fmac_f32_e32 v111, v202, v117
	v_or_b32_e32 v116, v2, v56
	v_mov_b32_e32 v117, v3
	v_lshl_add_u64 v[116:117], v[116:117], 2, s[52:53]
	v_fmac_f32_e32 v110, v178, v118
	v_fmac_f32_e32 v108, v178, v119
	v_fmac_f32_e32 v109, v202, v118
	v_fmac_f32_e32 v107, v202, v119
	s_waitcnt lgkmcnt(2)
	v_fmac_f32_e32 v106, v178, v120
	v_fmac_f32_e32 v104, v178, v121
	v_fmac_f32_e32 v102, v178, v122
	v_fmac_f32_e32 v100, v178, v123
	v_fmac_f32_e32 v105, v202, v120
	v_fmac_f32_e32 v103, v202, v121
	v_fmac_f32_e32 v101, v202, v122
	v_fmac_f32_e32 v99, v202, v123
	s_waitcnt lgkmcnt(1)
; #define LAS __attribute__((address_space(3)))
; DI void gla_gate_phase(int wv, LAS unsigned char* lds, const float* x, const float* w_in, const float* w2, const float* bg, const bf16_t* qk1,
;                        bf16_t* qd, bf16_t* ki, bf16_t* kst, float* decay, bf16_t* sbuf) {
;     ...
;             for (int i = 0; i < 16; ++i) { const int k = lane + 64 * i; const float x0 = x[t0 * DM + k], x1 = x[(t0 + 1) * DM + k];
; #pragma unroll
;                 for (int q = 0; q < 4; ++q) { const f32x4 w = *(const LAS f32x4*)(wg + k * 16 + 4 * q);
;                     a0[4 * q] += x0 * w.x; a0[4 * q + 1] += x0 * w.y; a0[4 * q + 2] += x0 * w.z; a0[4 * q + 3] += x0 * w.w;
;                     a1[4 * q] += x1 * w.x; a1[4 * q + 1] += x1 * w.y; a1[4 * q + 2] += x1 * w.z; a1[4 * q + 3] += x1 * w.w; } }
	v_fmac_f32_e32 v98, v178, v124
	v_fmac_f32_e32 v96, v178, v125
	v_fmac_f32_e32 v93, v178, v126
	v_fmac_f32_e32 v16, v178, v127
	v_fmac_f32_e32 v97, v202, v124
	v_fmac_f32_e32 v95, v202, v125
	v_fmac_f32_e32 v17, v202, v126
	v_fmac_f32_e32 v15, v202, v127
	s_waitcnt lgkmcnt(0)
	v_fmac_f32_e32 v14, v178, v128
	v_fmac_f32_e32 v12, v178, v129
	v_fmac_f32_e32 v10, v178, v130
	v_fmac_f32_e32 v8, v178, v131
	v_fmac_f32_e32 v13, v202, v128
	v_fmac_f32_e32 v11, v202, v129
	v_fmac_f32_e32 v9, v202, v130
	v_fmac_f32_e32 v7, v202, v131
	s_nop 0
	s_nop 0
	ds_read_b128 v[116:119], v57
	ds_read_b128 v[120:123], v57 offset:16
	ds_read_b128 v[124:127], v57 offset:32
	ds_read_b128 v[128:131], v57 offset:48
	s_waitcnt vmcnt(25) lgkmcnt(3)
	v_fmac_f32_e32 v114, v179, v116
	v_fmac_f32_e32 v112, v179, v117
	s_waitcnt vmcnt(24)
	v_fmac_f32_e32 v113, v203, v116
	v_fmac_f32_e32 v111, v203, v117
	v_or_b32_e32 v116, v2, v58
	v_mov_b32_e32 v117, v3
	v_lshl_add_u64 v[116:117], v[116:117], 2, s[52:53]
	v_fmac_f32_e32 v110, v179, v118
	v_fmac_f32_e32 v108, v179, v119
	v_fmac_f32_e32 v109, v203, v118
	v_fmac_f32_e32 v107, v203, v119
	s_waitcnt lgkmcnt(2)
	v_fmac_f32_e32 v106, v179, v120
	v_fmac_f32_e32 v104, v179, v121
	v_fmac_f32_e32 v102, v179, v122
	v_fmac_f32_e32 v100, v179, v123
	v_fmac_f32_e32 v105, v203, v120
	v_fmac_f32_e32 v103, v203, v121
	v_fmac_f32_e32 v101, v203, v122
	v_fmac_f32_e32 v99, v203, v123
	s_waitcnt lgkmcnt(1)
	v_fmac_f32_e32 v98, v179, v124
	v_fmac_f32_e32 v96, v179, v125
	v_fmac_f32_e32 v93, v179, v126
	v_fmac_f32_e32 v16, v179, v127
	v_fmac_f32_e32 v97, v203, v124
	v_fmac_f32_e32 v95, v203, v125
	v_fmac_f32_e32 v17, v203, v126
	v_fmac_f32_e32 v15, v203, v127
	s_waitcnt lgkmcnt(0)
	v_fmac_f32_e32 v14, v179, v128
	v_fmac_f32_e32 v12, v179, v129
	v_fmac_f32_e32 v10, v179, v130
	v_fmac_f32_e32 v8, v179, v131
	v_fmac_f32_e32 v13, v203, v128
	v_fmac_f32_e32 v11, v203, v129
	v_fmac_f32_e32 v9, v203, v130
	v_fmac_f32_e32 v7, v203, v131
	s_nop 0
	s_nop 0
	ds_read_b128 v[116:119], v59
	ds_read_b128 v[120:123], v59 offset:16
	ds_read_b128 v[124:127], v59 offset:32
	ds_read_b128 v[128:131], v59 offset:48
	s_waitcnt vmcnt(23) lgkmcnt(3)
	v_fmac_f32_e32 v114, v180, v116
	v_fmac_f32_e32 v112, v180, v117
	s_waitcnt vmcnt(22)
	v_fmac_f32_e32 v113, v204, v116
	v_fmac_f32_e32 v111, v204, v117
	v_or_b32_e32 v116, v2, v60
	v_mov_b32_e32 v117, v3
	v_lshl_add_u64 v[116:117], v[116:117], 2, s[52:53]
	v_fmac_f32_e32 v110, v180, v118
	v_fmac_f32_e32 v108, v180, v119
	v_fmac_f32_e32 v109, v204, v118
	v_fmac_f32_e32 v107, v204, v119
	s_waitcnt lgkmcnt(2)
	v_fmac_f32_e32 v106, v180, v120
	v_fmac_f32_e32 v104, v180, v121
	v_fmac_f32_e32 v102, v180, v122
	v_fmac_f32_e32 v100, v180, v123
	v_fmac_f32_e32 v105, v204, v120
	v_fmac_f32_e32 v103, v204, v121
	v_fmac_f32_e32 v101, v204, v122
	v_fmac_f32_e32 v99, v204, v123
	s_waitcnt lgkmcnt(1)
	v_fmac_f32_e32 v98, v180, v124
	v_fmac_f32_e32 v96, v180, v125
	v_fmac_f32_e32 v93, v180, v126
	v_fmac_f32_e32 v16, v180, v127
	v_fmac_f32_e32 v97, v204, v124
	v_fmac_f32_e32 v95, v204, v125
	v_fmac_f32_e32 v17, v204, v126
	v_fmac_f32_e32 v15, v204, v127
	s_waitcnt lgkmcnt(0)
	v_fmac_f32_e32 v14, v180, v128
	v_fmac_f32_e32 v12, v180, v129
	v_fmac_f32_e32 v10, v180, v130
	v_fmac_f32_e32 v8, v180, v131
	v_fmac_f32_e32 v13, v204, v128
	v_fmac_f32_e32 v11, v204, v129
	v_fmac_f32_e32 v9, v204, v130
	v_fmac_f32_e32 v7, v204, v131
	s_nop 0
	s_nop 0
	ds_read_b128 v[116:119], v61
	ds_read_b128 v[120:123], v61 offset:16
	ds_read_b128 v[124:127], v61 offset:32
	ds_read_b128 v[128:131], v61 offset:48
	s_waitcnt vmcnt(21) lgkmcnt(3)
	v_fmac_f32_e32 v114, v181, v116
	v_fmac_f32_e32 v112, v181, v117
	s_waitcnt vmcnt(20)
	v_fmac_f32_e32 v113, v205, v116
	v_fmac_f32_e32 v111, v205, v117
	v_or_b32_e32 v116, v2, v62
	v_mov_b32_e32 v117, v3
	v_lshl_add_u64 v[116:117], v[116:117], 2, s[52:53]
	v_fmac_f32_e32 v110, v181, v118
	v_fmac_f32_e32 v108, v181, v119
	v_fmac_f32_e32 v109, v205, v118
	v_fmac_f32_e32 v107, v205, v119
	s_waitcnt lgkmcnt(2)
	v_fmac_f32_e32 v106, v181, v120
	v_fmac_f32_e32 v104, v181, v121
	v_fmac_f32_e32 v102, v181, v122
	v_fmac_f32_e32 v100, v181, v123
	v_fmac_f32_e32 v105, v205, v120
	v_fmac_f32_e32 v103, v205, v121
	v_fmac_f32_e32 v101, v205, v122
	v_fmac_f32_e32 v99, v205, v123
	s_waitcnt lgkmcnt(1)
	v_fmac_f32_e32 v98, v181, v124
	v_fmac_f32_e32 v96, v181, v125
	v_fmac_f32_e32 v93, v181, v126
	v_fmac_f32_e32 v16, v181, v127
	v_fmac_f32_e32 v97, v205, v124
	v_fmac_f32_e32 v95, v205, v125
	v_fmac_f32_e32 v17, v205, v126
	v_fmac_f32_e32 v15, v205, v127
	s_waitcnt lgkmcnt(0)
	v_fmac_f32_e32 v14, v181, v128
	v_fmac_f32_e32 v12, v181, v129
	v_fmac_f32_e32 v10, v181, v130
	v_fmac_f32_e32 v8, v181, v131
	v_fmac_f32_e32 v13, v205, v128
	v_fmac_f32_e32 v11, v205, v129
	v_fmac_f32_e32 v9, v205, v130
	v_fmac_f32_e32 v7, v205, v131
	s_nop 0
	s_nop 0
	ds_read_b128 v[116:119], v63
	ds_read_b128 v[120:123], v63 offset:16
	ds_read_b128 v[124:127], v63 offset:32
	ds_read_b128 v[128:131], v63 offset:48
	s_waitcnt vmcnt(19) lgkmcnt(3)
	v_fmac_f32_e32 v114, v182, v116
	v_fmac_f32_e32 v112, v182, v117
	s_waitcnt vmcnt(18)
	v_fmac_f32_e32 v113, v206, v116
	v_fmac_f32_e32 v111, v206, v117
	v_or_b32_e32 v116, v2, v64
	v_mov_b32_e32 v117, v3
	v_lshl_add_u64 v[116:117], v[116:117], 2, s[52:53]
	v_fmac_f32_e32 v110, v182, v118
	v_fmac_f32_e32 v108, v182, v119
	v_fmac_f32_e32 v109, v206, v118
	v_fmac_f32_e32 v107, v206, v119
	s_waitcnt lgkmcnt(2)
	v_fmac_f32_e32 v106, v182, v120
	v_fmac_f32_e32 v104, v182, v121
	v_fmac_f32_e32 v102, v182, v122
	v_fmac_f32_e32 v100, v182, v123
	v_fmac_f32_e32 v105, v206, v120
	v_fmac_f32_e32 v103, v206, v121
	v_fmac_f32_e32 v101, v206, v122
	v_fmac_f32_e32 v99, v206, v123
	s_waitcnt lgkmcnt(1)
; #define LAS __attribute__((address_space(3)))
; DI void gla_gate_phase(int wv, LAS unsigned char* lds, const float* x, const float* w_in, const float* w2, const float* bg, const bf16_t* qk1,
;                        bf16_t* qd, bf16_t* ki, bf16_t* kst, float* decay, bf16_t* sbuf) {
;     ...
;             for (int i = 0; i < 16; ++i) { const int k = lane + 64 * i; const float x0 = x[t0 * DM + k], x1 = x[(t0 + 1) * DM + k];
; #pragma unroll
;                 for (int q = 0; q < 4; ++q) { const f32x4 w = *(const LAS f32x4*)(wg + k * 16 + 4 * q);
;                     a0[4 * q] += x0 * w.x; a0[4 * q + 1] += x0 * w.y; a0[4 * q + 2] += x0 * w.z; a0[4 * q + 3] += x0 * w.w;
;                     a1[4 * q] += x1 * w.x; a1[4 * q + 1] += x1 * w.y; a1[4 * q + 2] += x1 * w.z; a1[4 * q + 3] += x1 * w.w; } }
	v_fmac_f32_e32 v98, v182, v124
	v_fmac_f32_e32 v96, v182, v125
	v_fmac_f32_e32 v93, v182, v126
	v_fmac_f32_e32 v16, v182, v127
	v_fmac_f32_e32 v97, v206, v124
	v_fmac_f32_e32 v95, v206, v125
	v_fmac_f32_e32 v17, v206, v126
	v_fmac_f32_e32 v15, v206, v127
	s_waitcnt lgkmcnt(0)
	v_fmac_f32_e32 v14, v182, v128
	v_fmac_f32_e32 v12, v182, v129
	v_fmac_f32_e32 v10, v182, v130
	v_fmac_f32_e32 v8, v182, v131
	v_fmac_f32_e32 v13, v206, v128
	v_fmac_f32_e32 v11, v206, v129
	v_fmac_f32_e32 v9, v206, v130
	v_fmac_f32_e32 v7, v206, v131
	s_nop 0
	s_nop 0
	ds_read_b128 v[116:119], v65
	ds_read_b128 v[120:123], v65 offset:16
	ds_read_b128 v[124:127], v65 offset:32
	ds_read_b128 v[128:131], v65 offset:48
	s_waitcnt vmcnt(17) lgkmcnt(3)
	v_fmac_f32_e32 v114, v183, v116
	v_fmac_f32_e32 v112, v183, v117
	s_waitcnt vmcnt(16)
	v_fmac_f32_e32 v113, v207, v116
	v_fmac_f32_e32 v111, v207, v117
	v_or_b32_e32 v116, v2, v66
	v_mov_b32_e32 v117, v3
	v_lshl_add_u64 v[116:117], v[116:117], 2, s[52:53]
	v_fmac_f32_e32 v110, v183, v118
	v_fmac_f32_e32 v108, v183, v119
	v_fmac_f32_e32 v109, v207, v118
	v_fmac_f32_e32 v107, v207, v119
	s_waitcnt lgkmcnt(2)
	v_fmac_f32_e32 v106, v183, v120
	v_fmac_f32_e32 v104, v183, v121
	v_fmac_f32_e32 v102, v183, v122
	v_fmac_f32_e32 v100, v183, v123
	v_fmac_f32_e32 v105, v207, v120
	v_fmac_f32_e32 v103, v207, v121
	v_fmac_f32_e32 v101, v207, v122
	v_fmac_f32_e32 v99, v207, v123
	s_waitcnt lgkmcnt(1)
	v_fmac_f32_e32 v98, v183, v124
	v_fmac_f32_e32 v96, v183, v125
	v_fmac_f32_e32 v93, v183, v126
	v_fmac_f32_e32 v16, v183, v127
	v_fmac_f32_e32 v97, v207, v124
	v_fmac_f32_e32 v95, v207, v125
	v_fmac_f32_e32 v17, v207, v126
	v_fmac_f32_e32 v15, v207, v127
	s_waitcnt lgkmcnt(0)
	v_fmac_f32_e32 v14, v183, v128
	v_fmac_f32_e32 v12, v183, v129
	v_fmac_f32_e32 v10, v183, v130
	v_fmac_f32_e32 v8, v183, v131
	v_fmac_f32_e32 v13, v207, v128
	v_fmac_f32_e32 v11, v207, v129
	v_fmac_f32_e32 v9, v207, v130
	v_fmac_f32_e32 v7, v207, v131
	s_nop 0
	s_nop 0
	ds_read_b128 v[116:119], v67
	ds_read_b128 v[120:123], v67 offset:16
	ds_read_b128 v[124:127], v67 offset:32
	ds_read_b128 v[128:131], v67 offset:48
	s_waitcnt vmcnt(15) lgkmcnt(3)
	v_fmac_f32_e32 v114, v184, v116
	v_fmac_f32_e32 v112, v184, v117
	s_waitcnt vmcnt(14)
	v_fmac_f32_e32 v113, v208, v116
	v_fmac_f32_e32 v111, v208, v117
	v_or_b32_e32 v116, v2, v68
	v_mov_b32_e32 v117, v3
	v_lshl_add_u64 v[116:117], v[116:117], 2, s[52:53]
	v_fmac_f32_e32 v110, v184, v118
	v_fmac_f32_e32 v108, v184, v119
	v_fmac_f32_e32 v109, v208, v118
	v_fmac_f32_e32 v107, v208, v119
	s_waitcnt lgkmcnt(2)
	v_fmac_f32_e32 v106, v184, v120
	v_fmac_f32_e32 v104, v184, v121
	v_fmac_f32_e32 v102, v184, v122
	v_fmac_f32_e32 v100, v184, v123
	v_fmac_f32_e32 v105, v208, v120
	v_fmac_f32_e32 v103, v208, v121
	v_fmac_f32_e32 v101, v208, v122
	v_fmac_f32_e32 v99, v208, v123
	s_waitcnt lgkmcnt(1)
	v_fmac_f32_e32 v98, v184, v124
	v_fmac_f32_e32 v96, v184, v125
	v_fmac_f32_e32 v93, v184, v126
	v_fmac_f32_e32 v16, v184, v127
	v_fmac_f32_e32 v97, v208, v124
	v_fmac_f32_e32 v95, v208, v125
	v_fmac_f32_e32 v17, v208, v126
	v_fmac_f32_e32 v15, v208, v127
	s_waitcnt lgkmcnt(0)
	v_fmac_f32_e32 v14, v184, v128
	v_fmac_f32_e32 v12, v184, v129
	v_fmac_f32_e32 v10, v184, v130
	v_fmac_f32_e32 v8, v184, v131
	v_fmac_f32_e32 v13, v208, v128
	v_fmac_f32_e32 v11, v208, v129
	v_fmac_f32_e32 v9, v208, v130
	v_fmac_f32_e32 v7, v208, v131
	s_nop 0
	s_nop 0
	ds_read_b128 v[116:119], v69
	ds_read_b128 v[120:123], v69 offset:16
	ds_read_b128 v[124:127], v69 offset:32
	ds_read_b128 v[128:131], v69 offset:48
	s_waitcnt vmcnt(13) lgkmcnt(3)
	v_fmac_f32_e32 v114, v185, v116
	v_fmac_f32_e32 v112, v185, v117
	s_waitcnt vmcnt(12)
	v_fmac_f32_e32 v113, v209, v116
	v_fmac_f32_e32 v111, v209, v117
	v_or_b32_e32 v116, v2, v70
	v_mov_b32_e32 v117, v3
	v_lshl_add_u64 v[116:117], v[116:117], 2, s[52:53]
	v_fmac_f32_e32 v110, v185, v118
	v_fmac_f32_e32 v108, v185, v119
	v_fmac_f32_e32 v109, v209, v118
	v_fmac_f32_e32 v107, v209, v119
	s_waitcnt lgkmcnt(2)
	v_fmac_f32_e32 v106, v185, v120
	v_fmac_f32_e32 v104, v185, v121
	v_fmac_f32_e32 v102, v185, v122
	v_fmac_f32_e32 v100, v185, v123
	v_fmac_f32_e32 v105, v209, v120
	v_fmac_f32_e32 v103, v209, v121
	v_fmac_f32_e32 v101, v209, v122
	v_fmac_f32_e32 v99, v209, v123
	s_waitcnt lgkmcnt(1)
	v_fmac_f32_e32 v98, v185, v124
	v_fmac_f32_e32 v96, v185, v125
	v_fmac_f32_e32 v93, v185, v126
	v_fmac_f32_e32 v16, v185, v127
	v_fmac_f32_e32 v97, v209, v124
	v_fmac_f32_e32 v95, v209, v125
	v_fmac_f32_e32 v17, v209, v126
	v_fmac_f32_e32 v15, v209, v127
	s_waitcnt lgkmcnt(0)
	v_fmac_f32_e32 v14, v185, v128
	v_fmac_f32_e32 v12, v185, v129
	v_fmac_f32_e32 v10, v185, v130
	v_fmac_f32_e32 v8, v185, v131
	v_fmac_f32_e32 v13, v209, v128
	v_fmac_f32_e32 v11, v209, v129
	v_fmac_f32_e32 v9, v209, v130
	v_fmac_f32_e32 v7, v209, v131
	s_nop 0
	s_nop 0
	ds_read_b128 v[116:119], v71
	ds_read_b128 v[120:123], v71 offset:16
	ds_read_b128 v[124:127], v71 offset:32
	ds_read_b128 v[128:131], v71 offset:48
	s_waitcnt vmcnt(11) lgkmcnt(3)
	v_fmac_f32_e32 v114, v186, v116
	v_fmac_f32_e32 v112, v186, v117
	s_waitcnt vmcnt(10)
	v_fmac_f32_e32 v113, v210, v116
	v_fmac_f32_e32 v111, v210, v117
	v_or_b32_e32 v116, v2, v72
	v_mov_b32_e32 v117, v3
	v_lshl_add_u64 v[116:117], v[116:117], 2, s[52:53]
	v_fmac_f32_e32 v110, v186, v118
	v_fmac_f32_e32 v108, v186, v119
	v_fmac_f32_e32 v109, v210, v118
	v_fmac_f32_e32 v107, v210, v119
	s_waitcnt lgkmcnt(2)
	v_fmac_f32_e32 v106, v186, v120
	v_fmac_f32_e32 v104, v186, v121
	v_fmac_f32_e32 v102, v186, v122
	v_fmac_f32_e32 v100, v186, v123
	v_fmac_f32_e32 v105, v210, v120
	v_fmac_f32_e32 v103, v210, v121
	v_fmac_f32_e32 v101, v210, v122
	v_fmac_f32_e32 v99, v210, v123
	s_waitcnt lgkmcnt(1)
; #define LAS __attribute__((address_space(3)))
; DI void gla_gate_phase(int wv, LAS unsigned char* lds, const float* x, const float* w_in, const float* w2, const float* bg, const bf16_t* qk1,
;                        bf16_t* qd, bf16_t* ki, bf16_t* kst, float* decay, bf16_t* sbuf) {
;     ...
;             for (int i = 0; i < 16; ++i) { const int k = lane + 64 * i; const float x0 = x[t0 * DM + k], x1 = x[(t0 + 1) * DM + k];
; #pragma unroll
;                 for (int q = 0; q < 4; ++q) { const f32x4 w = *(const LAS f32x4*)(wg + k * 16 + 4 * q);
;                     a0[4 * q] += x0 * w.x; a0[4 * q + 1] += x0 * w.y; a0[4 * q + 2] += x0 * w.z; a0[4 * q + 3] += x0 * w.w;
;                     a1[4 * q] += x1 * w.x; a1[4 * q + 1] += x1 * w.y; a1[4 * q + 2] += x1 * w.z; a1[4 * q + 3] += x1 * w.w; } }
	v_fmac_f32_e32 v98, v186, v124
	v_fmac_f32_e32 v96, v186, v125
	v_fmac_f32_e32 v93, v186, v126
	v_fmac_f32_e32 v16, v186, v127
	v_fmac_f32_e32 v97, v210, v124
	v_fmac_f32_e32 v95, v210, v125
	v_fmac_f32_e32 v17, v210, v126
	v_fmac_f32_e32 v15, v210, v127
	s_waitcnt lgkmcnt(0)
	v_fmac_f32_e32 v14, v186, v128
	v_fmac_f32_e32 v12, v186, v129
	v_fmac_f32_e32 v10, v186, v130
	v_fmac_f32_e32 v8, v186, v131
	v_fmac_f32_e32 v13, v210, v128
	v_fmac_f32_e32 v11, v210, v129
	v_fmac_f32_e32 v9, v210, v130
	v_fmac_f32_e32 v7, v210, v131
	s_nop 0
	s_nop 0
	ds_read_b128 v[116:119], v73
	ds_read_b128 v[120:123], v73 offset:16
	ds_read_b128 v[124:127], v73 offset:32
	ds_read_b128 v[128:131], v73 offset:48
	s_waitcnt vmcnt(9) lgkmcnt(3)
	v_fmac_f32_e32 v114, v187, v116
	v_fmac_f32_e32 v112, v187, v117
	s_waitcnt vmcnt(8)
	v_fmac_f32_e32 v113, v211, v116
	v_fmac_f32_e32 v111, v211, v117
	v_or_b32_e32 v116, v2, v74
	v_mov_b32_e32 v117, v3
	v_lshl_add_u64 v[116:117], v[116:117], 2, s[52:53]
	v_fmac_f32_e32 v110, v187, v118
	v_fmac_f32_e32 v108, v187, v119
	v_fmac_f32_e32 v109, v211, v118
	v_fmac_f32_e32 v107, v211, v119
	s_waitcnt lgkmcnt(2)
	v_fmac_f32_e32 v106, v187, v120
	v_fmac_f32_e32 v104, v187, v121
	v_fmac_f32_e32 v102, v187, v122
	v_fmac_f32_e32 v100, v187, v123
	v_fmac_f32_e32 v105, v211, v120
	v_fmac_f32_e32 v103, v211, v121
	v_fmac_f32_e32 v101, v211, v122
	v_fmac_f32_e32 v99, v211, v123
	s_waitcnt lgkmcnt(1)
	v_fmac_f32_e32 v98, v187, v124
	v_fmac_f32_e32 v96, v187, v125
	v_fmac_f32_e32 v93, v187, v126
	v_fmac_f32_e32 v16, v187, v127
	v_fmac_f32_e32 v97, v211, v124
	v_fmac_f32_e32 v95, v211, v125
	v_fmac_f32_e32 v17, v211, v126
	v_fmac_f32_e32 v15, v211, v127
	s_waitcnt lgkmcnt(0)
	v_fmac_f32_e32 v14, v187, v128
	v_fmac_f32_e32 v12, v187, v129
	v_fmac_f32_e32 v10, v187, v130
	v_fmac_f32_e32 v8, v187, v131
	v_fmac_f32_e32 v13, v211, v128
	v_fmac_f32_e32 v11, v211, v129
	v_fmac_f32_e32 v9, v211, v130
	v_fmac_f32_e32 v7, v211, v131
	s_nop 0
	s_nop 0
	ds_read_b128 v[116:119], v75
	ds_read_b128 v[120:123], v75 offset:16
	ds_read_b128 v[124:127], v75 offset:32
	ds_read_b128 v[128:131], v75 offset:48
	s_waitcnt vmcnt(7) lgkmcnt(3)
	v_fmac_f32_e32 v114, v188, v116
	v_fmac_f32_e32 v112, v188, v117
	s_waitcnt vmcnt(6)
	v_fmac_f32_e32 v113, v212, v116
	v_fmac_f32_e32 v111, v212, v117
	v_or_b32_e32 v116, v2, v76
	v_mov_b32_e32 v117, v3
	v_lshl_add_u64 v[116:117], v[116:117], 2, s[52:53]
	v_fmac_f32_e32 v110, v188, v118
	v_fmac_f32_e32 v108, v188, v119
	v_fmac_f32_e32 v109, v212, v118
	v_fmac_f32_e32 v107, v212, v119
	s_waitcnt lgkmcnt(2)
	v_fmac_f32_e32 v106, v188, v120
	v_fmac_f32_e32 v104, v188, v121
	v_fmac_f32_e32 v102, v188, v122
	v_fmac_f32_e32 v100, v188, v123
	v_fmac_f32_e32 v105, v212, v120
	v_fmac_f32_e32 v103, v212, v121
	v_fmac_f32_e32 v101, v212, v122
	v_fmac_f32_e32 v99, v212, v123
	s_waitcnt lgkmcnt(1)
	v_fmac_f32_e32 v98, v188, v124
	v_fmac_f32_e32 v96, v188, v125
	v_fmac_f32_e32 v93, v188, v126
	v_fmac_f32_e32 v16, v188, v127
	v_fmac_f32_e32 v97, v212, v124
	v_fmac_f32_e32 v95, v212, v125
	v_fmac_f32_e32 v17, v212, v126
	v_fmac_f32_e32 v15, v212, v127
	s_waitcnt lgkmcnt(0)
	v_fmac_f32_e32 v14, v188, v128
	v_fmac_f32_e32 v12, v188, v129
	v_fmac_f32_e32 v10, v188, v130
	v_fmac_f32_e32 v8, v188, v131
	v_fmac_f32_e32 v13, v212, v128
	v_fmac_f32_e32 v11, v212, v129
	v_fmac_f32_e32 v9, v212, v130
	v_fmac_f32_e32 v7, v212, v131
	s_nop 0
	s_nop 0
	ds_read_b128 v[116:119], v77
	ds_read_b128 v[120:123], v77 offset:16
	ds_read_b128 v[124:127], v77 offset:32
	ds_read_b128 v[128:131], v77 offset:48
	s_waitcnt vmcnt(5) lgkmcnt(3)
	v_fmac_f32_e32 v114, v189, v116
	v_fmac_f32_e32 v112, v189, v117
	s_waitcnt vmcnt(4)
	v_fmac_f32_e32 v113, v213, v116
	v_fmac_f32_e32 v111, v213, v117
	v_or_b32_e32 v116, v2, v78
	v_mov_b32_e32 v117, v3
	v_lshl_add_u64 v[116:117], v[116:117], 2, s[52:53]
	v_fmac_f32_e32 v110, v189, v118
	v_fmac_f32_e32 v108, v189, v119
	v_fmac_f32_e32 v109, v213, v118
	v_fmac_f32_e32 v107, v213, v119
	s_waitcnt lgkmcnt(2)
	v_fmac_f32_e32 v106, v189, v120
	v_fmac_f32_e32 v104, v189, v121
	v_fmac_f32_e32 v102, v189, v122
	v_fmac_f32_e32 v100, v189, v123
	v_fmac_f32_e32 v105, v213, v120
	v_fmac_f32_e32 v103, v213, v121
	v_fmac_f32_e32 v101, v213, v122
	v_fmac_f32_e32 v99, v213, v123
	s_waitcnt lgkmcnt(1)
	v_fmac_f32_e32 v98, v189, v124
	v_fmac_f32_e32 v96, v189, v125
	v_fmac_f32_e32 v93, v189, v126
	v_fmac_f32_e32 v16, v189, v127
	v_fmac_f32_e32 v97, v213, v124
	v_fmac_f32_e32 v95, v213, v125
	v_fmac_f32_e32 v17, v213, v126
	v_fmac_f32_e32 v15, v213, v127
	s_waitcnt lgkmcnt(0)
	v_fmac_f32_e32 v14, v189, v128
	v_fmac_f32_e32 v12, v189, v129
	v_fmac_f32_e32 v10, v189, v130
	v_fmac_f32_e32 v8, v189, v131
	v_fmac_f32_e32 v13, v213, v128
	v_fmac_f32_e32 v11, v213, v129
	v_fmac_f32_e32 v9, v213, v130
	v_fmac_f32_e32 v7, v213, v131
	s_nop 0
	s_nop 0
	ds_read_b128 v[116:119], v79
	ds_read_b128 v[120:123], v79 offset:16
	ds_read_b128 v[124:127], v79 offset:32
	ds_read_b128 v[128:131], v79 offset:48
	s_waitcnt vmcnt(3) lgkmcnt(3)
	v_fmac_f32_e32 v114, v190, v116
	v_fmac_f32_e32 v112, v190, v117
	s_waitcnt vmcnt(2)
	v_fmac_f32_e32 v113, v214, v116
	v_fmac_f32_e32 v111, v214, v117
	v_or_b32_e32 v116, v2, v80
	v_mov_b32_e32 v117, v3
	v_lshl_add_u64 v[116:117], v[116:117], 2, s[52:53]
	v_fmac_f32_e32 v110, v190, v118
	v_fmac_f32_e32 v108, v190, v119
	v_fmac_f32_e32 v109, v214, v118
	v_fmac_f32_e32 v107, v214, v119
	s_waitcnt lgkmcnt(2)
	v_fmac_f32_e32 v106, v190, v120
	v_fmac_f32_e32 v104, v190, v121
	v_fmac_f32_e32 v102, v190, v122
	v_fmac_f32_e32 v100, v190, v123
	v_fmac_f32_e32 v105, v214, v120
	v_fmac_f32_e32 v103, v214, v121
	v_fmac_f32_e32 v101, v214, v122
	v_fmac_f32_e32 v99, v214, v123
	s_waitcnt lgkmcnt(1)
; #define LAS __attribute__((address_space(3)))
; DI void gla_gate_phase(int wv, LAS unsigned char* lds, const float* x, const float* w_in, const float* w2, const float* bg, const bf16_t* qk1,
;                        bf16_t* qd, bf16_t* ki, bf16_t* kst, float* decay, bf16_t* sbuf) {
;     ...
;             for (int i = 0; i < 16; ++i) { const int k = lane + 64 * i; const float x0 = x[t0 * DM + k], x1 = x[(t0 + 1) * DM + k];
; #pragma unroll
;                 for (int q = 0; q < 4; ++q) { const f32x4 w = *(const LAS f32x4*)(wg + k * 16 + 4 * q);
;                     a0[4 * q] += x0 * w.x; a0[4 * q + 1] += x0 * w.y; a0[4 * q + 2] += x0 * w.z; a0[4 * q + 3] += x0 * w.w;
;                     a1[4 * q] += x1 * w.x; a1[4 * q + 1] += x1 * w.y; a1[4 * q + 2] += x1 * w.z; a1[4 * q + 3] += x1 * w.w; } }
;             float v0 = 0.f, v1 = 0.f;
; #pragma unroll
;             for (int n = 0; n < 16; ++n) { const float s0 = wave_sum(a0[n]), s1 = wave_sum(a1[n]); v0 = (lane == n) ? s0 : v0; v1 = (lane == n) ? s1 : v1; }
	v_fmac_f32_e32 v98, v190, v124
	v_fmac_f32_e32 v96, v190, v125
	v_fmac_f32_e32 v93, v190, v126
	v_fmac_f32_e32 v16, v190, v127
	v_fmac_f32_e32 v97, v214, v124
	v_fmac_f32_e32 v95, v214, v125
	v_fmac_f32_e32 v17, v214, v126
	v_fmac_f32_e32 v15, v214, v127
	s_waitcnt lgkmcnt(0)
	v_fmac_f32_e32 v14, v190, v128
	v_fmac_f32_e32 v12, v190, v129
	v_fmac_f32_e32 v10, v190, v130
	v_fmac_f32_e32 v8, v190, v131
	v_fmac_f32_e32 v13, v214, v128
	v_fmac_f32_e32 v11, v214, v129
	v_fmac_f32_e32 v9, v214, v130
	v_fmac_f32_e32 v7, v214, v131
	s_nop 0
	s_nop 0
	ds_read_b128 v[116:119], v81
	ds_read_b128 v[120:123], v81 offset:16
	ds_read_b128 v[124:127], v81 offset:32
	ds_read_b128 v[128:131], v81 offset:48
	s_waitcnt vmcnt(1) lgkmcnt(3)
	v_fmac_f32_e32 v114, v191, v116
	v_fmac_f32_e32 v112, v191, v117
	v_fmac_f32_e32 v110, v191, v118
	v_fmac_f32_e32 v108, v191, v119
	s_waitcnt vmcnt(0)
	v_fmac_f32_e32 v113, v215, v116
	v_fmac_f32_e32 v111, v215, v117
	v_fmac_f32_e32 v109, v215, v118
	v_fmac_f32_e32 v107, v215, v119
	s_waitcnt lgkmcnt(2)
	v_fmac_f32_e32 v106, v191, v120
	v_fmac_f32_e32 v104, v191, v121
	v_fmac_f32_e32 v102, v191, v122
	v_fmac_f32_e32 v100, v191, v123
	v_fmac_f32_e32 v105, v215, v120
	v_fmac_f32_e32 v103, v215, v121
	v_fmac_f32_e32 v101, v215, v122
	v_fmac_f32_e32 v99, v215, v123
	s_waitcnt lgkmcnt(1)
	v_fmac_f32_e32 v98, v191, v124
	v_fmac_f32_e32 v96, v191, v125
	v_fmac_f32_e32 v93, v191, v126
	v_fmac_f32_e32 v16, v191, v127
	v_fmac_f32_e32 v97, v215, v124
	v_fmac_f32_e32 v95, v215, v125
	v_fmac_f32_e32 v17, v215, v126
	v_fmac_f32_e32 v15, v215, v127
	s_waitcnt lgkmcnt(0)
	v_fmac_f32_e32 v14, v191, v128
	v_fmac_f32_e32 v12, v191, v129
	v_fmac_f32_e32 v10, v191, v130
	v_fmac_f32_e32 v8, v191, v131
	v_fmac_f32_e32 v13, v215, v128
	v_fmac_f32_e32 v11, v215, v129
	v_fmac_f32_e32 v9, v215, v130
	v_fmac_f32_e32 v7, v215, v131
	ds_bpermute_b32 v115, v233, v114
	ds_bpermute_b32 v116, v233, v113
	ds_bpermute_b32 v117, v233, v112
	ds_bpermute_b32 v118, v233, v111
	ds_bpermute_b32 v119, v233, v110
	ds_bpermute_b32 v120, v233, v109
	ds_bpermute_b32 v121, v233, v108
	ds_bpermute_b32 v122, v233, v107
	ds_bpermute_b32 v123, v233, v106
	ds_bpermute_b32 v124, v233, v105
	ds_bpermute_b32 v125, v233, v104
	ds_bpermute_b32 v126, v233, v103
	ds_bpermute_b32 v127, v233, v102
	ds_bpermute_b32 v128, v233, v101
	ds_bpermute_b32 v129, v233, v100
	ds_bpermute_b32 v130, v233, v99
	ds_bpermute_b32 v131, v233, v98
	ds_bpermute_b32 v132, v233, v97
	ds_bpermute_b32 v133, v233, v96
	ds_bpermute_b32 v134, v233, v95
	ds_bpermute_b32 v135, v233, v93
	ds_bpermute_b32 v136, v233, v17
	ds_bpermute_b32 v137, v233, v16
	ds_bpermute_b32 v138, v233, v15
	ds_bpermute_b32 v139, v233, v14
	ds_bpermute_b32 v140, v233, v13
	ds_bpermute_b32 v141, v233, v12
	ds_bpermute_b32 v142, v233, v11
	ds_bpermute_b32 v143, v233, v10
	ds_bpermute_b32 v144, v233, v9
	ds_bpermute_b32 v145, v233, v8
	ds_bpermute_b32 v146, v233, v7
	s_waitcnt lgkmcnt(14)
	v_add_f32_e32 v114, v114, v115
	v_add_f32_e32 v113, v113, v116
	v_add_f32_e32 v112, v112, v117
	v_add_f32_e32 v111, v111, v118
	v_add_f32_e32 v110, v110, v119
	v_add_f32_e32 v109, v109, v120
	v_add_f32_e32 v108, v108, v121
	v_add_f32_e32 v107, v107, v122
	v_add_f32_e32 v106, v106, v123
	v_add_f32_e32 v105, v105, v124
	v_add_f32_e32 v104, v104, v125
	v_add_f32_e32 v103, v103, v126
	v_add_f32_e32 v102, v102, v127
	v_add_f32_e32 v101, v101, v128
	v_add_f32_e32 v100, v100, v129
	v_add_f32_e32 v99, v99, v130
	v_add_f32_e32 v98, v98, v131
	v_add_f32_e32 v97, v97, v132
	s_waitcnt lgkmcnt(13)
	v_add_f32_e32 v96, v96, v133
	s_waitcnt lgkmcnt(12)
	v_add_f32_e32 v95, v95, v134
	s_waitcnt lgkmcnt(11)
	v_add_f32_e32 v93, v93, v135
	s_waitcnt lgkmcnt(10)
	v_add_f32_e32 v17, v17, v136
	s_waitcnt lgkmcnt(9)
	v_add_f32_e32 v16, v16, v137
	s_waitcnt lgkmcnt(8)
	v_add_f32_e32 v15, v15, v138
	s_waitcnt lgkmcnt(7)
	v_add_f32_e32 v14, v14, v139
	s_waitcnt lgkmcnt(6)
	v_add_f32_e32 v13, v13, v140
	s_waitcnt lgkmcnt(5)
	v_add_f32_e32 v12, v12, v141
	s_waitcnt lgkmcnt(4)
	v_add_f32_e32 v11, v11, v142
	s_waitcnt lgkmcnt(3)
	v_add_f32_e32 v10, v10, v143
	s_waitcnt lgkmcnt(2)
	v_add_f32_e32 v9, v9, v144
	s_waitcnt lgkmcnt(1)
	v_add_f32_e32 v8, v8, v145
	s_waitcnt lgkmcnt(0)
	v_add_f32_e32 v7, v7, v146
	ds_bpermute_b32 v115, v234, v114
	ds_bpermute_b32 v116, v234, v113
	ds_bpermute_b32 v117, v234, v112
	ds_bpermute_b32 v118, v234, v111
	ds_bpermute_b32 v119, v234, v110
	ds_bpermute_b32 v120, v234, v109
	ds_bpermute_b32 v121, v234, v108
	ds_bpermute_b32 v122, v234, v107
	ds_bpermute_b32 v123, v234, v106
	ds_bpermute_b32 v124, v234, v105
	ds_bpermute_b32 v125, v234, v104
	ds_bpermute_b32 v126, v234, v103
	ds_bpermute_b32 v127, v234, v102
	ds_bpermute_b32 v128, v234, v101
	ds_bpermute_b32 v129, v234, v100
	ds_bpermute_b32 v130, v234, v99
	ds_bpermute_b32 v131, v234, v98
	ds_bpermute_b32 v132, v234, v97
	ds_bpermute_b32 v133, v234, v96
	ds_bpermute_b32 v134, v234, v95
	ds_bpermute_b32 v135, v234, v93
	ds_bpermute_b32 v136, v234, v17
	ds_bpermute_b32 v137, v234, v16
	ds_bpermute_b32 v138, v234, v15
	ds_bpermute_b32 v139, v234, v14
	ds_bpermute_b32 v140, v234, v13
	ds_bpermute_b32 v141, v234, v12
	ds_bpermute_b32 v142, v234, v11
	ds_bpermute_b32 v143, v234, v10
	ds_bpermute_b32 v144, v234, v9
	ds_bpermute_b32 v145, v234, v8
	ds_bpermute_b32 v146, v234, v7
	s_waitcnt lgkmcnt(14)
	v_add_f32_e32 v114, v114, v115
	v_add_f32_e32 v113, v113, v116
	v_add_f32_e32 v112, v112, v117
	v_add_f32_e32 v111, v111, v118
	v_add_f32_e32 v110, v110, v119
	v_add_f32_e32 v109, v109, v120
	v_add_f32_e32 v108, v108, v121
	v_add_f32_e32 v107, v107, v122
	v_add_f32_e32 v106, v106, v123
	v_add_f32_e32 v105, v105, v124
	v_add_f32_e32 v104, v104, v125
	v_add_f32_e32 v103, v103, v126
	v_add_f32_e32 v102, v102, v127
	v_add_f32_e32 v101, v101, v128
	v_add_f32_e32 v100, v100, v129
	v_add_f32_e32 v99, v99, v130
	v_add_f32_e32 v98, v98, v131
	v_add_f32_e32 v97, v97, v132
	s_waitcnt lgkmcnt(13)
; DI float wave_sum(float v) {
; #pragma unroll
;     for (int o = 1; o < 64; o <<= 1) v += __shfl_xor(v, o);
;     return v;
; }
; DI void gla_gate_phase(int wv, LAS unsigned char* lds, const float* x, const float* w_in, const float* w2, const float* bg, const bf16_t* qk1,
;                        bf16_t* qd, bf16_t* ki, bf16_t* kst, float* decay, bf16_t* sbuf) {
;     ...
;             for (int n = 0; n < 16; ++n) { const float s0 = wave_sum(a0[n]), s1 = wave_sum(a1[n]); v0 = (lane == n) ? s0 : v0; v1 = (lane == n) ? s1 : v1; }
	v_add_f32_e32 v96, v96, v133
	s_waitcnt lgkmcnt(12)
	v_add_f32_e32 v95, v95, v134
	s_waitcnt lgkmcnt(11)
	v_add_f32_e32 v93, v93, v135
	s_waitcnt lgkmcnt(10)
	v_add_f32_e32 v17, v17, v136
	s_waitcnt lgkmcnt(9)
	v_add_f32_e32 v16, v16, v137
	s_waitcnt lgkmcnt(8)
	v_add_f32_e32 v15, v15, v138
	s_waitcnt lgkmcnt(7)
	v_add_f32_e32 v14, v14, v139
	s_waitcnt lgkmcnt(6)
	v_add_f32_e32 v13, v13, v140
	s_waitcnt lgkmcnt(5)
	v_add_f32_e32 v12, v12, v141
	s_waitcnt lgkmcnt(4)
	v_add_f32_e32 v11, v11, v142
	s_waitcnt lgkmcnt(3)
	v_add_f32_e32 v10, v10, v143
	s_waitcnt lgkmcnt(2)
	v_add_f32_e32 v9, v9, v144
	s_waitcnt lgkmcnt(1)
	v_add_f32_e32 v8, v8, v145
	s_waitcnt lgkmcnt(0)
	v_add_f32_e32 v7, v7, v146
	ds_bpermute_b32 v115, v235, v114
	ds_bpermute_b32 v116, v235, v113
	ds_bpermute_b32 v117, v235, v112
	ds_bpermute_b32 v118, v235, v111
	ds_bpermute_b32 v119, v235, v110
	ds_bpermute_b32 v120, v235, v109
	ds_bpermute_b32 v121, v235, v108
	ds_bpermute_b32 v122, v235, v107
	ds_bpermute_b32 v123, v235, v106
	ds_bpermute_b32 v124, v235, v105
	ds_bpermute_b32 v125, v235, v104
	ds_bpermute_b32 v126, v235, v103
	ds_bpermute_b32 v127, v235, v102
	ds_bpermute_b32 v128, v235, v101
	ds_bpermute_b32 v129, v235, v100
	ds_bpermute_b32 v130, v235, v99
	ds_bpermute_b32 v131, v235, v98
	ds_bpermute_b32 v132, v235, v97
	ds_bpermute_b32 v133, v235, v96
	ds_bpermute_b32 v134, v235, v95
	ds_bpermute_b32 v135, v235, v93
	ds_bpermute_b32 v136, v235, v17
	ds_bpermute_b32 v137, v235, v16
	ds_bpermute_b32 v138, v235, v15
	ds_bpermute_b32 v139, v235, v14
	ds_bpermute_b32 v140, v235, v13
	ds_bpermute_b32 v141, v235, v12
	ds_bpermute_b32 v142, v235, v11
	ds_bpermute_b32 v143, v235, v10
	ds_bpermute_b32 v144, v235, v9
	ds_bpermute_b32 v145, v235, v8
	ds_bpermute_b32 v146, v235, v7
	s_waitcnt lgkmcnt(14)
	v_add_f32_e32 v114, v114, v115
	v_add_f32_e32 v113, v113, v116
	v_add_f32_e32 v112, v112, v117
	v_add_f32_e32 v111, v111, v118
	v_add_f32_e32 v110, v110, v119
	v_add_f32_e32 v109, v109, v120
	v_add_f32_e32 v108, v108, v121
	v_add_f32_e32 v107, v107, v122
	v_add_f32_e32 v106, v106, v123
	v_add_f32_e32 v105, v105, v124
	v_add_f32_e32 v104, v104, v125
	v_add_f32_e32 v103, v103, v126
	v_add_f32_e32 v102, v102, v127
	v_add_f32_e32 v101, v101, v128
	v_add_f32_e32 v100, v100, v129
	v_add_f32_e32 v99, v99, v130
	v_add_f32_e32 v98, v98, v131
	v_add_f32_e32 v97, v97, v132
	s_waitcnt lgkmcnt(13)
	v_add_f32_e32 v96, v96, v133
	s_waitcnt lgkmcnt(12)
	v_add_f32_e32 v95, v95, v134
	s_waitcnt lgkmcnt(11)
	v_add_f32_e32 v93, v93, v135
	s_waitcnt lgkmcnt(10)
	v_add_f32_e32 v17, v17, v136
	s_waitcnt lgkmcnt(9)
	v_add_f32_e32 v16, v16, v137
	s_waitcnt lgkmcnt(8)
	v_add_f32_e32 v15, v15, v138
	s_waitcnt lgkmcnt(7)
	v_add_f32_e32 v14, v14, v139
	s_waitcnt lgkmcnt(6)
	v_add_f32_e32 v13, v13, v140
	s_waitcnt lgkmcnt(5)
	v_add_f32_e32 v12, v12, v141
	s_waitcnt lgkmcnt(4)
	v_add_f32_e32 v11, v11, v142
	s_waitcnt lgkmcnt(3)
	v_add_f32_e32 v10, v10, v143
	s_waitcnt lgkmcnt(2)
	v_add_f32_e32 v9, v9, v144
	s_waitcnt lgkmcnt(1)
	v_add_f32_e32 v8, v8, v145
	s_waitcnt lgkmcnt(0)
	v_add_f32_e32 v7, v7, v146
	ds_bpermute_b32 v115, v236, v114
	ds_bpermute_b32 v116, v236, v113
	ds_bpermute_b32 v117, v236, v112
	ds_bpermute_b32 v118, v236, v111
	ds_bpermute_b32 v119, v236, v110
	ds_bpermute_b32 v120, v236, v109
	ds_bpermute_b32 v121, v236, v108
	ds_bpermute_b32 v122, v236, v107
	ds_bpermute_b32 v123, v236, v106
	ds_bpermute_b32 v124, v236, v105
	ds_bpermute_b32 v125, v236, v104
	ds_bpermute_b32 v126, v236, v103
	ds_bpermute_b32 v127, v236, v102
	ds_bpermute_b32 v128, v236, v101
	ds_bpermute_b32 v129, v236, v100
	ds_bpermute_b32 v130, v236, v99
	ds_bpermute_b32 v131, v236, v98
	ds_bpermute_b32 v132, v236, v97
	ds_bpermute_b32 v133, v236, v96
	ds_bpermute_b32 v134, v236, v95
	ds_bpermute_b32 v135, v236, v93
	ds_bpermute_b32 v136, v236, v17
	ds_bpermute_b32 v137, v236, v16
	ds_bpermute_b32 v138, v236, v15
	ds_bpermute_b32 v139, v236, v14
	ds_bpermute_b32 v140, v236, v13
	ds_bpermute_b32 v141, v236, v12
	ds_bpermute_b32 v142, v236, v11
	ds_bpermute_b32 v143, v236, v10
	ds_bpermute_b32 v144, v236, v9
	ds_bpermute_b32 v145, v236, v8
	ds_bpermute_b32 v146, v236, v7
	s_waitcnt lgkmcnt(14)
	v_add_f32_e32 v114, v114, v115
	v_add_f32_e32 v113, v113, v116
	v_add_f32_e32 v112, v112, v117
	v_add_f32_e32 v111, v111, v118
	v_add_f32_e32 v110, v110, v119
	v_add_f32_e32 v109, v109, v120
	v_add_f32_e32 v108, v108, v121
	v_add_f32_e32 v107, v107, v122
	v_add_f32_e32 v106, v106, v123
	v_add_f32_e32 v105, v105, v124
	v_add_f32_e32 v104, v104, v125
	v_add_f32_e32 v103, v103, v126
	v_add_f32_e32 v102, v102, v127
	v_add_f32_e32 v101, v101, v128
	v_add_f32_e32 v100, v100, v129
	v_add_f32_e32 v99, v99, v130
	v_add_f32_e32 v98, v98, v131
	v_add_f32_e32 v97, v97, v132
	s_waitcnt lgkmcnt(13)
	v_add_f32_e32 v96, v96, v133
	s_waitcnt lgkmcnt(12)
	v_add_f32_e32 v95, v95, v134
	s_waitcnt lgkmcnt(11)
	v_add_f32_e32 v93, v93, v135
	s_waitcnt lgkmcnt(10)
	v_add_f32_e32 v17, v17, v136
	s_waitcnt lgkmcnt(9)
	v_add_f32_e32 v16, v16, v137
	s_waitcnt lgkmcnt(8)
	v_add_f32_e32 v15, v15, v138
	s_waitcnt lgkmcnt(7)
	v_add_f32_e32 v14, v14, v139
	s_waitcnt lgkmcnt(6)
	v_add_f32_e32 v13, v13, v140
	s_waitcnt lgkmcnt(5)
	v_add_f32_e32 v12, v12, v141
	s_waitcnt lgkmcnt(4)
	v_add_f32_e32 v11, v11, v142
	s_waitcnt lgkmcnt(3)
	v_add_f32_e32 v10, v10, v143
	s_waitcnt lgkmcnt(2)
	v_add_f32_e32 v9, v9, v144
	s_waitcnt lgkmcnt(1)
	v_add_f32_e32 v8, v8, v145
	s_waitcnt lgkmcnt(0)
; DI void gla_gate_phase(int wv, LAS unsigned char* lds, const float* x, const float* w_in, const float* w2, const float* bg, const bf16_t* qk1,
;                        bf16_t* qd, bf16_t* ki, bf16_t* kst, float* decay, bf16_t* sbuf) {
;     ...
;             for (int n = 0; n < 16; ++n) { const float s0 = wave_sum(a0[n]), s1 = wave_sum(a1[n]); v0 = (lane == n) ? s0 : v0; v1 = (lane == n) ? s1 : v1; }
;             if (lane < 16) { gl[(wid * 8 + tt) * 16 + lane] = v0; gl[(wid * 8 + tt + 1) * 16 + lane] = v1; }
	v_add_f32_e32 v7, v7, v146
	ds_bpermute_b32 v115, v237, v114
	ds_bpermute_b32 v116, v237, v113
	ds_bpermute_b32 v117, v237, v112
	ds_bpermute_b32 v118, v237, v111
	ds_bpermute_b32 v119, v237, v110
	ds_bpermute_b32 v120, v237, v109
	ds_bpermute_b32 v121, v237, v108
	ds_bpermute_b32 v122, v237, v107
	ds_bpermute_b32 v123, v237, v106
	ds_bpermute_b32 v124, v237, v105
	ds_bpermute_b32 v125, v237, v104
	ds_bpermute_b32 v126, v237, v103
	ds_bpermute_b32 v127, v237, v102
	ds_bpermute_b32 v128, v237, v101
	ds_bpermute_b32 v129, v237, v100
	ds_bpermute_b32 v130, v237, v99
	ds_bpermute_b32 v131, v237, v98
	ds_bpermute_b32 v132, v237, v97
	ds_bpermute_b32 v133, v237, v96
	ds_bpermute_b32 v134, v237, v95
	ds_bpermute_b32 v135, v237, v93
	ds_bpermute_b32 v136, v237, v17
	ds_bpermute_b32 v137, v237, v16
	ds_bpermute_b32 v138, v237, v15
	ds_bpermute_b32 v139, v237, v14
	ds_bpermute_b32 v140, v237, v13
	ds_bpermute_b32 v141, v237, v12
	ds_bpermute_b32 v142, v237, v11
	ds_bpermute_b32 v143, v237, v10
	ds_bpermute_b32 v144, v237, v9
	ds_bpermute_b32 v145, v237, v8
	ds_bpermute_b32 v146, v237, v7
	s_waitcnt lgkmcnt(14)
	v_add_f32_e32 v114, v114, v115
	v_add_f32_e32 v113, v113, v116
	v_add_f32_e32 v112, v112, v117
	v_add_f32_e32 v111, v111, v118
	v_add_f32_e32 v110, v110, v119
	v_add_f32_e32 v109, v109, v120
	v_add_f32_e32 v108, v108, v121
	v_add_f32_e32 v107, v107, v122
	v_add_f32_e32 v106, v106, v123
	v_add_f32_e32 v105, v105, v124
	v_add_f32_e32 v104, v104, v125
	v_add_f32_e32 v103, v103, v126
	v_add_f32_e32 v102, v102, v127
	v_add_f32_e32 v101, v101, v128
	v_add_f32_e32 v100, v100, v129
	v_add_f32_e32 v99, v99, v130
	v_add_f32_e32 v98, v98, v131
	v_add_f32_e32 v97, v97, v132
	s_waitcnt lgkmcnt(13)
	v_add_f32_e32 v96, v96, v133
	s_waitcnt lgkmcnt(12)
	v_add_f32_e32 v95, v95, v134
	s_waitcnt lgkmcnt(11)
	v_add_f32_e32 v93, v93, v135
	s_waitcnt lgkmcnt(10)
	v_add_f32_e32 v17, v17, v136
	s_waitcnt lgkmcnt(9)
	v_add_f32_e32 v16, v16, v137
	s_waitcnt lgkmcnt(8)
	v_add_f32_e32 v15, v15, v138
	s_waitcnt lgkmcnt(7)
	v_add_f32_e32 v14, v14, v139
	s_waitcnt lgkmcnt(6)
	v_add_f32_e32 v13, v13, v140
	s_waitcnt lgkmcnt(5)
	v_add_f32_e32 v12, v12, v141
	s_waitcnt lgkmcnt(4)
	v_add_f32_e32 v11, v11, v142
	s_waitcnt lgkmcnt(3)
	v_add_f32_e32 v10, v10, v143
	s_waitcnt lgkmcnt(2)
	v_add_f32_e32 v9, v9, v144
	s_waitcnt lgkmcnt(1)
	v_add_f32_e32 v8, v8, v145
	s_waitcnt lgkmcnt(0)
	v_add_f32_e32 v7, v7, v146
	ds_bpermute_b32 v115, v238, v114
	ds_bpermute_b32 v116, v238, v113
	ds_bpermute_b32 v117, v238, v112
	ds_bpermute_b32 v118, v238, v111
	ds_bpermute_b32 v119, v238, v110
	ds_bpermute_b32 v120, v238, v109
	ds_bpermute_b32 v121, v238, v108
	ds_bpermute_b32 v122, v238, v107
	ds_bpermute_b32 v123, v238, v106
	ds_bpermute_b32 v124, v238, v105
	ds_bpermute_b32 v125, v238, v104
	ds_bpermute_b32 v126, v238, v103
	ds_bpermute_b32 v127, v238, v102
	ds_bpermute_b32 v128, v238, v101
	ds_bpermute_b32 v129, v238, v100
	ds_bpermute_b32 v130, v238, v99
	ds_bpermute_b32 v131, v238, v98
	ds_bpermute_b32 v132, v238, v97
	ds_bpermute_b32 v133, v238, v96
	ds_bpermute_b32 v134, v238, v95
	ds_bpermute_b32 v135, v238, v93
	ds_bpermute_b32 v136, v238, v17
	ds_bpermute_b32 v137, v238, v16
	ds_bpermute_b32 v138, v238, v15
	ds_bpermute_b32 v139, v238, v14
	ds_bpermute_b32 v140, v238, v13
	ds_bpermute_b32 v141, v238, v12
	ds_bpermute_b32 v142, v238, v11
	ds_bpermute_b32 v143, v238, v10
	ds_bpermute_b32 v144, v238, v9
	ds_bpermute_b32 v145, v238, v8
	ds_bpermute_b32 v146, v238, v7
	s_and_saveexec_b64 s[44:45], s[42:43]
	s_cbranch_execz .LBB0_142
	s_waitcnt lgkmcnt(14)
	v_add_f32_e32 v113, v113, v116
	v_add_f32_e32 v111, v111, v118
	v_cndmask_b32_e64 v113, 0, v113, s[40:41]
	v_add_f32_e32 v109, v109, v120
	v_cndmask_b32_e64 v111, v113, v111, s[38:39]
	v_add_f32_e32 v107, v107, v122
	v_cndmask_b32_e64 v109, v111, v109, s[36:37]
	v_add_f32_e32 v105, v105, v124
	v_cndmask_b32_e64 v107, v109, v107, s[34:35]
	v_add_f32_e32 v103, v103, v126
	v_cndmask_b32_e64 v105, v107, v105, s[30:31]
	v_add_f32_e32 v101, v101, v128
	v_cndmask_b32_e64 v103, v105, v103, s[28:29]
	v_add_f32_e32 v99, v99, v130
	v_cndmask_b32_e64 v101, v103, v101, s[26:27]
	v_add_f32_e32 v97, v97, v132
	v_cndmask_b32_e64 v99, v101, v99, s[24:25]
	s_waitcnt lgkmcnt(12)
	v_add_f32_e32 v95, v95, v134
	v_cndmask_b32_e64 v97, v99, v97, s[22:23]
	s_waitcnt lgkmcnt(10)
	v_add_f32_e32 v17, v17, v136
	v_cndmask_b32_e64 v95, v97, v95, s[20:21]
	s_waitcnt lgkmcnt(8)
	v_add_f32_e32 v15, v15, v138
	v_cndmask_b32_e64 v17, v95, v17, s[18:19]
	s_waitcnt lgkmcnt(6)
	v_add_f32_e32 v13, v13, v140
	v_cndmask_b32_e64 v15, v17, v15, s[16:17]
	v_add_f32_e32 v99, v114, v115
	s_waitcnt lgkmcnt(4)
	v_add_f32_e32 v11, v11, v142
	v_cndmask_b32_e64 v13, v15, v13, s[14:15]
	v_add_f32_e32 v15, v98, v131
	v_add_f32_e32 v98, v112, v117
	v_cndmask_b32_e64 v99, 0, v99, s[40:41]
	s_waitcnt lgkmcnt(2)
	v_add_f32_e32 v9, v9, v144
	v_cndmask_b32_e64 v11, v13, v11, s[12:13]
	v_add_f32_e32 v97, v110, v119
	v_cndmask_b32_e64 v98, v99, v98, s[38:39]
	v_cndmask_b32_e64 v9, v11, v9, s[10:11]
	v_add_f32_e32 v11, v14, v139
	v_add_f32_e32 v14, v96, v133
	v_add_f32_e32 v96, v108, v121
	v_cndmask_b32_e64 v97, v98, v97, s[36:37]
	v_add_f32_e32 v95, v106, v123
	v_cndmask_b32_e64 v96, v97, v96, s[34:35]
	v_add_f32_e32 v13, v93, v135
	v_add_f32_e32 v93, v104, v125
	v_cndmask_b32_e64 v95, v96, v95, s[30:31]
	s_waitcnt lgkmcnt(0)
	v_add_f32_e32 v7, v7, v146
	v_add_f32_e32 v17, v102, v127
	v_cndmask_b32_e64 v93, v95, v93, s[28:29]
	v_cndmask_b32_e64 v7, v9, v7, s[8:9]
	v_add_f32_e32 v9, v10, v143
	v_add_f32_e32 v10, v12, v141
	v_add_f32_e32 v12, v16, v137
	v_add_f32_e32 v16, v100, v129
	v_cndmask_b32_e64 v17, v93, v17, s[26:27]
	v_cndmask_b32_e64 v16, v17, v16, s[24:25]
	v_cndmask_b32_e64 v15, v16, v15, s[22:23]
	v_cndmask_b32_e64 v14, v15, v14, s[20:21]
	v_cndmask_b32_e64 v13, v14, v13, s[18:19]
	v_cndmask_b32_e64 v12, v13, v12, s[16:17]
	v_cndmask_b32_e64 v11, v12, v11, s[14:15]
	v_cndmask_b32_e64 v10, v11, v10, s[12:13]
	v_add_f32_e32 v8, v8, v145
	v_cndmask_b32_e64 v9, v10, v9, s[10:11]
	v_cndmask_b32_e64 v8, v9, v8, s[8:9]
	ds_write2_b32 v6, v8, v7 offset1:16
	s_branch .LBB0_142

; DI unsigned pk2(float lo, float hi) { f32x2 f = {lo, hi}; bf2_t v = __builtin_convertvector(f, bf2_t); return __builtin_bit_cast(unsigned, v); }
; DI void gla_finish_phase(int wv, const float* obuf, const bf16_t* rb, const float* gn, bf16_t* ob) {
;     ...
;     for (int row0 = bid * 8 + wid; row0 < M_TOK; row0 += 2 * nw) {
;         f32x4 v[2][4]; u32x2 rw[2][4];
; #pragma unroll
;         for (int u = 0; u < 2; ++u) { const int row = (row0 + u * nw < M_TOK) ? row0 + u * nw : row0;
; #pragma unroll
;             for (int i = 0; i < 4; ++i) { v[u][i] = ((const f32x4*)(obuf + (size_t)row * 1024))[lane + 64 * i]; rw[u][i] = ((const u32x2*)(rb + (size_t)row * 1024))[lane + 64 * i]; } }
; #pragma unroll
;         for (int u = 0; u < 2; ++u) { const int row = row0 + u * nw; if (row < M_TOK) {
; #pragma unroll
;             for (int i = 0; i < 4; ++i) {
;                 const f32x4 x = v[u][i];
;                 const float ss = wave_sum((x.x * x.x + x.y * x.y) + (x.z * x.z + x.w * x.w));
;                 const float rn = 1.f / sqrtf(ss * (1.f / 256.f) + 1e-6f);
;                 const u32x2 r_ = rw[u][i];
;                 const float r0 = __uint_as_float(r_.x << 16), r1 = __uint_as_float(r_.x & 0xffff0000u), r2 = __uint_as_float(r_.y << 16), r3 = __uint_as_float(r_.y & 0xffff0000u);
;                 const float s0 = r0 / (1.f + expf(-r0)), s1 = r1 / (1.f + expf(-r1)), s2 = r2 / (1.f + expf(-r2)), s3 = r3 / (1.f + expf(-r3));
;                 u32x2 w; w.x = pk2(x.x * rn * g4.x * s0, x.y * rn * g4.y * s1); w.y = pk2(x.z * rn * g4.z * s2, x.w * rn * g4.w * s3);
;                 ((u32x2*)(ob + (size_t)row * 1024))[lane + 64 * i] = w;
.LBB0_238:
	v_add_u32_e32 v0, s47, v38
	v_cmp_gt_i32_e64 s[0:1], s71, v0
	v_lshl_add_u64 v[34:35], s[48:49], 0, v[48:49]
	v_lshl_add_u64 v[36:37], s[48:49], 0, v[50:51]
	v_cndmask_b32_e64 v6, v38, v0, s[0:1]
	v_ashrrev_i32_e32 v7, 31, v6
	v_lshlrev_b64 v[8:9], 12, v[6:7]
	v_lshlrev_b64 v[6:7], 11, v[6:7]
	v_lshl_add_u64 v[8:9], v[40:41], 0, v[8:9]
	v_lshl_add_u64 v[22:23], v[42:43], 0, v[6:7]
	global_load_dwordx4 v[18:21], v[8:9], off nt
	global_load_dwordx2 v[58:59], v[22:23], off nt
	global_load_dwordx4 v[14:17], v[8:9], off offset:1024 nt
	global_load_dwordx2 v[56:57], v[22:23], off offset:512 nt
	global_load_dwordx4 v[10:13], v[8:9], off offset:2048 nt
	global_load_dwordx2 v[54:55], v[22:23], off offset:1024 nt
	s_nop 0
	global_load_dwordx4 v[6:9], v[8:9], off offset:3072 nt
	s_nop 0
	global_load_dwordx2 v[52:53], v[22:23], off offset:1536 nt
	global_load_dwordx2 v[60:61], v[34:35], off offset:512 nt
	s_nop 0
	global_load_dwordx4 v[22:25], v[36:37], off offset:3072 nt
	global_load_dwordx2 v[62:63], v[34:35], off nt
	global_load_dwordx4 v[26:29], v[36:37], off offset:2048 nt
	global_load_dwordx2 v[64:65], v[34:35], off offset:-512 nt
	global_load_dwordx4 v[30:33], v[36:37], off offset:1024 nt
	global_load_dwordx2 v[66:67], v[34:35], off offset:-1024 nt
	s_nop 0
	global_load_dwordx4 v[34:37], v[36:37], off nt
	s_mov_b32 s2, 0xf800000
	s_waitcnt vmcnt(0)
	v_pk_mul_f32 v[68:69], v[36:37], v[36:37]
	v_pk_mul_f32 v[70:71], v[34:35], v[34:35]
	s_nop 0
	v_pk_mov_b32 v[72:73], v[70:71], v[68:69] op_sel:[1,0]
	v_mov_b32_e32 v71, v69
	v_pk_add_f32 v[68:69], v[72:73], v[70:71]
	s_nop 0
	v_add_f32_e32 v0, v68, v69
	ds_bpermute_b32 v39, v233, v0
	s_waitcnt lgkmcnt(0)
	v_add_f32_e32 v0, v0, v39
	ds_bpermute_b32 v39, v234, v0
	s_waitcnt lgkmcnt(0)
	v_add_f32_e32 v0, v0, v39
	ds_bpermute_b32 v39, v235, v0
	s_waitcnt lgkmcnt(0)
	v_add_f32_e32 v0, v0, v39
	ds_bpermute_b32 v39, v236, v0
	s_waitcnt lgkmcnt(0)
	v_add_f32_e32 v0, v0, v39
	ds_bpermute_b32 v39, v237, v0
	s_waitcnt lgkmcnt(0)
	v_add_f32_e32 v0, v0, v39
	ds_bpermute_b32 v39, v238, v0
	s_waitcnt lgkmcnt(0)
	v_add_f32_e32 v0, v0, v39
	v_fmamk_f32 v0, v0, 0x3b800000, v241
	v_cmp_gt_f32_e32 vcc, s2, v0
	v_mul_f32_e32 v39, 0x4f800000, v0
	s_nop 0
	v_cndmask_b32_e32 v0, v0, v39, vcc
	v_sqrt_f32_e32 v39, v0
	s_nop 0
	v_add_u32_e32 v68, -1, v39
	v_fma_f32 v69, -v68, v39, v0
	v_cmp_ge_f32_e64 s[4:5], 0, v69
	v_add_u32_e32 v69, 1, v39
	s_nop 0
	v_cndmask_b32_e64 v68, v39, v68, s[4:5]
	v_fma_f32 v39, -v69, v39, v0
	v_cmp_lt_f32_e64 s[4:5], 0, v39
	s_nop 1
	v_cndmask_b32_e64 v39, v68, v69, s[4:5]
	v_mul_f32_e32 v68, 0x37800000, v39
	v_cndmask_b32_e32 v39, v39, v68, vcc
	v_cmp_class_f32_e32 vcc, v0, v242
	s_nop 1
	v_cndmask_b32_e32 v0, v39, v0, vcc
	v_div_scale_f32 v39, s[4:5], v0, v0, 1.0
	v_rcp_f32_e32 v68, v39
	s_nop 0
	v_fma_f32 v69, -v39, v68, 1.0
	v_fmac_f32_e32 v68, v69, v68
	v_div_scale_f32 v69, vcc, 1.0, v0, 1.0
	v_mul_f32_e32 v70, v69, v68
	v_fma_f32 v71, -v39, v70, v69
	v_fmac_f32_e32 v70, v71, v68
	v_fma_f32 v39, -v39, v70, v69
	v_div_fmas_f32 v39, v39, v68, v70
	v_div_fixup_f32 v0, v39, v0, 1.0
	v_lshlrev_b32_e32 v39, 16, v66
	v_mul_f32_e32 v68, 0xbfb8aa3b, v39
	v_fma_f32 v69, v39, s89, -v68
	v_rndne_f32_e32 v70, v68
	v_fmac_f32_e32 v69, 0xb2a5705f, v39
	v_sub_f32_e32 v68, v68, v70
	v_add_f32_e32 v68, v68, v69
	v_exp_f32_e32 v68, v68
	v_cvt_i32_f32_e32 v69, v70
	v_and_b32_e32 v66, 0xffff0000, v66
	v_cmp_nlt_f32_e32 vcc, s96, v39
	v_pk_mul_f32 v[34:35], v[34:35], v[0:1] op_sel_hi:[1,0]
	v_ldexp_f32 v68, v68, v69
	v_mul_f32_e32 v69, 0xbfb8aa3b, v66
	v_fma_f32 v70, v66, s89, -v69
	v_rndne_f32_e32 v71, v69
	v_fmac_f32_e32 v70, 0xb2a5705f, v66
	v_sub_f32_e32 v69, v69, v71
	v_add_f32_e32 v69, v69, v70
	v_exp_f32_e32 v69, v69
	v_cvt_i32_f32_e32 v70, v71
	v_cndmask_b32_e32 v68, 0, v68, vcc
	v_cmp_ngt_f32_e32 vcc, s97, v39
	v_pk_mul_f32 v[34:35], v[2:3], v[34:35]
	v_ldexp_f32 v69, v69, v70
	v_cndmask_b32_e32 v68, v246, v68, vcc
	v_cmp_nlt_f32_e32 vcc, s96, v66
	v_pk_mul_f32 v[36:37], v[36:37], v[0:1] op_sel_hi:[1,0]
	s_nop 0
	v_cndmask_b32_e32 v69, 0, v69, vcc
	v_cmp_ngt_f32_e32 vcc, s97, v66
	v_pk_mul_f32 v[36:37], v[4:5], v[36:37]
	s_nop 0
	v_cndmask_b32_e32 v69, v246, v69, vcc
	v_pk_add_f32 v[68:69], v[68:69], 1.0 op_sel_hi:[1,0]
	s_nop 0
	v_div_scale_f32 v70, s[4:5], v69, v69, v66
	v_rcp_f32_e32 v71, v70
	s_nop 0
	v_fma_f32 v72, -v70, v71, 1.0
	v_fmac_f32_e32 v71, v72, v71
	v_div_scale_f32 v72, vcc, v66, v69, v66
	v_mul_f32_e32 v73, v72, v71
	v_fma_f32 v74, -v70, v73, v72
	v_fmac_f32_e32 v73, v74, v71
	v_fma_f32 v70, -v70, v73, v72
	v_div_fmas_f32 v70, v70, v71, v73
	v_div_fixup_f32 v69, v70, v69, v66
	v_div_scale_f32 v66, s[4:5], v68, v68, v39
	v_rcp_f32_e32 v70, v66
	s_nop 0
	v_fma_f32 v71, -v66, v70, 1.0
	v_fmac_f32_e32 v70, v71, v70
	v_div_scale_f32 v71, vcc, v39, v68, v39
	v_mul_f32_e32 v72, v71, v70
	v_fma_f32 v73, -v66, v72, v71
	v_fmac_f32_e32 v72, v73, v70
	v_fma_f32 v66, -v66, v72, v71
	v_div_fmas_f32 v66, v66, v70, v72
	v_div_fixup_f32 v68, v66, v68, v39
	v_pk_mul_f32 v[34:35], v[68:69], v[34:35]
	v_lshlrev_b32_e32 v39, 16, v67
	v_cvt_pk_bf16_f32 v66, v34, v35
	v_mul_f32_e32 v34, 0xbfb8aa3b, v39
	v_fma_f32 v35, v39, s89, -v34
	v_rndne_f32_e32 v68, v34
	v_fmac_f32_e32 v35, 0xb2a5705f, v39
	v_sub_f32_e32 v34, v34, v68
	v_add_f32_e32 v34, v34, v35
	v_exp_f32_e32 v34, v34
	v_cvt_i32_f32_e32 v35, v68
	v_and_b32_e32 v67, 0xffff0000, v67
	v_cmp_nlt_f32_e32 vcc, s96, v39
	v_ldexp_f32 v34, v34, v35
	v_mul_f32_e32 v35, 0xbfb8aa3b, v67
	v_fma_f32 v68, v67, s89, -v35
	v_rndne_f32_e32 v69, v35
	v_fmac_f32_e32 v68, 0xb2a5705f, v67
	v_sub_f32_e32 v35, v35, v69
	v_add_f32_e32 v35, v35, v68
; DI unsigned pk2(float lo, float hi) { f32x2 f = {lo, hi}; bf2_t v = __builtin_convertvector(f, bf2_t); return __builtin_bit_cast(unsigned, v); }
; DI void gla_finish_phase(int wv, const float* obuf, const bf16_t* rb, const float* gn, bf16_t* ob) {
;     ...
;             for (int i = 0; i < 4; ++i) {
;                 const f32x4 x = v[u][i];
;                 const float ss = wave_sum((x.x * x.x + x.y * x.y) + (x.z * x.z + x.w * x.w));
;                 const float rn = 1.f / sqrtf(ss * (1.f / 256.f) + 1e-6f);
;                 const u32x2 r_ = rw[u][i];
;                 const float r0 = __uint_as_float(r_.x << 16), r1 = __uint_as_float(r_.x & 0xffff0000u), r2 = __uint_as_float(r_.y << 16), r3 = __uint_as_float(r_.y & 0xffff0000u);
;                 const float s0 = r0 / (1.f + expf(-r0)), s1 = r1 / (1.f + expf(-r1)), s2 = r2 / (1.f + expf(-r2)), s3 = r3 / (1.f + expf(-r3));
;                 u32x2 w; w.x = pk2(x.x * rn * g4.x * s0, x.y * rn * g4.y * s1); w.y = pk2(x.z * rn * g4.z * s2, x.w * rn * g4.w * s3);
;                 ((u32x2*)(ob + (size_t)row * 1024))[lane + 64 * i] = w;
	v_exp_f32_e32 v35, v35
	v_cvt_i32_f32_e32 v68, v69
	v_cndmask_b32_e32 v34, 0, v34, vcc
	v_cmp_ngt_f32_e32 vcc, s97, v39
	v_ldexp_f32 v35, v35, v68
	s_nop 0
	v_cndmask_b32_e32 v34, v246, v34, vcc
	v_cmp_nlt_f32_e32 vcc, s96, v67
	s_nop 1
	v_cndmask_b32_e32 v35, 0, v35, vcc
	v_cmp_ngt_f32_e32 vcc, s97, v67
	s_nop 1
	v_cndmask_b32_e32 v35, v246, v35, vcc
	v_pk_add_f32 v[34:35], v[34:35], 1.0 op_sel_hi:[1,0]
	s_nop 0
	v_div_scale_f32 v68, s[4:5], v35, v35, v67
	v_rcp_f32_e32 v69, v68
	s_nop 0
	v_fma_f32 v70, -v68, v69, 1.0
	v_fmac_f32_e32 v69, v70, v69
	v_div_scale_f32 v70, vcc, v67, v35, v67
	v_mul_f32_e32 v71, v70, v69
	v_fma_f32 v72, -v68, v71, v70
	v_fmac_f32_e32 v71, v72, v69
	v_fma_f32 v68, -v68, v71, v70
	v_div_fmas_f32 v68, v68, v69, v71
	v_div_fixup_f32 v35, v68, v35, v67
	v_div_scale_f32 v67, s[4:5], v34, v34, v39
	v_rcp_f32_e32 v68, v67
	s_nop 0
	v_fma_f32 v69, -v67, v68, 1.0
	v_fmac_f32_e32 v68, v69, v68
	v_div_scale_f32 v69, vcc, v39, v34, v39
	v_mul_f32_e32 v70, v69, v68
	v_fma_f32 v71, -v67, v70, v69
	v_fmac_f32_e32 v70, v71, v68
	v_fma_f32 v67, -v67, v70, v69
	v_div_fmas_f32 v67, v67, v68, v70
	v_div_fixup_f32 v34, v67, v34, v39
	v_pk_mul_f32 v[34:35], v[34:35], v[36:37]
	v_pk_mul_f32 v[36:37], v[32:33], v[32:33]
	v_cvt_pk_bf16_f32 v67, v34, v35
	v_lshl_add_u64 v[34:35], s[48:49], 0, v[46:47]
	global_store_dwordx2 v[34:35], v[66:67], off offset:-1024
	v_pk_mul_f32 v[66:67], v[30:31], v[30:31]
	s_nop 0
	v_pk_mov_b32 v[68:69], v[66:67], v[36:37] op_sel:[1,0]
	v_mov_b32_e32 v67, v37
	v_pk_add_f32 v[36:37], v[68:69], v[66:67]
	s_nop 0
	v_add_f32_e32 v0, v36, v37
	ds_bpermute_b32 v36, v233, v0
	s_waitcnt lgkmcnt(0)
	v_add_f32_e32 v0, v0, v36
	ds_bpermute_b32 v36, v234, v0
	s_waitcnt lgkmcnt(0)
	v_add_f32_e32 v0, v0, v36
	ds_bpermute_b32 v36, v235, v0
	s_waitcnt lgkmcnt(0)
	v_add_f32_e32 v0, v0, v36
	ds_bpermute_b32 v36, v236, v0
	s_waitcnt lgkmcnt(0)
	v_add_f32_e32 v0, v0, v36
	ds_bpermute_b32 v36, v237, v0
	s_waitcnt lgkmcnt(0)
	v_add_f32_e32 v0, v0, v36
	ds_bpermute_b32 v36, v238, v0
	s_waitcnt lgkmcnt(0)
	v_add_f32_e32 v0, v0, v36
	v_fmamk_f32 v0, v0, 0x3b800000, v241
	v_cmp_gt_f32_e32 vcc, s2, v0
	v_mul_f32_e32 v36, 0x4f800000, v0
	s_nop 0
	v_cndmask_b32_e32 v0, v0, v36, vcc
	v_sqrt_f32_e32 v36, v0
	s_nop 0
	v_add_u32_e32 v37, -1, v36
	v_fma_f32 v39, -v37, v36, v0
	v_cmp_ge_f32_e64 s[4:5], 0, v39
	v_add_u32_e32 v39, 1, v36
	s_nop 0
	v_cndmask_b32_e64 v37, v36, v37, s[4:5]
	v_fma_f32 v36, -v39, v36, v0
	v_cmp_lt_f32_e64 s[4:5], 0, v36
	s_nop 1
	v_cndmask_b32_e64 v36, v37, v39, s[4:5]
	v_mul_f32_e32 v37, 0x37800000, v36
	v_cndmask_b32_e32 v36, v36, v37, vcc
	v_cmp_class_f32_e32 vcc, v0, v242
	s_nop 1
	v_cndmask_b32_e32 v0, v36, v0, vcc
	v_div_scale_f32 v36, s[4:5], v0, v0, 1.0
	v_rcp_f32_e32 v37, v36
	s_nop 0
	v_fma_f32 v39, -v36, v37, 1.0
	v_fmac_f32_e32 v37, v39, v37
	v_div_scale_f32 v39, vcc, 1.0, v0, 1.0
	v_mul_f32_e32 v66, v39, v37
	v_fma_f32 v67, -v36, v66, v39
	v_fmac_f32_e32 v66, v67, v37
	v_fma_f32 v36, -v36, v66, v39
	v_div_fmas_f32 v36, v36, v37, v66
	v_lshlrev_b32_e32 v39, 16, v64
	v_div_fixup_f32 v0, v36, v0, 1.0
	v_mul_f32_e32 v36, 0xbfb8aa3b, v39
	v_fma_f32 v37, v39, s89, -v36
	v_rndne_f32_e32 v66, v36
	v_fmac_f32_e32 v37, 0xb2a5705f, v39
	v_sub_f32_e32 v36, v36, v66
	v_add_f32_e32 v36, v36, v37
	v_exp_f32_e32 v36, v36
	v_cvt_i32_f32_e32 v37, v66
	v_and_b32_e32 v64, 0xffff0000, v64
	v_cmp_nlt_f32_e32 vcc, s96, v39
	v_pk_mul_f32 v[30:31], v[30:31], v[0:1] op_sel_hi:[1,0]
	v_ldexp_f32 v36, v36, v37
	v_mul_f32_e32 v37, 0xbfb8aa3b, v64
	v_fma_f32 v66, v64, s89, -v37
	v_rndne_f32_e32 v67, v37
	v_fmac_f32_e32 v66, 0xb2a5705f, v64
	v_sub_f32_e32 v37, v37, v67
	v_add_f32_e32 v37, v37, v66
	v_exp_f32_e32 v37, v37
	v_cvt_i32_f32_e32 v66, v67
	v_cndmask_b32_e32 v36, 0, v36, vcc
	v_cmp_ngt_f32_e32 vcc, s97, v39
	v_pk_mul_f32 v[30:31], v[2:3], v[30:31]
	v_ldexp_f32 v37, v37, v66
	v_cndmask_b32_e32 v36, v246, v36, vcc
	v_cmp_nlt_f32_e32 vcc, s96, v64
	v_pk_mul_f32 v[32:33], v[32:33], v[0:1] op_sel_hi:[1,0]
	s_nop 0
	v_cndmask_b32_e32 v37, 0, v37, vcc
	v_cmp_ngt_f32_e32 vcc, s97, v64
	v_pk_mul_f32 v[32:33], v[4:5], v[32:33]
	s_nop 0
	v_cndmask_b32_e32 v37, v246, v37, vcc
	v_pk_add_f32 v[36:37], v[36:37], 1.0 op_sel_hi:[1,0]
	s_nop 0
	v_div_scale_f32 v66, s[4:5], v37, v37, v64
	v_rcp_f32_e32 v67, v66
	s_nop 0
	v_fma_f32 v68, -v66, v67, 1.0
	v_fmac_f32_e32 v67, v68, v67
	v_div_scale_f32 v68, vcc, v64, v37, v64
	v_mul_f32_e32 v69, v68, v67
	v_fma_f32 v70, -v66, v69, v68
	v_fmac_f32_e32 v69, v70, v67
	v_fma_f32 v66, -v66, v69, v68
	v_div_fmas_f32 v66, v66, v67, v69
	v_div_fixup_f32 v37, v66, v37, v64
	v_div_scale_f32 v64, s[4:5], v36, v36, v39
	v_rcp_f32_e32 v66, v64
	s_nop 0
	v_fma_f32 v67, -v64, v66, 1.0
	v_fmac_f32_e32 v66, v67, v66
	v_div_scale_f32 v67, vcc, v39, v36, v39
	v_mul_f32_e32 v68, v67, v66
	v_fma_f32 v69, -v64, v68, v67
	v_fmac_f32_e32 v68, v69, v66
	v_fma_f32 v64, -v64, v68, v67
	v_div_fmas_f32 v64, v64, v66, v68
	v_div_fixup_f32 v36, v64, v36, v39
	v_pk_mul_f32 v[30:31], v[36:37], v[30:31]
	v_and_b32_e32 v39, 0xffff0000, v65
	v_cvt_pk_bf16_f32 v30, v30, v31
	v_lshlrev_b32_e32 v31, 16, v65
	v_mul_f32_e32 v36, 0xbfb8aa3b, v31
	v_fma_f32 v37, v31, s89, -v36
	v_rndne_f32_e32 v64, v36
	v_fmac_f32_e32 v37, 0xb2a5705f, v31
	v_sub_f32_e32 v36, v36, v64
	v_add_f32_e32 v36, v36, v37
	v_exp_f32_e32 v36, v36
	v_cvt_i32_f32_e32 v37, v64
	v_cmp_nlt_f32_e32 vcc, s96, v31
	v_ldexp_f32 v36, v36, v37
	v_mul_f32_e32 v37, 0xbfb8aa3b, v39
	v_fma_f32 v64, v39, s89, -v37
	v_rndne_f32_e32 v65, v37
	v_fmac_f32_e32 v64, 0xb2a5705f, v39
	v_sub_f32_e32 v37, v37, v65
	v_add_f32_e32 v37, v37, v64
	v_exp_f32_e32 v37, v37
	v_cvt_i32_f32_e32 v64, v65
; DI unsigned pk2(float lo, float hi) { f32x2 f = {lo, hi}; bf2_t v = __builtin_convertvector(f, bf2_t); return __builtin_bit_cast(unsigned, v); }
; DI void gla_finish_phase(int wv, const float* obuf, const bf16_t* rb, const float* gn, bf16_t* ob) {
;     ...
;             for (int i = 0; i < 4; ++i) {
;                 const f32x4 x = v[u][i];
;                 const float ss = wave_sum((x.x * x.x + x.y * x.y) + (x.z * x.z + x.w * x.w));
;                 const float rn = 1.f / sqrtf(ss * (1.f / 256.f) + 1e-6f);
;                 const u32x2 r_ = rw[u][i];
;                 const float r0 = __uint_as_float(r_.x << 16), r1 = __uint_as_float(r_.x & 0xffff0000u), r2 = __uint_as_float(r_.y << 16), r3 = __uint_as_float(r_.y & 0xffff0000u);
;                 const float s0 = r0 / (1.f + expf(-r0)), s1 = r1 / (1.f + expf(-r1)), s2 = r2 / (1.f + expf(-r2)), s3 = r3 / (1.f + expf(-r3));
;                 u32x2 w; w.x = pk2(x.x * rn * g4.x * s0, x.y * rn * g4.y * s1); w.y = pk2(x.z * rn * g4.z * s2, x.w * rn * g4.w * s3);
;                 ((u32x2*)(ob + (size_t)row * 1024))[lane + 64 * i] = w;
	v_cndmask_b32_e32 v36, 0, v36, vcc
	v_cmp_ngt_f32_e32 vcc, s97, v31
	v_ldexp_f32 v37, v37, v64
	s_nop 0
	v_cndmask_b32_e32 v36, v246, v36, vcc
	v_cmp_nlt_f32_e32 vcc, s96, v39
	s_nop 1
	v_cndmask_b32_e32 v37, 0, v37, vcc
	v_cmp_ngt_f32_e32 vcc, s97, v39
	s_nop 1
	v_cndmask_b32_e32 v37, v246, v37, vcc
	v_pk_add_f32 v[36:37], v[36:37], 1.0 op_sel_hi:[1,0]
	s_nop 0
	v_div_scale_f32 v64, s[4:5], v37, v37, v39
	v_rcp_f32_e32 v65, v64
	s_nop 0
	v_fma_f32 v66, -v64, v65, 1.0
	v_fmac_f32_e32 v65, v66, v65
	v_div_scale_f32 v66, vcc, v39, v37, v39
	v_mul_f32_e32 v67, v66, v65
	v_fma_f32 v68, -v64, v67, v66
	v_fmac_f32_e32 v67, v68, v65
	v_fma_f32 v64, -v64, v67, v66
	v_div_fmas_f32 v64, v64, v65, v67
	v_div_fixup_f32 v37, v64, v37, v39
	v_div_scale_f32 v39, s[4:5], v36, v36, v31
	v_rcp_f32_e32 v64, v39
	s_nop 0
	v_fma_f32 v65, -v39, v64, 1.0
	v_fmac_f32_e32 v64, v65, v64
	v_div_scale_f32 v65, vcc, v31, v36, v31
	v_mul_f32_e32 v66, v65, v64
	v_fma_f32 v67, -v39, v66, v65
	v_fmac_f32_e32 v66, v67, v64
	v_fma_f32 v39, -v39, v66, v65
	v_div_fmas_f32 v39, v39, v64, v66
	v_div_fixup_f32 v36, v39, v36, v31
	v_pk_mul_f32 v[32:33], v[36:37], v[32:33]
	s_nop 0
	v_cvt_pk_bf16_f32 v31, v32, v33
	global_store_dwordx2 v[34:35], v[30:31], off offset:-512
	v_pk_mul_f32 v[30:31], v[28:29], v[28:29]
	v_pk_mul_f32 v[32:33], v[26:27], v[26:27]
	s_nop 0
	v_pk_mov_b32 v[36:37], v[32:33], v[30:31] op_sel:[1,0]
	v_mov_b32_e32 v33, v31
	v_pk_add_f32 v[30:31], v[36:37], v[32:33]
	s_nop 0
	v_add_f32_e32 v0, v30, v31
	ds_bpermute_b32 v30, v233, v0
	s_waitcnt lgkmcnt(0)
	v_add_f32_e32 v0, v0, v30
	ds_bpermute_b32 v30, v234, v0
	s_waitcnt lgkmcnt(0)
	v_add_f32_e32 v0, v0, v30
	ds_bpermute_b32 v30, v235, v0
	s_waitcnt lgkmcnt(0)
	v_add_f32_e32 v0, v0, v30
	ds_bpermute_b32 v30, v236, v0
	s_waitcnt lgkmcnt(0)
	v_add_f32_e32 v0, v0, v30
	ds_bpermute_b32 v30, v237, v0
	s_waitcnt lgkmcnt(0)
	v_add_f32_e32 v0, v0, v30
	ds_bpermute_b32 v30, v238, v0
	s_waitcnt lgkmcnt(0)
	v_add_f32_e32 v0, v0, v30
	v_fmamk_f32 v0, v0, 0x3b800000, v241
	v_cmp_gt_f32_e32 vcc, s2, v0
	v_mul_f32_e32 v30, 0x4f800000, v0
	s_nop 0
	v_cndmask_b32_e32 v0, v0, v30, vcc
	v_sqrt_f32_e32 v30, v0
	s_nop 0
	v_add_u32_e32 v31, -1, v30
	v_fma_f32 v32, -v31, v30, v0
	v_cmp_ge_f32_e64 s[4:5], 0, v32
	v_add_u32_e32 v32, 1, v30
	s_nop 0
	v_cndmask_b32_e64 v31, v30, v31, s[4:5]
	v_fma_f32 v30, -v32, v30, v0
	v_cmp_lt_f32_e64 s[4:5], 0, v30
	s_nop 1
	v_cndmask_b32_e64 v30, v31, v32, s[4:5]
	v_mul_f32_e32 v31, 0x37800000, v30
	v_cndmask_b32_e32 v30, v30, v31, vcc
	v_cmp_class_f32_e32 vcc, v0, v242
	s_nop 1
	v_cndmask_b32_e32 v0, v30, v0, vcc
	v_div_scale_f32 v30, s[4:5], v0, v0, 1.0
	v_rcp_f32_e32 v31, v30
	s_nop 0
	v_fma_f32 v32, -v30, v31, 1.0
	v_fmac_f32_e32 v31, v32, v31
	v_div_scale_f32 v32, vcc, 1.0, v0, 1.0
	v_mul_f32_e32 v33, v32, v31
	v_fma_f32 v36, -v30, v33, v32
	v_fmac_f32_e32 v33, v36, v31
	v_fma_f32 v30, -v30, v33, v32
	v_div_fmas_f32 v30, v30, v31, v33
	v_lshlrev_b32_e32 v32, 16, v62
	v_div_fixup_f32 v0, v30, v0, 1.0
	v_mul_f32_e32 v30, 0xbfb8aa3b, v32
	v_fma_f32 v31, v32, s89, -v30
	v_rndne_f32_e32 v36, v30
	v_fmac_f32_e32 v31, 0xb2a5705f, v32
	v_sub_f32_e32 v30, v30, v36
	v_add_f32_e32 v30, v30, v31
	v_exp_f32_e32 v30, v30
	v_cvt_i32_f32_e32 v31, v36
	v_and_b32_e32 v33, 0xffff0000, v62
	v_cmp_nlt_f32_e32 vcc, s96, v32
	v_pk_mul_f32 v[26:27], v[26:27], v[0:1] op_sel_hi:[1,0]
	v_ldexp_f32 v30, v30, v31
	v_mul_f32_e32 v31, 0xbfb8aa3b, v33
	v_fma_f32 v36, v33, s89, -v31
	v_rndne_f32_e32 v37, v31
	v_fmac_f32_e32 v36, 0xb2a5705f, v33
	v_sub_f32_e32 v31, v31, v37
	v_add_f32_e32 v31, v31, v36
	v_exp_f32_e32 v31, v31
	v_cvt_i32_f32_e32 v36, v37
	v_cndmask_b32_e32 v30, 0, v30, vcc
	v_cmp_ngt_f32_e32 vcc, s97, v32
	v_pk_mul_f32 v[26:27], v[2:3], v[26:27]
	v_ldexp_f32 v31, v31, v36
	v_cndmask_b32_e32 v30, v246, v30, vcc
	v_cmp_nlt_f32_e32 vcc, s96, v33
	v_pk_mul_f32 v[28:29], v[28:29], v[0:1] op_sel_hi:[1,0]
	s_nop 0
	v_cndmask_b32_e32 v31, 0, v31, vcc
	v_cmp_ngt_f32_e32 vcc, s97, v33
	v_pk_mul_f32 v[28:29], v[4:5], v[28:29]
	s_nop 0
	v_cndmask_b32_e32 v31, v246, v31, vcc
	v_pk_add_f32 v[30:31], v[30:31], 1.0 op_sel_hi:[1,0]
	s_nop 0
	v_div_scale_f32 v36, s[4:5], v31, v31, v33
	v_rcp_f32_e32 v37, v36
	s_nop 0
	v_fma_f32 v39, -v36, v37, 1.0
	v_fmac_f32_e32 v37, v39, v37
	v_div_scale_f32 v39, vcc, v33, v31, v33
	v_mul_f32_e32 v62, v39, v37
	v_fma_f32 v64, -v36, v62, v39
	v_fmac_f32_e32 v62, v64, v37
	v_fma_f32 v36, -v36, v62, v39
	v_div_fmas_f32 v36, v36, v37, v62
	v_div_fixup_f32 v31, v36, v31, v33
	v_div_scale_f32 v33, s[4:5], v30, v30, v32
	v_rcp_f32_e32 v36, v33
	s_nop 0
	v_fma_f32 v37, -v33, v36, 1.0
	v_fmac_f32_e32 v36, v37, v36
	v_div_scale_f32 v37, vcc, v32, v30, v32
	v_mul_f32_e32 v39, v37, v36
	v_fma_f32 v62, -v33, v39, v37
	v_fmac_f32_e32 v39, v62, v36
	v_fma_f32 v33, -v33, v39, v37
	v_div_fmas_f32 v33, v33, v36, v39
	v_div_fixup_f32 v30, v33, v30, v32
	v_pk_mul_f32 v[26:27], v[30:31], v[26:27]
	v_and_b32_e32 v32, 0xffff0000, v63
	v_cvt_pk_bf16_f32 v26, v26, v27
	v_lshlrev_b32_e32 v27, 16, v63
	v_mul_f32_e32 v30, 0xbfb8aa3b, v27
	v_fma_f32 v31, v27, s89, -v30
	v_rndne_f32_e32 v33, v30
	v_fmac_f32_e32 v31, 0xb2a5705f, v27
	v_sub_f32_e32 v30, v30, v33
	v_add_f32_e32 v30, v30, v31
	v_exp_f32_e32 v30, v30
	v_cvt_i32_f32_e32 v31, v33
	v_cmp_nlt_f32_e32 vcc, s96, v27
	v_ldexp_f32 v30, v30, v31
	v_mul_f32_e32 v31, 0xbfb8aa3b, v32
	v_fma_f32 v33, v32, s89, -v31
	v_rndne_f32_e32 v36, v31
	v_fmac_f32_e32 v33, 0xb2a5705f, v32
	v_sub_f32_e32 v31, v31, v36
	v_add_f32_e32 v31, v31, v33
	v_exp_f32_e32 v31, v31
	v_cvt_i32_f32_e32 v33, v36
	v_cndmask_b32_e32 v30, 0, v30, vcc
	v_cmp_ngt_f32_e32 vcc, s97, v27
	v_ldexp_f32 v31, v31, v33
; DI unsigned pk2(float lo, float hi) { f32x2 f = {lo, hi}; bf2_t v = __builtin_convertvector(f, bf2_t); return __builtin_bit_cast(unsigned, v); }
; DI void gla_finish_phase(int wv, const float* obuf, const bf16_t* rb, const float* gn, bf16_t* ob) {
;     ...
;         for (int u = 0; u < 2; ++u) { const int row = row0 + u * nw; if (row < M_TOK) {
; #pragma unroll
;             for (int i = 0; i < 4; ++i) {
;                 const f32x4 x = v[u][i];
;                 const float ss = wave_sum((x.x * x.x + x.y * x.y) + (x.z * x.z + x.w * x.w));
;                 const float rn = 1.f / sqrtf(ss * (1.f / 256.f) + 1e-6f);
;                 const u32x2 r_ = rw[u][i];
;                 const float r0 = __uint_as_float(r_.x << 16), r1 = __uint_as_float(r_.x & 0xffff0000u), r2 = __uint_as_float(r_.y << 16), r3 = __uint_as_float(r_.y & 0xffff0000u);
;                 const float s0 = r0 / (1.f + expf(-r0)), s1 = r1 / (1.f + expf(-r1)), s2 = r2 / (1.f + expf(-r2)), s3 = r3 / (1.f + expf(-r3));
;                 u32x2 w; w.x = pk2(x.x * rn * g4.x * s0, x.y * rn * g4.y * s1); w.y = pk2(x.z * rn * g4.z * s2, x.w * rn * g4.w * s3);
;                 ((u32x2*)(ob + (size_t)row * 1024))[lane + 64 * i] = w;
	s_nop 0
	v_cndmask_b32_e32 v30, v246, v30, vcc
	v_cmp_nlt_f32_e32 vcc, s96, v32
	s_nop 1
	v_cndmask_b32_e32 v31, 0, v31, vcc
	v_cmp_ngt_f32_e32 vcc, s97, v32
	s_nop 1
	v_cndmask_b32_e32 v31, v246, v31, vcc
	v_pk_add_f32 v[30:31], v[30:31], 1.0 op_sel_hi:[1,0]
	s_nop 0
	v_div_scale_f32 v33, s[4:5], v31, v31, v32
	v_rcp_f32_e32 v36, v33
	s_nop 0
	v_fma_f32 v37, -v33, v36, 1.0
	v_fmac_f32_e32 v36, v37, v36
	v_div_scale_f32 v37, vcc, v32, v31, v32
	v_mul_f32_e32 v39, v37, v36
	v_fma_f32 v62, -v33, v39, v37
	v_fmac_f32_e32 v39, v62, v36
	v_fma_f32 v33, -v33, v39, v37
	v_div_fmas_f32 v33, v33, v36, v39
	v_div_fixup_f32 v31, v33, v31, v32
	v_div_scale_f32 v32, s[4:5], v30, v30, v27
	v_rcp_f32_e32 v33, v32
	s_nop 0
	v_fma_f32 v36, -v32, v33, 1.0
	v_fmac_f32_e32 v33, v36, v33
	v_div_scale_f32 v36, vcc, v27, v30, v27
	v_mul_f32_e32 v37, v36, v33
	v_fma_f32 v39, -v32, v37, v36
	v_fmac_f32_e32 v37, v39, v33
	v_fma_f32 v32, -v32, v37, v36
	v_div_fmas_f32 v32, v32, v33, v37
	v_div_fixup_f32 v30, v32, v30, v27
	v_pk_mul_f32 v[28:29], v[30:31], v[28:29]
	s_nop 0
	v_cvt_pk_bf16_f32 v27, v28, v29
	global_store_dwordx2 v[34:35], v[26:27], off
	v_pk_mul_f32 v[26:27], v[24:25], v[24:25]
	v_pk_mul_f32 v[28:29], v[22:23], v[22:23]
	s_nop 0
	v_pk_mov_b32 v[30:31], v[28:29], v[26:27] op_sel:[1,0]
	v_mov_b32_e32 v29, v27
	v_pk_add_f32 v[26:27], v[30:31], v[28:29]
	s_nop 0
	v_add_f32_e32 v0, v26, v27
	ds_bpermute_b32 v26, v233, v0
	s_waitcnt lgkmcnt(0)
	v_add_f32_e32 v0, v0, v26
	ds_bpermute_b32 v26, v234, v0
	s_waitcnt lgkmcnt(0)
	v_add_f32_e32 v0, v0, v26
	ds_bpermute_b32 v26, v235, v0
	s_waitcnt lgkmcnt(0)
	v_add_f32_e32 v0, v0, v26
	ds_bpermute_b32 v26, v236, v0
	s_waitcnt lgkmcnt(0)
	v_add_f32_e32 v0, v0, v26
	ds_bpermute_b32 v26, v237, v0
	s_waitcnt lgkmcnt(0)
	v_add_f32_e32 v0, v0, v26
	ds_bpermute_b32 v26, v238, v0
	s_waitcnt lgkmcnt(0)
	v_add_f32_e32 v0, v0, v26
	v_fmamk_f32 v0, v0, 0x3b800000, v241
	v_cmp_gt_f32_e32 vcc, s2, v0
	v_mul_f32_e32 v26, 0x4f800000, v0
	s_nop 0
	v_cndmask_b32_e32 v0, v0, v26, vcc
	v_sqrt_f32_e32 v26, v0
	s_nop 0
	v_add_u32_e32 v27, -1, v26
	v_fma_f32 v28, -v27, v26, v0
	v_cmp_ge_f32_e64 s[4:5], 0, v28
	v_add_u32_e32 v28, 1, v26
	s_nop 0
	v_cndmask_b32_e64 v27, v26, v27, s[4:5]
	v_fma_f32 v26, -v28, v26, v0
	v_cmp_lt_f32_e64 s[4:5], 0, v26
	s_nop 1
	v_cndmask_b32_e64 v26, v27, v28, s[4:5]
	v_mul_f32_e32 v27, 0x37800000, v26
	v_cndmask_b32_e32 v26, v26, v27, vcc
	v_cmp_class_f32_e32 vcc, v0, v242
	s_nop 1
	v_cndmask_b32_e32 v0, v26, v0, vcc
	v_div_scale_f32 v26, s[4:5], v0, v0, 1.0
	v_rcp_f32_e32 v27, v26
	s_nop 0
	v_fma_f32 v28, -v26, v27, 1.0
	v_fmac_f32_e32 v27, v28, v27
	v_div_scale_f32 v28, vcc, 1.0, v0, 1.0
	v_mul_f32_e32 v29, v28, v27
	v_fma_f32 v30, -v26, v29, v28
	v_fmac_f32_e32 v29, v30, v27
	v_fma_f32 v26, -v26, v29, v28
	v_div_fmas_f32 v26, v26, v27, v29
	v_lshlrev_b32_e32 v28, 16, v60
	v_div_fixup_f32 v0, v26, v0, 1.0
	v_mul_f32_e32 v26, 0xbfb8aa3b, v28
	v_fma_f32 v27, v28, s89, -v26
	v_rndne_f32_e32 v30, v26
	v_fmac_f32_e32 v27, 0xb2a5705f, v28
	v_sub_f32_e32 v26, v26, v30
	v_add_f32_e32 v26, v26, v27
	v_exp_f32_e32 v26, v26
	v_cvt_i32_f32_e32 v27, v30
	v_and_b32_e32 v29, 0xffff0000, v60
	v_cmp_nlt_f32_e32 vcc, s96, v28
	v_pk_mul_f32 v[22:23], v[22:23], v[0:1] op_sel_hi:[1,0]
	v_ldexp_f32 v26, v26, v27
	v_mul_f32_e32 v27, 0xbfb8aa3b, v29
	v_fma_f32 v30, v29, s89, -v27
	v_rndne_f32_e32 v31, v27
	v_fmac_f32_e32 v30, 0xb2a5705f, v29
	v_sub_f32_e32 v27, v27, v31
	v_add_f32_e32 v27, v27, v30
	v_exp_f32_e32 v27, v27
	v_cvt_i32_f32_e32 v30, v31
	v_cndmask_b32_e32 v26, 0, v26, vcc
	v_cmp_ngt_f32_e32 vcc, s97, v28
	v_pk_mul_f32 v[22:23], v[2:3], v[22:23]
	v_ldexp_f32 v27, v27, v30
	v_cndmask_b32_e32 v26, v246, v26, vcc
	v_cmp_nlt_f32_e32 vcc, s96, v29
	v_pk_mul_f32 v[24:25], v[24:25], v[0:1] op_sel_hi:[1,0]
	s_nop 0
	v_cndmask_b32_e32 v27, 0, v27, vcc
	v_cmp_ngt_f32_e32 vcc, s97, v29
	v_pk_mul_f32 v[24:25], v[4:5], v[24:25]
	s_nop 0
	v_cndmask_b32_e32 v27, v246, v27, vcc
	v_pk_add_f32 v[26:27], v[26:27], 1.0 op_sel_hi:[1,0]
	s_nop 0
	v_div_scale_f32 v30, s[4:5], v27, v27, v29
	v_rcp_f32_e32 v31, v30
	s_nop 0
	v_fma_f32 v32, -v30, v31, 1.0
	v_fmac_f32_e32 v31, v32, v31
	v_div_scale_f32 v32, vcc, v29, v27, v29
	v_mul_f32_e32 v33, v32, v31
	v_fma_f32 v36, -v30, v33, v32
	v_fmac_f32_e32 v33, v36, v31
	v_fma_f32 v30, -v30, v33, v32
	v_div_fmas_f32 v30, v30, v31, v33
	v_div_fixup_f32 v27, v30, v27, v29
	v_div_scale_f32 v29, s[4:5], v26, v26, v28
	v_rcp_f32_e32 v30, v29
	s_nop 0
	v_fma_f32 v31, -v29, v30, 1.0
	v_fmac_f32_e32 v30, v31, v30
	v_div_scale_f32 v31, vcc, v28, v26, v28
	v_mul_f32_e32 v32, v31, v30
	v_fma_f32 v33, -v29, v32, v31
	v_fmac_f32_e32 v32, v33, v30
	v_fma_f32 v29, -v29, v32, v31
	v_div_fmas_f32 v29, v29, v30, v32
	v_div_fixup_f32 v26, v29, v26, v28
	v_pk_mul_f32 v[22:23], v[26:27], v[22:23]
	v_and_b32_e32 v28, 0xffff0000, v61
	v_cvt_pk_bf16_f32 v22, v22, v23
	v_lshlrev_b32_e32 v23, 16, v61
	v_mul_f32_e32 v26, 0xbfb8aa3b, v23
	v_fma_f32 v27, v23, s89, -v26
	v_rndne_f32_e32 v29, v26
	v_fmac_f32_e32 v27, 0xb2a5705f, v23
	v_sub_f32_e32 v26, v26, v29
	v_add_f32_e32 v26, v26, v27
	v_exp_f32_e32 v26, v26
	v_cvt_i32_f32_e32 v27, v29
	v_cmp_nlt_f32_e32 vcc, s96, v23
	v_ldexp_f32 v26, v26, v27
	v_mul_f32_e32 v27, 0xbfb8aa3b, v28
	v_fma_f32 v29, v28, s89, -v27
	v_rndne_f32_e32 v30, v27
	v_fmac_f32_e32 v29, 0xb2a5705f, v28
	v_sub_f32_e32 v27, v27, v30
	v_add_f32_e32 v27, v27, v29
	v_exp_f32_e32 v27, v27
	v_cvt_i32_f32_e32 v29, v30
	v_cndmask_b32_e32 v26, 0, v26, vcc
	v_cmp_ngt_f32_e32 vcc, s97, v23
	v_ldexp_f32 v27, v27, v29
	s_nop 0
	v_cndmask_b32_e32 v26, v246, v26, vcc
	v_cmp_nlt_f32_e32 vcc, s96, v28
	s_nop 1
	v_cndmask_b32_e32 v27, 0, v27, vcc
	v_cmp_ngt_f32_e32 vcc, s97, v28
	s_nop 1
	v_cndmask_b32_e32 v27, v246, v27, vcc
	v_pk_add_f32 v[26:27], v[26:27], 1.0 op_sel_hi:[1,0]
	s_nop 0
	v_div_scale_f32 v29, s[4:5], v27, v27, v28
	v_rcp_f32_e32 v30, v29
	s_nop 0
	v_fma_f32 v31, -v29, v30, 1.0
	v_fmac_f32_e32 v30, v31, v30
	v_div_scale_f32 v31, vcc, v28, v27, v28
	v_mul_f32_e32 v32, v31, v30
	v_fma_f32 v33, -v29, v32, v31
	v_fmac_f32_e32 v32, v33, v30
	v_fma_f32 v29, -v29, v32, v31
	v_div_fmas_f32 v29, v29, v30, v32
	v_div_fixup_f32 v27, v29, v27, v28
	v_div_scale_f32 v28, s[4:5], v26, v26, v23
	v_rcp_f32_e32 v29, v28
	s_nop 0
	v_fma_f32 v30, -v28, v29, 1.0
	v_fmac_f32_e32 v29, v30, v29
	v_div_scale_f32 v30, vcc, v23, v26, v23
	v_mul_f32_e32 v31, v30, v29
	v_fma_f32 v32, -v28, v31, v30
	v_fmac_f32_e32 v31, v32, v29
	v_fma_f32 v28, -v28, v31, v30
	v_div_fmas_f32 v28, v28, v29, v31
	v_div_fixup_f32 v26, v28, v26, v23
	v_pk_mul_f32 v[24:25], v[26:27], v[24:25]
	s_nop 0
	v_cvt_pk_bf16_f32 v23, v24, v25
	global_store_dwordx2 v[34:35], v[22:23], off offset:512
	s_and_saveexec_b64 s[4:5], s[0:1]
	s_cbranch_execz .LBB0_237
; DI unsigned pk2(float lo, float hi) { f32x2 f = {lo, hi}; bf2_t v = __builtin_convertvector(f, bf2_t); return __builtin_bit_cast(unsigned, v); }
; DI void gla_finish_phase(int wv, const float* obuf, const bf16_t* rb, const float* gn, bf16_t* ob) {
;     ...
;             for (int i = 0; i < 4; ++i) {
;                 const f32x4 x = v[u][i];
;                 const float ss = wave_sum((x.x * x.x + x.y * x.y) + (x.z * x.z + x.w * x.w));
;                 const float rn = 1.f / sqrtf(ss * (1.f / 256.f) + 1e-6f);
;                 const u32x2 r_ = rw[u][i];
;                 const float r0 = __uint_as_float(r_.x << 16), r1 = __uint_as_float(r_.x & 0xffff0000u), r2 = __uint_as_float(r_.y << 16), r3 = __uint_as_float(r_.y & 0xffff0000u);
;                 const float s0 = r0 / (1.f + expf(-r0)), s1 = r1 / (1.f + expf(-r1)), s2 = r2 / (1.f + expf(-r2)), s3 = r3 / (1.f + expf(-r3));
;                 u32x2 w; w.x = pk2(x.x * rn * g4.x * s0, x.y * rn * g4.y * s1); w.y = pk2(x.z * rn * g4.z * s2, x.w * rn * g4.w * s3);
;                 ((u32x2*)(ob + (size_t)row * 1024))[lane + 64 * i] = w;
	v_pk_mul_f32 v[22:23], v[20:21], v[20:21]
	v_pk_mul_f32 v[24:25], v[18:19], v[18:19]
	s_nop 0
	v_pk_mov_b32 v[26:27], v[24:25], v[22:23] op_sel:[1,0]
	v_mov_b32_e32 v25, v23
	v_pk_add_f32 v[22:23], v[26:27], v[24:25]
	s_nop 0
	v_add_f32_e32 v0, v22, v23
	ds_bpermute_b32 v22, v233, v0
	s_waitcnt lgkmcnt(0)
	v_add_f32_e32 v0, v0, v22
	ds_bpermute_b32 v22, v234, v0
	s_waitcnt lgkmcnt(0)
	v_add_f32_e32 v0, v0, v22
	ds_bpermute_b32 v22, v235, v0
	s_waitcnt lgkmcnt(0)
	v_add_f32_e32 v0, v0, v22
	ds_bpermute_b32 v22, v236, v0
	s_waitcnt lgkmcnt(0)
	v_add_f32_e32 v0, v0, v22
	ds_bpermute_b32 v22, v237, v0
	s_waitcnt lgkmcnt(0)
	v_add_f32_e32 v0, v0, v22
	ds_bpermute_b32 v22, v238, v0
	s_waitcnt lgkmcnt(0)
	v_add_f32_e32 v0, v0, v22
	v_fmamk_f32 v0, v0, 0x3b800000, v241
	v_cmp_gt_f32_e32 vcc, s2, v0
	v_mul_f32_e32 v22, 0x4f800000, v0
	s_nop 0
	v_cndmask_b32_e32 v0, v0, v22, vcc
	v_sqrt_f32_e32 v22, v0
	s_nop 0
	v_add_u32_e32 v23, -1, v22
	v_fma_f32 v24, -v23, v22, v0
	v_cmp_ge_f32_e64 s[0:1], 0, v24
	v_add_u32_e32 v24, 1, v22
	s_nop 0
	v_cndmask_b32_e64 v23, v22, v23, s[0:1]
	v_fma_f32 v22, -v24, v22, v0
	v_cmp_lt_f32_e64 s[0:1], 0, v22
	s_nop 1
	v_cndmask_b32_e64 v22, v23, v24, s[0:1]
	v_mul_f32_e32 v23, 0x37800000, v22
	v_cndmask_b32_e32 v22, v22, v23, vcc
	v_cmp_class_f32_e32 vcc, v0, v242
	s_nop 1
	v_cndmask_b32_e32 v0, v22, v0, vcc
	v_div_scale_f32 v22, s[0:1], v0, v0, 1.0
	v_rcp_f32_e32 v23, v22
	s_nop 0
	v_fma_f32 v24, -v22, v23, 1.0
	v_fmac_f32_e32 v23, v24, v23
	v_div_scale_f32 v24, vcc, 1.0, v0, 1.0
	v_mul_f32_e32 v25, v24, v23
	v_fma_f32 v26, -v22, v25, v24
	v_fmac_f32_e32 v25, v26, v23
	v_fma_f32 v22, -v22, v25, v24
	v_div_fmas_f32 v22, v22, v23, v25
	v_lshlrev_b32_e32 v24, 16, v58
	v_div_fixup_f32 v0, v22, v0, 1.0
	v_mul_f32_e32 v22, 0xbfb8aa3b, v24
	v_fma_f32 v23, v24, s89, -v22
	v_rndne_f32_e32 v26, v22
	v_fmac_f32_e32 v23, 0xb2a5705f, v24
	v_sub_f32_e32 v22, v22, v26
	v_add_f32_e32 v22, v22, v23
	v_exp_f32_e32 v22, v22
	v_cvt_i32_f32_e32 v23, v26
	v_and_b32_e32 v25, 0xffff0000, v58
	v_cmp_nlt_f32_e32 vcc, s96, v24
	v_pk_mul_f32 v[18:19], v[18:19], v[0:1] op_sel_hi:[1,0]
	v_ldexp_f32 v22, v22, v23
	v_mul_f32_e32 v23, 0xbfb8aa3b, v25
	v_fma_f32 v26, v25, s89, -v23
	v_rndne_f32_e32 v27, v23
	v_fmac_f32_e32 v26, 0xb2a5705f, v25
	v_sub_f32_e32 v23, v23, v27
	v_add_f32_e32 v23, v23, v26
	v_exp_f32_e32 v23, v23
	v_cvt_i32_f32_e32 v26, v27
	v_cndmask_b32_e32 v22, 0, v22, vcc
	v_cmp_ngt_f32_e32 vcc, s97, v24
	v_pk_mul_f32 v[18:19], v[2:3], v[18:19]
	v_ldexp_f32 v23, v23, v26
	v_cndmask_b32_e32 v22, v246, v22, vcc
	v_cmp_nlt_f32_e32 vcc, s96, v25
	v_pk_mul_f32 v[20:21], v[20:21], v[0:1] op_sel_hi:[1,0]
	s_nop 0
	v_cndmask_b32_e32 v23, 0, v23, vcc
	v_cmp_ngt_f32_e32 vcc, s97, v25
	v_pk_mul_f32 v[20:21], v[4:5], v[20:21]
	s_nop 0
	v_cndmask_b32_e32 v23, v246, v23, vcc
	v_pk_add_f32 v[22:23], v[22:23], 1.0 op_sel_hi:[1,0]
	s_nop 0
	v_div_scale_f32 v26, s[0:1], v23, v23, v25
	v_rcp_f32_e32 v27, v26
	s_nop 0
	v_fma_f32 v28, -v26, v27, 1.0
	v_fmac_f32_e32 v27, v28, v27
	v_div_scale_f32 v28, vcc, v25, v23, v25
	v_mul_f32_e32 v29, v28, v27
	v_fma_f32 v30, -v26, v29, v28
	v_fmac_f32_e32 v29, v30, v27
	v_fma_f32 v26, -v26, v29, v28
	v_div_fmas_f32 v26, v26, v27, v29
	v_div_fixup_f32 v23, v26, v23, v25
	v_div_scale_f32 v25, s[0:1], v22, v22, v24
	v_rcp_f32_e32 v26, v25
	s_nop 0
	v_fma_f32 v27, -v25, v26, 1.0
	v_fmac_f32_e32 v26, v27, v26
	v_div_scale_f32 v27, vcc, v24, v22, v24
	v_mul_f32_e32 v28, v27, v26
	v_fma_f32 v29, -v25, v28, v27
	v_fmac_f32_e32 v28, v29, v26
	v_fma_f32 v25, -v25, v28, v27
	v_div_fmas_f32 v25, v25, v26, v28
	v_div_fixup_f32 v22, v25, v22, v24
	v_pk_mul_f32 v[18:19], v[22:23], v[18:19]
	v_lshlrev_b32_e32 v23, 16, v59
	v_cvt_pk_bf16_f32 v22, v18, v19
	v_mul_f32_e32 v18, 0xbfb8aa3b, v23
	v_fma_f32 v19, v23, s89, -v18
	v_rndne_f32_e32 v25, v18
	v_fmac_f32_e32 v19, 0xb2a5705f, v23
	v_sub_f32_e32 v18, v18, v25
	v_add_f32_e32 v18, v18, v19
	v_exp_f32_e32 v18, v18
	v_cvt_i32_f32_e32 v19, v25
	v_and_b32_e32 v24, 0xffff0000, v59
	v_cmp_nlt_f32_e32 vcc, s96, v23
	v_ldexp_f32 v18, v18, v19
	v_mul_f32_e32 v19, 0xbfb8aa3b, v24
	v_fma_f32 v25, v24, s89, -v19
	v_rndne_f32_e32 v26, v19
	v_fmac_f32_e32 v25, 0xb2a5705f, v24
	v_sub_f32_e32 v19, v19, v26
	v_add_f32_e32 v19, v19, v25
	v_exp_f32_e32 v19, v19
	v_cvt_i32_f32_e32 v25, v26
	v_cndmask_b32_e32 v18, 0, v18, vcc
	v_cmp_ngt_f32_e32 vcc, s97, v23
	v_ldexp_f32 v19, v19, v25
	s_nop 0
	v_cndmask_b32_e32 v18, v246, v18, vcc
	v_cmp_nlt_f32_e32 vcc, s96, v24
	s_nop 1
	v_cndmask_b32_e32 v19, 0, v19, vcc
	v_cmp_ngt_f32_e32 vcc, s97, v24
	s_nop 1
	v_cndmask_b32_e32 v19, v246, v19, vcc
	v_pk_add_f32 v[18:19], v[18:19], 1.0 op_sel_hi:[1,0]
	s_nop 0
	v_div_scale_f32 v25, s[0:1], v19, v19, v24
	v_rcp_f32_e32 v26, v25
	s_nop 0
	v_fma_f32 v27, -v25, v26, 1.0
	v_fmac_f32_e32 v26, v27, v26
	v_div_scale_f32 v27, vcc, v24, v19, v24
	v_mul_f32_e32 v28, v27, v26
	v_fma_f32 v29, -v25, v28, v27
	v_fmac_f32_e32 v28, v29, v26
	v_fma_f32 v25, -v25, v28, v27
	v_div_fmas_f32 v25, v25, v26, v28
	v_div_fixup_f32 v19, v25, v19, v24
	v_div_scale_f32 v24, s[0:1], v18, v18, v23
	v_rcp_f32_e32 v25, v24
	s_nop 0
	v_fma_f32 v26, -v24, v25, 1.0
	v_fmac_f32_e32 v25, v26, v25
	v_div_scale_f32 v26, vcc, v23, v18, v23
	v_mul_f32_e32 v27, v26, v25
	v_fma_f32 v28, -v24, v27, v26
	v_fmac_f32_e32 v27, v28, v25
	v_fma_f32 v24, -v24, v27, v26
	v_div_fmas_f32 v24, v24, v25, v27
	v_div_fixup_f32 v18, v24, v18, v23
	v_pk_mul_f32 v[18:19], v[18:19], v[20:21]
	v_pk_mul_f32 v[20:21], v[16:17], v[16:17]
	v_cvt_pk_bf16_f32 v23, v18, v19
	v_lshl_add_u64 v[18:19], s[48:49], 0, v[44:45]
	global_store_dwordx2 v[18:19], v[22:23], off offset:-1024
	v_pk_mul_f32 v[22:23], v[14:15], v[14:15]
	s_nop 0
	v_pk_mov_b32 v[24:25], v[22:23], v[20:21] op_sel:[1,0]
	v_mov_b32_e32 v23, v21
	v_pk_add_f32 v[20:21], v[24:25], v[22:23]
	s_nop 0
	v_add_f32_e32 v0, v20, v21
	ds_bpermute_b32 v20, v233, v0
	s_waitcnt lgkmcnt(0)
; DI unsigned pk2(float lo, float hi) { f32x2 f = {lo, hi}; bf2_t v = __builtin_convertvector(f, bf2_t); return __builtin_bit_cast(unsigned, v); }
; DI void gla_finish_phase(int wv, const float* obuf, const bf16_t* rb, const float* gn, bf16_t* ob) {
;     ...
;             for (int i = 0; i < 4; ++i) {
;                 const f32x4 x = v[u][i];
;                 const float ss = wave_sum((x.x * x.x + x.y * x.y) + (x.z * x.z + x.w * x.w));
;                 const float rn = 1.f / sqrtf(ss * (1.f / 256.f) + 1e-6f);
;                 const u32x2 r_ = rw[u][i];
;                 const float r0 = __uint_as_float(r_.x << 16), r1 = __uint_as_float(r_.x & 0xffff0000u), r2 = __uint_as_float(r_.y << 16), r3 = __uint_as_float(r_.y & 0xffff0000u);
;                 const float s0 = r0 / (1.f + expf(-r0)), s1 = r1 / (1.f + expf(-r1)), s2 = r2 / (1.f + expf(-r2)), s3 = r3 / (1.f + expf(-r3));
;                 u32x2 w; w.x = pk2(x.x * rn * g4.x * s0, x.y * rn * g4.y * s1); w.y = pk2(x.z * rn * g4.z * s2, x.w * rn * g4.w * s3);
;                 ((u32x2*)(ob + (size_t)row * 1024))[lane + 64 * i] = w;
	v_add_f32_e32 v0, v0, v20
	ds_bpermute_b32 v20, v234, v0
	s_waitcnt lgkmcnt(0)
	v_add_f32_e32 v0, v0, v20
	ds_bpermute_b32 v20, v235, v0
	s_waitcnt lgkmcnt(0)
	v_add_f32_e32 v0, v0, v20
	ds_bpermute_b32 v20, v236, v0
	s_waitcnt lgkmcnt(0)
	v_add_f32_e32 v0, v0, v20
	ds_bpermute_b32 v20, v237, v0
	s_waitcnt lgkmcnt(0)
	v_add_f32_e32 v0, v0, v20
	ds_bpermute_b32 v20, v238, v0
	s_waitcnt lgkmcnt(0)
	v_add_f32_e32 v0, v0, v20
	v_fmamk_f32 v0, v0, 0x3b800000, v241
	v_cmp_gt_f32_e32 vcc, s2, v0
	v_mul_f32_e32 v20, 0x4f800000, v0
	s_nop 0
	v_cndmask_b32_e32 v0, v0, v20, vcc
	v_sqrt_f32_e32 v20, v0
	s_nop 0
	v_add_u32_e32 v21, -1, v20
	v_fma_f32 v22, -v21, v20, v0
	v_cmp_ge_f32_e64 s[0:1], 0, v22
	v_add_u32_e32 v22, 1, v20
	s_nop 0
	v_cndmask_b32_e64 v21, v20, v21, s[0:1]
	v_fma_f32 v20, -v22, v20, v0
	v_cmp_lt_f32_e64 s[0:1], 0, v20
	s_nop 1
	v_cndmask_b32_e64 v20, v21, v22, s[0:1]
	v_mul_f32_e32 v21, 0x37800000, v20
	v_cndmask_b32_e32 v20, v20, v21, vcc
	v_cmp_class_f32_e32 vcc, v0, v242
	s_nop 1
	v_cndmask_b32_e32 v0, v20, v0, vcc
	v_div_scale_f32 v20, s[0:1], v0, v0, 1.0
	v_rcp_f32_e32 v21, v20
	s_nop 0
	v_fma_f32 v22, -v20, v21, 1.0
	v_fmac_f32_e32 v21, v22, v21
	v_div_scale_f32 v22, vcc, 1.0, v0, 1.0
	v_mul_f32_e32 v23, v22, v21
	v_fma_f32 v24, -v20, v23, v22
	v_fmac_f32_e32 v23, v24, v21
	v_fma_f32 v20, -v20, v23, v22
	v_div_fmas_f32 v20, v20, v21, v23
	v_lshlrev_b32_e32 v22, 16, v56
	v_div_fixup_f32 v0, v20, v0, 1.0
	v_mul_f32_e32 v20, 0xbfb8aa3b, v22
	v_fma_f32 v21, v22, s89, -v20
	v_rndne_f32_e32 v24, v20
	v_fmac_f32_e32 v21, 0xb2a5705f, v22
	v_sub_f32_e32 v20, v20, v24
	v_add_f32_e32 v20, v20, v21
	v_exp_f32_e32 v20, v20
	v_cvt_i32_f32_e32 v21, v24
	v_and_b32_e32 v23, 0xffff0000, v56
	v_cmp_nlt_f32_e32 vcc, s96, v22
	v_pk_mul_f32 v[14:15], v[14:15], v[0:1] op_sel_hi:[1,0]
	v_ldexp_f32 v20, v20, v21
	v_mul_f32_e32 v21, 0xbfb8aa3b, v23
	v_fma_f32 v24, v23, s89, -v21
	v_rndne_f32_e32 v25, v21
	v_fmac_f32_e32 v24, 0xb2a5705f, v23
	v_sub_f32_e32 v21, v21, v25
	v_add_f32_e32 v21, v21, v24
	v_exp_f32_e32 v21, v21
	v_cvt_i32_f32_e32 v24, v25
	v_cndmask_b32_e32 v20, 0, v20, vcc
	v_cmp_ngt_f32_e32 vcc, s97, v22
	v_pk_mul_f32 v[14:15], v[2:3], v[14:15]
	v_ldexp_f32 v21, v21, v24
	v_cndmask_b32_e32 v20, v246, v20, vcc
	v_cmp_nlt_f32_e32 vcc, s96, v23
	v_pk_mul_f32 v[16:17], v[16:17], v[0:1] op_sel_hi:[1,0]
	s_nop 0
	v_cndmask_b32_e32 v21, 0, v21, vcc
	v_cmp_ngt_f32_e32 vcc, s97, v23
	v_pk_mul_f32 v[16:17], v[4:5], v[16:17]
	s_nop 0
	v_cndmask_b32_e32 v21, v246, v21, vcc
	v_pk_add_f32 v[20:21], v[20:21], 1.0 op_sel_hi:[1,0]
	s_nop 0
	v_div_scale_f32 v24, s[0:1], v21, v21, v23
	v_rcp_f32_e32 v25, v24
	s_nop 0
	v_fma_f32 v26, -v24, v25, 1.0
	v_fmac_f32_e32 v25, v26, v25
	v_div_scale_f32 v26, vcc, v23, v21, v23
	v_mul_f32_e32 v27, v26, v25
	v_fma_f32 v28, -v24, v27, v26
	v_fmac_f32_e32 v27, v28, v25
	v_fma_f32 v24, -v24, v27, v26
	v_div_fmas_f32 v24, v24, v25, v27
	v_div_fixup_f32 v21, v24, v21, v23
	v_div_scale_f32 v23, s[0:1], v20, v20, v22
	v_rcp_f32_e32 v24, v23
	s_nop 0
	v_fma_f32 v25, -v23, v24, 1.0
	v_fmac_f32_e32 v24, v25, v24
	v_div_scale_f32 v25, vcc, v22, v20, v22
	v_mul_f32_e32 v26, v25, v24
	v_fma_f32 v27, -v23, v26, v25
	v_fmac_f32_e32 v26, v27, v24
	v_fma_f32 v23, -v23, v26, v25
	v_div_fmas_f32 v23, v23, v24, v26
	v_div_fixup_f32 v20, v23, v20, v22
	v_pk_mul_f32 v[14:15], v[20:21], v[14:15]
	v_and_b32_e32 v22, 0xffff0000, v57
	v_cvt_pk_bf16_f32 v14, v14, v15
	v_lshlrev_b32_e32 v15, 16, v57
	v_mul_f32_e32 v20, 0xbfb8aa3b, v15
	v_fma_f32 v21, v15, s89, -v20
	v_rndne_f32_e32 v23, v20
	v_fmac_f32_e32 v21, 0xb2a5705f, v15
	v_sub_f32_e32 v20, v20, v23
	v_add_f32_e32 v20, v20, v21
	v_exp_f32_e32 v20, v20
	v_cvt_i32_f32_e32 v21, v23
	v_cmp_nlt_f32_e32 vcc, s96, v15
	v_ldexp_f32 v20, v20, v21
	v_mul_f32_e32 v21, 0xbfb8aa3b, v22
	v_fma_f32 v23, v22, s89, -v21
	v_rndne_f32_e32 v24, v21
	v_fmac_f32_e32 v23, 0xb2a5705f, v22
	v_sub_f32_e32 v21, v21, v24
	v_add_f32_e32 v21, v21, v23
	v_exp_f32_e32 v21, v21
	v_cvt_i32_f32_e32 v23, v24
	v_cndmask_b32_e32 v20, 0, v20, vcc
	v_cmp_ngt_f32_e32 vcc, s97, v15
	v_ldexp_f32 v21, v21, v23
	s_nop 0
	v_cndmask_b32_e32 v20, v246, v20, vcc
	v_cmp_nlt_f32_e32 vcc, s96, v22
	s_nop 1
	v_cndmask_b32_e32 v21, 0, v21, vcc
	v_cmp_ngt_f32_e32 vcc, s97, v22
	s_nop 1
	v_cndmask_b32_e32 v21, v246, v21, vcc
	v_pk_add_f32 v[20:21], v[20:21], 1.0 op_sel_hi:[1,0]
	s_nop 0
	v_div_scale_f32 v23, s[0:1], v21, v21, v22
	v_rcp_f32_e32 v24, v23
	s_nop 0
	v_fma_f32 v25, -v23, v24, 1.0
	v_fmac_f32_e32 v24, v25, v24
	v_div_scale_f32 v25, vcc, v22, v21, v22
	v_mul_f32_e32 v26, v25, v24
	v_fma_f32 v27, -v23, v26, v25
	v_fmac_f32_e32 v26, v27, v24
	v_fma_f32 v23, -v23, v26, v25
	v_div_fmas_f32 v23, v23, v24, v26
	v_div_fixup_f32 v21, v23, v21, v22
	v_div_scale_f32 v22, s[0:1], v20, v20, v15
	v_rcp_f32_e32 v23, v22
	s_nop 0
	v_fma_f32 v24, -v22, v23, 1.0
	v_fmac_f32_e32 v23, v24, v23
	v_div_scale_f32 v24, vcc, v15, v20, v15
	v_mul_f32_e32 v25, v24, v23
	v_fma_f32 v26, -v22, v25, v24
	v_fmac_f32_e32 v25, v26, v23
	v_fma_f32 v22, -v22, v25, v24
	v_div_fmas_f32 v22, v22, v23, v25
	v_div_fixup_f32 v20, v22, v20, v15
	v_pk_mul_f32 v[16:17], v[20:21], v[16:17]
	s_nop 0
	v_cvt_pk_bf16_f32 v15, v16, v17
	global_store_dwordx2 v[18:19], v[14:15], off offset:-512
	v_pk_mul_f32 v[14:15], v[12:13], v[12:13]
	v_pk_mul_f32 v[16:17], v[10:11], v[10:11]
	s_nop 0
	v_pk_mov_b32 v[20:21], v[16:17], v[14:15] op_sel:[1,0]
	v_mov_b32_e32 v17, v15
	v_pk_add_f32 v[14:15], v[20:21], v[16:17]
	s_nop 0
	v_add_f32_e32 v0, v14, v15
	ds_bpermute_b32 v14, v233, v0
	s_waitcnt lgkmcnt(0)
	v_add_f32_e32 v0, v0, v14
	ds_bpermute_b32 v14, v234, v0
	s_waitcnt lgkmcnt(0)
; DI unsigned pk2(float lo, float hi) { f32x2 f = {lo, hi}; bf2_t v = __builtin_convertvector(f, bf2_t); return __builtin_bit_cast(unsigned, v); }
; DI void gla_finish_phase(int wv, const float* obuf, const bf16_t* rb, const float* gn, bf16_t* ob) {
;     ...
;             for (int i = 0; i < 4; ++i) {
;                 const f32x4 x = v[u][i];
;                 const float ss = wave_sum((x.x * x.x + x.y * x.y) + (x.z * x.z + x.w * x.w));
;                 const float rn = 1.f / sqrtf(ss * (1.f / 256.f) + 1e-6f);
;                 const u32x2 r_ = rw[u][i];
;                 const float r0 = __uint_as_float(r_.x << 16), r1 = __uint_as_float(r_.x & 0xffff0000u), r2 = __uint_as_float(r_.y << 16), r3 = __uint_as_float(r_.y & 0xffff0000u);
;                 const float s0 = r0 / (1.f + expf(-r0)), s1 = r1 / (1.f + expf(-r1)), s2 = r2 / (1.f + expf(-r2)), s3 = r3 / (1.f + expf(-r3));
;                 u32x2 w; w.x = pk2(x.x * rn * g4.x * s0, x.y * rn * g4.y * s1); w.y = pk2(x.z * rn * g4.z * s2, x.w * rn * g4.w * s3);
;                 ((u32x2*)(ob + (size_t)row * 1024))[lane + 64 * i] = w;
	v_add_f32_e32 v0, v0, v14
	ds_bpermute_b32 v14, v235, v0
	s_waitcnt lgkmcnt(0)
	v_add_f32_e32 v0, v0, v14
	ds_bpermute_b32 v14, v236, v0
	s_waitcnt lgkmcnt(0)
	v_add_f32_e32 v0, v0, v14
	ds_bpermute_b32 v14, v237, v0
	s_waitcnt lgkmcnt(0)
	v_add_f32_e32 v0, v0, v14
	ds_bpermute_b32 v14, v238, v0
	s_waitcnt lgkmcnt(0)
	v_add_f32_e32 v0, v0, v14
	v_fmamk_f32 v0, v0, 0x3b800000, v241
	v_cmp_gt_f32_e32 vcc, s2, v0
	v_mul_f32_e32 v14, 0x4f800000, v0
	s_nop 0
	v_cndmask_b32_e32 v0, v0, v14, vcc
	v_sqrt_f32_e32 v14, v0
	s_nop 0
	v_add_u32_e32 v15, -1, v14
	v_fma_f32 v16, -v15, v14, v0
	v_cmp_ge_f32_e64 s[0:1], 0, v16
	v_add_u32_e32 v16, 1, v14
	s_nop 0
	v_cndmask_b32_e64 v15, v14, v15, s[0:1]
	v_fma_f32 v14, -v16, v14, v0
	v_cmp_lt_f32_e64 s[0:1], 0, v14
	s_nop 1
	v_cndmask_b32_e64 v14, v15, v16, s[0:1]
	v_mul_f32_e32 v15, 0x37800000, v14
	v_cndmask_b32_e32 v14, v14, v15, vcc
	v_cmp_class_f32_e32 vcc, v0, v242
	s_nop 1
	v_cndmask_b32_e32 v0, v14, v0, vcc
	v_div_scale_f32 v14, s[0:1], v0, v0, 1.0
	v_rcp_f32_e32 v15, v14
	s_nop 0
	v_fma_f32 v16, -v14, v15, 1.0
	v_fmac_f32_e32 v15, v16, v15
	v_div_scale_f32 v16, vcc, 1.0, v0, 1.0
	v_mul_f32_e32 v17, v16, v15
	v_fma_f32 v20, -v14, v17, v16
	v_fmac_f32_e32 v17, v20, v15
	v_fma_f32 v14, -v14, v17, v16
	v_div_fmas_f32 v14, v14, v15, v17
	v_lshlrev_b32_e32 v16, 16, v54
	v_div_fixup_f32 v0, v14, v0, 1.0
	v_mul_f32_e32 v14, 0xbfb8aa3b, v16
	v_fma_f32 v15, v16, s89, -v14
	v_rndne_f32_e32 v20, v14
	v_fmac_f32_e32 v15, 0xb2a5705f, v16
	v_sub_f32_e32 v14, v14, v20
	v_add_f32_e32 v14, v14, v15
	v_exp_f32_e32 v14, v14
	v_cvt_i32_f32_e32 v15, v20
	v_and_b32_e32 v17, 0xffff0000, v54
	v_cmp_nlt_f32_e32 vcc, s96, v16
	v_pk_mul_f32 v[10:11], v[10:11], v[0:1] op_sel_hi:[1,0]
	v_ldexp_f32 v14, v14, v15
	v_mul_f32_e32 v15, 0xbfb8aa3b, v17
	v_fma_f32 v20, v17, s89, -v15
	v_rndne_f32_e32 v21, v15
	v_fmac_f32_e32 v20, 0xb2a5705f, v17
	v_sub_f32_e32 v15, v15, v21
	v_add_f32_e32 v15, v15, v20
	v_exp_f32_e32 v15, v15
	v_cvt_i32_f32_e32 v20, v21
	v_cndmask_b32_e32 v14, 0, v14, vcc
	v_cmp_ngt_f32_e32 vcc, s97, v16
	v_pk_mul_f32 v[10:11], v[2:3], v[10:11]
	v_ldexp_f32 v15, v15, v20
	v_cndmask_b32_e32 v14, v246, v14, vcc
	v_cmp_nlt_f32_e32 vcc, s96, v17
	v_pk_mul_f32 v[12:13], v[12:13], v[0:1] op_sel_hi:[1,0]
	s_nop 0
	v_cndmask_b32_e32 v15, 0, v15, vcc
	v_cmp_ngt_f32_e32 vcc, s97, v17
	v_pk_mul_f32 v[12:13], v[4:5], v[12:13]
	s_nop 0
	v_cndmask_b32_e32 v15, v246, v15, vcc
	v_pk_add_f32 v[14:15], v[14:15], 1.0 op_sel_hi:[1,0]
	s_nop 0
	v_div_scale_f32 v20, s[0:1], v15, v15, v17
	v_rcp_f32_e32 v21, v20
	s_nop 0
	v_fma_f32 v22, -v20, v21, 1.0
	v_fmac_f32_e32 v21, v22, v21
	v_div_scale_f32 v22, vcc, v17, v15, v17
	v_mul_f32_e32 v23, v22, v21
	v_fma_f32 v24, -v20, v23, v22
	v_fmac_f32_e32 v23, v24, v21
	v_fma_f32 v20, -v20, v23, v22
	v_div_fmas_f32 v20, v20, v21, v23
	v_div_fixup_f32 v15, v20, v15, v17
	v_div_scale_f32 v17, s[0:1], v14, v14, v16
	v_rcp_f32_e32 v20, v17
	s_nop 0
	v_fma_f32 v21, -v17, v20, 1.0
	v_fmac_f32_e32 v20, v21, v20
	v_div_scale_f32 v21, vcc, v16, v14, v16
	v_mul_f32_e32 v22, v21, v20
	v_fma_f32 v23, -v17, v22, v21
	v_fmac_f32_e32 v22, v23, v20
	v_fma_f32 v17, -v17, v22, v21
	v_div_fmas_f32 v17, v17, v20, v22
	v_div_fixup_f32 v14, v17, v14, v16
	v_pk_mul_f32 v[10:11], v[14:15], v[10:11]
	v_and_b32_e32 v16, 0xffff0000, v55
	v_cvt_pk_bf16_f32 v10, v10, v11
	v_lshlrev_b32_e32 v11, 16, v55
	v_mul_f32_e32 v14, 0xbfb8aa3b, v11
	v_fma_f32 v15, v11, s89, -v14
	v_rndne_f32_e32 v17, v14
	v_fmac_f32_e32 v15, 0xb2a5705f, v11
	v_sub_f32_e32 v14, v14, v17
	v_add_f32_e32 v14, v14, v15
	v_exp_f32_e32 v14, v14
	v_cvt_i32_f32_e32 v15, v17
	v_cmp_nlt_f32_e32 vcc, s96, v11
	v_ldexp_f32 v14, v14, v15
	v_mul_f32_e32 v15, 0xbfb8aa3b, v16
	v_fma_f32 v17, v16, s89, -v15
	v_rndne_f32_e32 v20, v15
	v_fmac_f32_e32 v17, 0xb2a5705f, v16
	v_sub_f32_e32 v15, v15, v20
	v_add_f32_e32 v15, v15, v17
	v_exp_f32_e32 v15, v15
	v_cvt_i32_f32_e32 v17, v20
	v_cndmask_b32_e32 v14, 0, v14, vcc
	v_cmp_ngt_f32_e32 vcc, s97, v11
	v_ldexp_f32 v15, v15, v17
	s_nop 0
	v_cndmask_b32_e32 v14, v246, v14, vcc
	v_cmp_nlt_f32_e32 vcc, s96, v16
	s_nop 1
	v_cndmask_b32_e32 v15, 0, v15, vcc
	v_cmp_ngt_f32_e32 vcc, s97, v16
	s_nop 1
	v_cndmask_b32_e32 v15, v246, v15, vcc
	v_pk_add_f32 v[14:15], v[14:15], 1.0 op_sel_hi:[1,0]
	s_nop 0
	v_div_scale_f32 v17, s[0:1], v15, v15, v16
	v_rcp_f32_e32 v20, v17
	s_nop 0
	v_fma_f32 v21, -v17, v20, 1.0
	v_fmac_f32_e32 v20, v21, v20
	v_div_scale_f32 v21, vcc, v16, v15, v16
	v_mul_f32_e32 v22, v21, v20
	v_fma_f32 v23, -v17, v22, v21
	v_fmac_f32_e32 v22, v23, v20
	v_fma_f32 v17, -v17, v22, v21
	v_div_fmas_f32 v17, v17, v20, v22
	v_div_fixup_f32 v15, v17, v15, v16
	v_div_scale_f32 v16, s[0:1], v14, v14, v11
	v_rcp_f32_e32 v17, v16
	s_nop 0
	v_fma_f32 v20, -v16, v17, 1.0
	v_fmac_f32_e32 v17, v20, v17
	v_div_scale_f32 v20, vcc, v11, v14, v11
	v_mul_f32_e32 v21, v20, v17
	v_fma_f32 v22, -v16, v21, v20
	v_fmac_f32_e32 v21, v22, v17
	v_fma_f32 v16, -v16, v21, v20
	v_div_fmas_f32 v16, v16, v17, v21
	v_div_fixup_f32 v14, v16, v14, v11
	v_pk_mul_f32 v[12:13], v[14:15], v[12:13]
	s_nop 0
	v_cvt_pk_bf16_f32 v11, v12, v13
	global_store_dwordx2 v[18:19], v[10:11], off
	v_pk_mul_f32 v[10:11], v[8:9], v[8:9]
	v_pk_mul_f32 v[12:13], v[6:7], v[6:7]
	s_nop 0
	v_pk_mov_b32 v[14:15], v[12:13], v[10:11] op_sel:[1,0]
	v_mov_b32_e32 v13, v11
	v_pk_add_f32 v[10:11], v[14:15], v[12:13]
	s_nop 0
	v_add_f32_e32 v0, v10, v11
	ds_bpermute_b32 v10, v233, v0
	s_waitcnt lgkmcnt(0)
; DI unsigned pk2(float lo, float hi) { f32x2 f = {lo, hi}; bf2_t v = __builtin_convertvector(f, bf2_t); return __builtin_bit_cast(unsigned, v); }
; DI void gla_finish_phase(int wv, const float* obuf, const bf16_t* rb, const float* gn, bf16_t* ob) {
;     ...
;             for (int i = 0; i < 4; ++i) {
;                 const f32x4 x = v[u][i];
;                 const float ss = wave_sum((x.x * x.x + x.y * x.y) + (x.z * x.z + x.w * x.w));
;                 const float rn = 1.f / sqrtf(ss * (1.f / 256.f) + 1e-6f);
;                 const u32x2 r_ = rw[u][i];
;                 const float r0 = __uint_as_float(r_.x << 16), r1 = __uint_as_float(r_.x & 0xffff0000u), r2 = __uint_as_float(r_.y << 16), r3 = __uint_as_float(r_.y & 0xffff0000u);
;                 const float s0 = r0 / (1.f + expf(-r0)), s1 = r1 / (1.f + expf(-r1)), s2 = r2 / (1.f + expf(-r2)), s3 = r3 / (1.f + expf(-r3));
;                 u32x2 w; w.x = pk2(x.x * rn * g4.x * s0, x.y * rn * g4.y * s1); w.y = pk2(x.z * rn * g4.z * s2, x.w * rn * g4.w * s3);
;                 ((u32x2*)(ob + (size_t)row * 1024))[lane + 64 * i] = w;
	v_add_f32_e32 v0, v0, v10
	ds_bpermute_b32 v10, v234, v0
	s_waitcnt lgkmcnt(0)
	v_add_f32_e32 v0, v0, v10
	ds_bpermute_b32 v10, v235, v0
	s_waitcnt lgkmcnt(0)
	v_add_f32_e32 v0, v0, v10
	ds_bpermute_b32 v10, v236, v0
	s_waitcnt lgkmcnt(0)
	v_add_f32_e32 v0, v0, v10
	ds_bpermute_b32 v10, v237, v0
	s_waitcnt lgkmcnt(0)
	v_add_f32_e32 v0, v0, v10
	ds_bpermute_b32 v10, v238, v0
	s_waitcnt lgkmcnt(0)
	v_add_f32_e32 v0, v0, v10
	v_fmamk_f32 v0, v0, 0x3b800000, v241
	v_cmp_gt_f32_e32 vcc, s2, v0
	v_mul_f32_e32 v10, 0x4f800000, v0
	s_nop 0
	v_cndmask_b32_e32 v0, v0, v10, vcc
	v_sqrt_f32_e32 v10, v0
	s_nop 0
	v_add_u32_e32 v11, -1, v10
	v_fma_f32 v12, -v11, v10, v0
	v_cmp_ge_f32_e64 s[0:1], 0, v12
	v_add_u32_e32 v12, 1, v10
	s_nop 0
	v_cndmask_b32_e64 v11, v10, v11, s[0:1]
	v_fma_f32 v10, -v12, v10, v0
	v_cmp_lt_f32_e64 s[0:1], 0, v10
	s_nop 1
	v_cndmask_b32_e64 v10, v11, v12, s[0:1]
	v_mul_f32_e32 v11, 0x37800000, v10
	v_cndmask_b32_e32 v10, v10, v11, vcc
	v_cmp_class_f32_e32 vcc, v0, v242
	s_nop 1
	v_cndmask_b32_e32 v0, v10, v0, vcc
	v_div_scale_f32 v10, s[0:1], v0, v0, 1.0
	v_rcp_f32_e32 v11, v10
	s_nop 0
	v_fma_f32 v12, -v10, v11, 1.0
	v_fmac_f32_e32 v11, v12, v11
	v_div_scale_f32 v12, vcc, 1.0, v0, 1.0
	v_mul_f32_e32 v13, v12, v11
	v_fma_f32 v14, -v10, v13, v12
	v_fmac_f32_e32 v13, v14, v11
	v_fma_f32 v10, -v10, v13, v12
	v_div_fmas_f32 v10, v10, v11, v13
	v_lshlrev_b32_e32 v12, 16, v52
	v_div_fixup_f32 v0, v10, v0, 1.0
	v_mul_f32_e32 v10, 0xbfb8aa3b, v12
	v_fma_f32 v11, v12, s89, -v10
	v_rndne_f32_e32 v14, v10
	v_fmac_f32_e32 v11, 0xb2a5705f, v12
	v_sub_f32_e32 v10, v10, v14
	v_add_f32_e32 v10, v10, v11
	v_exp_f32_e32 v10, v10
	v_cvt_i32_f32_e32 v11, v14
	v_and_b32_e32 v13, 0xffff0000, v52
	v_cmp_nlt_f32_e32 vcc, s96, v12
	v_pk_mul_f32 v[6:7], v[6:7], v[0:1] op_sel_hi:[1,0]
	v_ldexp_f32 v10, v10, v11
	v_mul_f32_e32 v11, 0xbfb8aa3b, v13
	v_fma_f32 v14, v13, s89, -v11
	v_rndne_f32_e32 v15, v11
	v_fmac_f32_e32 v14, 0xb2a5705f, v13
	v_sub_f32_e32 v11, v11, v15
	v_add_f32_e32 v11, v11, v14
	v_exp_f32_e32 v11, v11
	v_cvt_i32_f32_e32 v14, v15
	v_cndmask_b32_e32 v10, 0, v10, vcc
	v_cmp_ngt_f32_e32 vcc, s97, v12
	v_pk_mul_f32 v[6:7], v[2:3], v[6:7]
	v_ldexp_f32 v11, v11, v14
	v_cndmask_b32_e32 v10, v246, v10, vcc
	v_cmp_nlt_f32_e32 vcc, s96, v13
	v_pk_mul_f32 v[8:9], v[8:9], v[0:1] op_sel_hi:[1,0]
	s_nop 0
	v_cndmask_b32_e32 v11, 0, v11, vcc
	v_cmp_ngt_f32_e32 vcc, s97, v13
	v_pk_mul_f32 v[8:9], v[4:5], v[8:9]
	s_nop 0
	v_cndmask_b32_e32 v11, v246, v11, vcc
	v_pk_add_f32 v[10:11], v[10:11], 1.0 op_sel_hi:[1,0]
	s_nop 0
	v_div_scale_f32 v14, s[0:1], v11, v11, v13
	v_rcp_f32_e32 v15, v14
	s_nop 0
	v_fma_f32 v16, -v14, v15, 1.0
	v_fmac_f32_e32 v15, v16, v15
	v_div_scale_f32 v16, vcc, v13, v11, v13
	v_mul_f32_e32 v17, v16, v15
	v_fma_f32 v20, -v14, v17, v16
	v_fmac_f32_e32 v17, v20, v15
	v_fma_f32 v14, -v14, v17, v16
	v_div_fmas_f32 v14, v14, v15, v17
	v_div_fixup_f32 v11, v14, v11, v13
	v_div_scale_f32 v13, s[0:1], v10, v10, v12
	v_rcp_f32_e32 v14, v13
	s_nop 0
	v_fma_f32 v15, -v13, v14, 1.0
	v_fmac_f32_e32 v14, v15, v14
	v_div_scale_f32 v15, vcc, v12, v10, v12
	v_mul_f32_e32 v16, v15, v14
	v_fma_f32 v17, -v13, v16, v15
	v_fmac_f32_e32 v16, v17, v14
	v_fma_f32 v13, -v13, v16, v15
	v_div_fmas_f32 v13, v13, v14, v16
	v_div_fixup_f32 v10, v13, v10, v12
	v_pk_mul_f32 v[6:7], v[10:11], v[6:7]
	v_and_b32_e32 v12, 0xffff0000, v53
	v_cvt_pk_bf16_f32 v6, v6, v7
	v_lshlrev_b32_e32 v7, 16, v53
	v_mul_f32_e32 v10, 0xbfb8aa3b, v7
	v_fma_f32 v11, v7, s89, -v10
	v_rndne_f32_e32 v13, v10
	v_fmac_f32_e32 v11, 0xb2a5705f, v7
	v_sub_f32_e32 v10, v10, v13
	v_add_f32_e32 v10, v10, v11
	v_exp_f32_e32 v10, v10
	v_cvt_i32_f32_e32 v11, v13
	v_cmp_nlt_f32_e32 vcc, s96, v7
	v_ldexp_f32 v10, v10, v11
	v_mul_f32_e32 v11, 0xbfb8aa3b, v12
	v_fma_f32 v13, v12, s89, -v11
	v_rndne_f32_e32 v14, v11
	v_fmac_f32_e32 v13, 0xb2a5705f, v12
	v_sub_f32_e32 v11, v11, v14
	v_add_f32_e32 v11, v11, v13
	v_exp_f32_e32 v11, v11
	v_cvt_i32_f32_e32 v13, v14
	v_cndmask_b32_e32 v10, 0, v10, vcc
	v_cmp_ngt_f32_e32 vcc, s97, v7
	v_ldexp_f32 v11, v11, v13
	s_nop 0
	v_cndmask_b32_e32 v10, v246, v10, vcc
	v_cmp_nlt_f32_e32 vcc, s96, v12
	s_nop 1
	v_cndmask_b32_e32 v11, 0, v11, vcc
	v_cmp_ngt_f32_e32 vcc, s97, v12
	s_nop 1
	v_cndmask_b32_e32 v11, v246, v11, vcc
	v_pk_add_f32 v[10:11], v[10:11], 1.0 op_sel_hi:[1,0]
	s_nop 0
	v_div_scale_f32 v13, s[0:1], v11, v11, v12
	v_rcp_f32_e32 v14, v13
	s_nop 0
	v_fma_f32 v15, -v13, v14, 1.0
	v_fmac_f32_e32 v14, v15, v14
	v_div_scale_f32 v15, vcc, v12, v11, v12
	v_mul_f32_e32 v16, v15, v14
	v_fma_f32 v17, -v13, v16, v15
	v_fmac_f32_e32 v16, v17, v14
	v_fma_f32 v13, -v13, v16, v15
	v_div_fmas_f32 v13, v13, v14, v16
	v_div_fixup_f32 v11, v13, v11, v12
	v_div_scale_f32 v12, s[0:1], v10, v10, v7
	v_rcp_f32_e32 v13, v12
	s_nop 0
	v_fma_f32 v14, -v12, v13, 1.0
	v_fmac_f32_e32 v13, v14, v13
	v_div_scale_f32 v14, vcc, v7, v10, v7
	v_mul_f32_e32 v15, v14, v13
	v_fma_f32 v16, -v12, v15, v14
	v_fmac_f32_e32 v15, v16, v13
	v_fma_f32 v12, -v12, v15, v14
	v_div_fmas_f32 v12, v12, v13, v15
	v_div_fixup_f32 v10, v12, v10, v7
	v_pk_mul_f32 v[8:9], v[10:11], v[8:9]
	s_nop 0
	v_cvt_pk_bf16_f32 v7, v8, v9
	global_store_dwordx2 v[18:19], v[6:7], off offset:512
	s_branch .LBB0_237

; DI void ln_phase(int wv, const bf16_t* y, float* xo, const float* g, const float* bta, bf16_t* xb) {
;     ...
;     for (int row0 = bid * 8 + wid; row0 < M_TOK; row0 += R * nw) {
;         u32x4 raw[R][2], rsd[R][2];
; #pragma unroll
;         for (int r = 0; r < R; ++r) { const int row = (row0 + r * nw < M_TOK) ? row0 + r * nw : row0;
; #pragma unroll
;             for (int j = 0; j < 2; ++j) { raw[r][j] = *(const u32x4*)(y + (size_t)row * DM + j * 512 + lane * 8); rsd[r][j] = *(const u32x4*)(xb + (size_t)row * DM + j * 512 + lane * 8); } }
; #pragma unroll
;         for (int r = 0; r < R; ++r) {
;             const int row = row0 + r * nw;
;             if (row < M_TOK) {
;                 f32x4 v[4];
; #pragma unroll
;                 for (int j = 0; j < 2; ++j) { const u32x4 q = raw[r][j], x_ = rsd[r][j];
;                     v[2 * j] = (f32x4){__uint_as_float(q.x << 16), __uint_as_float(q.x & 0xffff0000u), __uint_as_float(q.y << 16), __uint_as_float(q.y & 0xffff0000u)}
;                              + (f32x4){__uint_as_float(x_.x << 16), __uint_as_float(x_.x & 0xffff0000u), __uint_as_float(x_.y << 16), __uint_as_float(x_.y & 0xffff0000u)} * ALPHA_RES;
;                     v[2 * j + 1] = (f32x4){__uint_as_float(q.z << 16), __uint_as_float(q.z & 0xffff0000u), __uint_as_float(q.w << 16), __uint_as_float(q.w & 0xffff0000u)}
;                                  + (f32x4){__uint_as_float(x_.z << 16), __uint_as_float(x_.z & 0xffff0000u), __uint_as_float(x_.w << 16), __uint_as_float(x_.w & 0xffff0000u)} * ALPHA_RES; }
;                 float s_ = 0.f;
; #pragma unroll
;                 for (int j = 0; j < 4; ++j) s_ += (v[j].x + v[j].y) + (v[j].z + v[j].w);
;                 const float mean = wave_sum(s_) * (1.f / DM); float s2 = 0.f;
.LBB0_586:
	v_ashrrev_i32_e32 v83, 31, v82
	s_waitcnt vmcnt(0)
	v_lshlrev_b64 v[38:39], 11, v[82:83]
	v_lshl_add_u64 v[42:43], v[90:91], 0, v[38:39]
	global_load_dwordx4 v[34:37], v[42:43], off nt
	s_nop 0
	v_lshl_add_u64 v[102:103], v[92:93], 0, v[38:39]
	global_load_dwordx4 v[38:41], v[102:103], off nt
	s_nop 0
	global_load_dwordx4 v[42:45], v[42:43], off offset:1024 nt
	s_nop 0
	global_load_dwordx4 v[46:49], v[102:103], off offset:1024 nt
	s_mul_i32 s0, s46, 24
	v_add_u32_e32 v98, s0, v82
	v_cmp_gt_i32_e64 s[8:9], s71, v98
	v_add_u32_e32 v96, s47, v82
	v_add_u32_e32 v100, s36, v82
	v_cmp_gt_i32_e64 s[6:7], s71, v96
	v_cmp_gt_i32_e64 s[4:5], s71, v100
	s_nop 1
	v_cndmask_b32_e64 v148, v82, v96, s[6:7]
	v_cndmask_b32_e64 v150, v82, v100, s[4:5]
	v_cndmask_b32_e64 v152, v82, v98, s[8:9]
	v_ashrrev_i32_e32 v149, 31, v148
	v_ashrrev_i32_e32 v151, 31, v150
	v_ashrrev_i32_e32 v153, 31, v152
	v_lshlrev_b64 v[148:149], 11, v[148:149]
	v_lshlrev_b64 v[150:151], 11, v[150:151]
	v_lshlrev_b64 v[152:153], 11, v[152:153]
	v_lshl_add_u64 v[154:155], v[90:91], 0, v[148:149]
	v_lshl_add_u64 v[148:149], v[92:93], 0, v[148:149]
	v_lshl_add_u64 v[156:157], v[90:91], 0, v[150:151]
	v_lshl_add_u64 v[150:151], v[92:93], 0, v[150:151]
	v_lshl_add_u64 v[158:159], v[90:91], 0, v[152:153]
	v_lshl_add_u64 v[152:153], v[92:93], 0, v[152:153]
	global_load_dwordx4 v[176:179], v[154:155], off nt
	global_load_dwordx4 v[180:183], v[154:155], off offset:1024 nt
	global_load_dwordx4 v[184:187], v[148:149], off nt
	global_load_dwordx4 v[188:191], v[148:149], off offset:1024 nt
	global_load_dwordx4 v[192:195], v[156:157], off nt
	global_load_dwordx4 v[196:199], v[156:157], off offset:1024 nt
	global_load_dwordx4 v[200:203], v[150:151], off nt
	global_load_dwordx4 v[204:207], v[150:151], off offset:1024 nt
	global_load_dwordx4 v[208:211], v[158:159], off nt
	global_load_dwordx4 v[212:215], v[158:159], off offset:1024 nt
	global_load_dwordx4 v[216:219], v[152:153], off nt
	global_load_dwordx4 v[220:223], v[152:153], off offset:1024 nt
	s_waitcnt vmcnt(14)
	v_lshlrev_b32_e32 v56, 16, v38
	v_lshlrev_b32_e32 v54, 16, v34
	v_and_b32_e32 v55, 0xffff0000, v34
	v_lshlrev_b32_e32 v34, 16, v35
	v_and_b32_e32 v35, 0xffff0000, v35
	v_and_b32_e32 v57, 0xffff0000, v38
	v_lshlrev_b32_e32 v38, 16, v39
	v_and_b32_e32 v39, 0xffff0000, v39
	v_lshlrev_b32_e32 v58, 16, v36
	v_and_b32_e32 v59, 0xffff0000, v36
	v_lshlrev_b32_e32 v36, 16, v37
	v_and_b32_e32 v37, 0xffff0000, v37
	v_lshlrev_b32_e32 v60, 16, v40
	v_and_b32_e32 v61, 0xffff0000, v40
	v_lshlrev_b32_e32 v40, 16, v41
	v_and_b32_e32 v41, 0xffff0000, v41
	v_pk_fma_f32 v[84:85], v[38:39], s[70:71], v[34:35] op_sel_hi:[1,0,1]
	v_pk_fma_f32 v[112:113], v[56:57], s[70:71], v[54:55] op_sel_hi:[1,0,1]
	v_pk_fma_f32 v[86:87], v[40:41], s[70:71], v[36:37] op_sel_hi:[1,0,1]
	v_pk_fma_f32 v[88:89], v[60:61], s[70:71], v[58:59] op_sel_hi:[1,0,1]
	v_pk_mov_b32 v[34:35], v[112:113], v[84:85] op_sel:[1,0]
	v_mov_b32_e32 v36, v112
	v_mov_b32_e32 v37, v85
	v_pk_mov_b32 v[38:39], v[88:89], v[86:87] op_sel:[1,0]
	v_mov_b32_e32 v40, v88
	v_mov_b32_e32 v41, v87
	s_waitcnt vmcnt(13)
	v_lshlrev_b32_e32 v62, 16, v42
	v_and_b32_e32 v63, 0xffff0000, v42
	v_lshlrev_b32_e32 v42, 16, v43
	v_and_b32_e32 v43, 0xffff0000, v43
	s_waitcnt vmcnt(12)
	v_lshlrev_b32_e32 v64, 16, v46
	v_and_b32_e32 v65, 0xffff0000, v46
	v_lshlrev_b32_e32 v46, 16, v47
	v_and_b32_e32 v47, 0xffff0000, v47
	v_lshlrev_b32_e32 v66, 16, v44
	v_and_b32_e32 v67, 0xffff0000, v44
	v_lshlrev_b32_e32 v44, 16, v45
	v_and_b32_e32 v45, 0xffff0000, v45
	v_lshlrev_b32_e32 v68, 16, v48
	v_and_b32_e32 v69, 0xffff0000, v48
	v_lshlrev_b32_e32 v48, 16, v49
	v_and_b32_e32 v49, 0xffff0000, v49
	v_pk_add_f32 v[34:35], v[34:35], v[36:37]
	v_pk_add_f32 v[36:37], v[38:39], v[40:41]
	v_pk_fma_f32 v[108:109], v[46:47], s[70:71], v[42:43] op_sel_hi:[1,0,1]
	v_pk_fma_f32 v[110:111], v[64:65], s[70:71], v[62:63] op_sel_hi:[1,0,1]
	v_pk_fma_f32 v[104:105], v[48:49], s[70:71], v[44:45] op_sel_hi:[1,0,1]
	v_pk_fma_f32 v[106:107], v[68:69], s[70:71], v[66:67] op_sel_hi:[1,0,1]
	v_add_f32_e32 v0, v34, v35
	v_pk_add_f32 v[34:35], v[36:37], v[36:37] op_sel_hi:[0,1]
	v_add_f32_e32 v43, v110, v111
	v_add_f32_e32 v45, v108, v109
	v_mov_b32_e32 v42, v106
	v_mov_b32_e32 v44, v107
	v_mov_b32_e32 v46, v105
	v_add_f32_e32 v47, 0, v0
	v_mov_b32_e32 v34, v104
	v_pk_add_f32 v[38:39], v[42:43], v[44:45]
	v_pk_add_f32 v[34:35], v[34:35], v[46:47]
	v_cndmask_b32_e64 v50, v82, v96, s[6:7]
	v_pk_add_f32 v[34:35], v[38:39], v[34:35]
	v_cndmask_b32_e64 v52, v82, v100, s[4:5]
	v_add_f32_e32 v0, v34, v35
	ds_bpermute_b32 v35, v233, v0
	v_cndmask_b32_e64 v34, v82, v98, s[8:9]
	v_ashrrev_i32_e32 v51, 31, v50
	v_ashrrev_i32_e32 v53, 31, v52
	v_lshlrev_b64 v[36:37], 11, v[50:51]
	s_waitcnt lgkmcnt(0)
	v_add_f32_e32 v0, v0, v35
	ds_bpermute_b32 v40, v234, v0
	v_ashrrev_i32_e32 v35, 31, v34
	v_lshlrev_b64 v[34:35], 11, v[34:35]
	v_lshl_add_u64 v[114:115], v[92:93], 0, v[34:35]
	v_lshlrev_b64 v[38:39], 11, v[52:53]
	s_waitcnt lgkmcnt(0)
	v_add_f32_e32 v0, v0, v40
	ds_bpermute_b32 v44, v235, v0
	v_lshl_add_u64 v[40:41], v[90:91], 0, v[36:37]
	v_lshl_add_u64 v[36:37], v[92:93], 0, v[36:37]
	v_lshl_add_u64 v[42:43], v[90:91], 0, v[38:39]
	s_waitcnt vmcnt(0)
	v_mov_b32_e32 v74, v176
	v_mov_b32_e32 v75, v177
	v_mov_b32_e32 v76, v178
	v_mov_b32_e32 v77, v179
	v_mov_b32_e32 v66, v180
	v_mov_b32_e32 v67, v181
	v_mov_b32_e32 v68, v182
	v_mov_b32_e32 v69, v183
	s_waitcnt lgkmcnt(0)
; DI unsigned pk2(float lo, float hi) { f32x2 f = {lo, hi}; bf2_t v = __builtin_convertvector(f, bf2_t); return __builtin_bit_cast(unsigned, v); }
; DI void ln_phase(int wv, const bf16_t* y, float* xo, const float* g, const float* bta, bf16_t* xb) {
;     ...
;                 const float mean = wave_sum(s_) * (1.f / DM); float s2 = 0.f;
; #pragma unroll
;                 for (int j = 0; j < 4; ++j) { v[j] = v[j] - mean; s2 += (v[j].x * v[j].x + v[j].y * v[j].y) + (v[j].z * v[j].z + v[j].w * v[j].w); }
;                 const float rstd = 1.f / sqrtf(wave_sum(s2) * (1.f / DM) + 1e-5f);
; #pragma unroll
;                 for (int j = 0; j < 2; ++j) { const f32x4 y0 = v[2 * j] * rstd * gv[2 * j] + bv[2 * j], y1 = v[2 * j + 1] * rstd * gv[2 * j + 1] + bv[2 * j + 1];
;                     if (xo) { *(f32x4*)(xo + (size_t)row * DM + j * 512 + lane * 8) = y0; *(f32x4*)(xo + (size_t)row * DM + j * 512 + lane * 8 + 4) = y1; }
;                     u32x4 w; w.x = pk2(y0.x, y0.y); w.y = pk2(y0.z, y0.w); w.z = pk2(y1.x, y1.y); w.w = pk2(y1.z, y1.w);
;                     *(u32x4*)(xb + (size_t)row * DM + j * 512 + lane * 8) = w; }
	v_add_f32_e32 v0, v0, v44
	ds_bpermute_b32 v46, v236, v0
	v_lshl_add_u64 v[44:45], v[90:91], 0, v[34:35]
	v_mov_b32_e32 v78, v184
	v_mov_b32_e32 v79, v185
	v_mov_b32_e32 v80, v186
	v_mov_b32_e32 v81, v187
	v_mov_b32_e32 v70, v188
	v_mov_b32_e32 v71, v189
	v_mov_b32_e32 v72, v190
	v_mov_b32_e32 v73, v191
	v_mov_b32_e32 v58, v192
	v_mov_b32_e32 v59, v193
	v_mov_b32_e32 v60, v194
	v_mov_b32_e32 v61, v195
	v_mov_b32_e32 v50, v196
	v_mov_b32_e32 v51, v197
	v_mov_b32_e32 v52, v198
	v_mov_b32_e32 v53, v199
	v_lshl_add_u64 v[38:39], v[92:93], 0, v[38:39]
	v_lshlrev_b64 v[82:83], 12, v[82:83]
	s_waitcnt lgkmcnt(0)
	v_add_f32_e32 v0, v0, v46
	ds_bpermute_b32 v34, v237, v0
	s_waitcnt lgkmcnt(0)
	v_add_f32_e32 v0, v0, v34
	ds_bpermute_b32 v42, v238, v0
	v_mov_b32_e32 v62, v200
	v_mov_b32_e32 v63, v201
	v_mov_b32_e32 v64, v202
	v_mov_b32_e32 v65, v203
	v_mov_b32_e32 v54, v204
	v_mov_b32_e32 v55, v205
	v_mov_b32_e32 v56, v206
	v_mov_b32_e32 v57, v207
	s_nop 0
	v_mov_b32_e32 v38, v208
	v_mov_b32_e32 v39, v209
	v_mov_b32_e32 v40, v210
	v_mov_b32_e32 v41, v211
	v_mov_b32_e32 v34, v212
	v_mov_b32_e32 v35, v213
	v_mov_b32_e32 v36, v214
	v_mov_b32_e32 v37, v215
	s_waitcnt lgkmcnt(0)
	v_add_f32_e32 v97, v0, v42
	v_fmamk_f32 v113, v97, 0xba800000, v113
	v_fmac_f32_e32 v112, 0xba800000, v97
	v_fmamk_f32 v85, v97, 0xba800000, v85
	v_fmac_f32_e32 v84, 0xba800000, v97
	v_fmamk_f32 v89, v97, 0xba800000, v89
	v_fmac_f32_e32 v88, 0xba800000, v97
	v_fmamk_f32 v87, v97, 0xba800000, v87
	v_fmac_f32_e32 v86, 0xba800000, v97
	v_pk_mul_f32 v[42:43], v[84:85], v[84:85]
	v_pk_mul_f32 v[44:45], v[112:113], v[112:113]
	v_pk_mul_f32 v[46:47], v[86:87], v[86:87]
	v_pk_mul_f32 v[48:49], v[88:89], v[88:89]
	v_fmac_f32_e32 v110, 0xba800000, v97
	v_pk_mov_b32 v[116:117], v[44:45], v[42:43] op_sel:[1,0]
	v_mov_b32_e32 v45, v43
	v_pk_mov_b32 v[42:43], v[48:49], v[46:47] op_sel:[1,0]
	v_mov_b32_e32 v49, v47
	v_fmac_f32_e32 v108, 0xba800000, v97
	v_fmamk_f32 v111, v97, 0xba800000, v111
	v_mul_f32_e32 v0, v110, v110
	v_fmamk_f32 v109, v97, 0xba800000, v109
	v_pk_add_f32 v[44:45], v[116:117], v[44:45]
	v_pk_add_f32 v[42:43], v[42:43], v[48:49]
	v_pk_fma_f32 v[46:47], v[110:111], v[110:111], v[0:1] op_sel_hi:[1,1,0]
	v_mul_f32_e32 v0, v108, v108
	v_pk_add_f32 v[44:45], v[44:45], v[44:45] op_sel_hi:[0,1]
	v_pk_add_f32 v[42:43], v[42:43], v[42:43] op_sel_hi:[0,1]
	v_pk_fma_f32 v[48:49], v[108:109], v[108:109], v[0:1] op_sel_hi:[1,1,0]
	v_fmamk_f32 v105, v97, 0xba800000, v105
	v_fmac_f32_e32 v104, 0xba800000, v97
	v_fmamk_f32 v107, v97, 0xba800000, v107
	v_fmac_f32_e32 v106, 0xba800000, v97
	v_mul_f32_e32 v46, v106, v106
	v_mul_f32_e32 v48, v107, v107
	v_mul_f32_e32 v44, v104, v104
	v_mul_f32_e32 v42, v105, v105
	v_pk_add_f32 v[46:47], v[46:47], v[48:49]
	v_pk_add_f32 v[42:43], v[44:45], v[42:43]
	s_nop 0
	v_pk_add_f32 v[42:43], v[46:47], v[42:43]
	s_nop 0
	v_add_f32_e32 v0, v42, v43
	v_mov_b32_e32 v46, v216
	v_mov_b32_e32 v47, v217
	v_mov_b32_e32 v48, v218
	v_mov_b32_e32 v49, v219
	v_mov_b32_e32 v42, v220
	v_mov_b32_e32 v43, v221
	v_mov_b32_e32 v44, v222
	v_mov_b32_e32 v45, v223
	ds_bpermute_b32 v97, v233, v0
	s_waitcnt lgkmcnt(0)
	v_add_f32_e32 v0, v0, v97
	ds_bpermute_b32 v97, v234, v0
	s_waitcnt lgkmcnt(0)
	v_add_f32_e32 v0, v0, v97
	ds_bpermute_b32 v97, v235, v0
	s_waitcnt lgkmcnt(0)
	v_add_f32_e32 v0, v0, v97
	ds_bpermute_b32 v97, v236, v0
	s_waitcnt lgkmcnt(0)
	v_add_f32_e32 v0, v0, v97
	ds_bpermute_b32 v97, v237, v0
	s_waitcnt lgkmcnt(0)
	v_add_f32_e32 v0, v0, v97
	ds_bpermute_b32 v97, v238, v0
	s_waitcnt lgkmcnt(0)
	v_add_f32_e32 v0, v0, v97
	v_fmamk_f32 v0, v0, 0x3a800000, v243
	v_mul_f32_e32 v97, 0x4f800000, v0
	v_cmp_gt_f32_e32 vcc, s37, v0
	s_nop 1
	v_cndmask_b32_e32 v0, v0, v97, vcc
	v_sqrt_f32_e32 v97, v0
	s_nop 0
	v_add_u32_e32 v99, -1, v97
	v_add_u32_e32 v101, 1, v97
	v_fma_f32 v114, -v99, v97, v0
	v_fma_f32 v115, -v101, v97, v0
	v_cmp_ge_f32_e64 s[0:1], 0, v114
	s_nop 1
	v_cndmask_b32_e64 v97, v97, v99, s[0:1]
	v_cmp_lt_f32_e64 s[0:1], 0, v115
	v_lshl_add_u64 v[114:115], v[94:95], 0, v[82:83]
	s_nop 0
	v_cndmask_b32_e64 v97, v97, v101, s[0:1]
	v_mul_f32_e32 v99, 0x37800000, v97
	v_cndmask_b32_e32 v97, v97, v99, vcc
	v_cmp_class_f32_e32 vcc, v0, v242
	s_nop 1
	v_cndmask_b32_e32 v0, v97, v0, vcc
	v_div_scale_f32 v97, s[0:1], v0, v0, 1.0
	v_rcp_f32_e32 v99, v97
	v_div_scale_f32 v82, vcc, 1.0, v0, 1.0
	v_fma_f32 v83, -v97, v99, 1.0
	v_fmac_f32_e32 v99, v83, v99
	v_mul_f32_e32 v83, v82, v99
	v_fma_f32 v101, -v97, v83, v82
	v_fmac_f32_e32 v83, v101, v99
	v_fma_f32 v82, -v97, v83, v82
	v_div_fmas_f32 v82, v82, v99, v83
	v_div_fixup_f32 v116, v82, v0, 1.0
	v_pk_mul_f32 v[82:83], v[112:113], v[116:117] op_sel_hi:[1,0]
	v_pk_mul_f32 v[84:85], v[84:85], v[116:117] op_sel_hi:[1,0]
	v_pk_mul_f32 v[112:113], v[88:89], v[116:117] op_sel_hi:[1,0]
	v_pk_mul_f32 v[86:87], v[86:87], v[116:117] op_sel_hi:[1,0]
	v_cndmask_b32_e64 v0, 0, 1, s[28:29]
	v_pk_fma_f32 v[84:85], v[12:13], v[84:85], v[16:17]
	v_pk_fma_f32 v[82:83], v[10:11], v[82:83], v[14:15]
	v_pk_fma_f32 v[88:89], v[4:5], v[86:87], v[8:9]
	v_cmp_ne_u32_e64 s[0:1], 1, v0
	s_andn2_b64 vcc, exec, s[28:29]
	v_pk_fma_f32 v[86:87], v[2:3], v[112:113], v[6:7]
	s_cbranch_vccnz .LBB0_588
	global_store_dwordx4 v[114:115], v[82:85], off
	global_store_dwordx4 v[114:115], v[86:89], off offset:16

; #define LAS __attribute__((address_space(3)))
; #define scr (p.ws + opq_off(SCR_OFF))
; DI void transpose_item(const float* W, int K, int ldw, int nblk, bf16_t* WT, LAS float* scr, int item, int lane) {
;     const int kb = item / nblk, nb = item % nblk, k0 = 64 * kb, n0 = 32 * nb;
;     float wv_[32];
; #pragma unroll
;     for (int i = 0; i < 32; ++i) { const int kk = 2 * i + (lane >> 5); wv_[i] = W[(size_t)(k0 + kk) * ldw + n0 + (lane & 31)]; }
; #pragma unroll
;     for (int i = 0; i < 32; ++i) { const int kk = 2 * i + (lane >> 5); scr[kk * 33 + (lane & 31)] = wv_[i]; }
; DI void wprep_layer(int wv, LAS unsigned char* lds, const Params& p, int layer, bf16_t* wb) {
;     ...
;     for (int it = bid * 8 + wid; it < tot; it += gridDim.x * 8) {
;         int r = it;
;         if (r < I0) { transpose_item(w_in, 1024, ldw_in, nin / 32, wb, scr, r, lane); continue; } r -= I0;
;         if (r < I1) { transpose_item(w_out, 1024, 1024, 32, wb_out, scr, r, lane); continue; } r -= I1;
;         if (r < I2) { transpose_item(w1, 1024, 4096, 128, wb_1, scr, r, lane); continue; } r -= I2;
;         transpose_item(w2, 4096, 1024, 32, wb_2, scr, r, lane);
.LBB0_611:
	v_cmp_le_i32_e32 vcc, s44, v19
	s_and_saveexec_b64 s[6:7], vcc
	s_xor_b64 s[6:7], exec, s[6:7]
	s_cbranch_execz .LBB0_621
	v_add_u32_e32 v0, s73, v19
	s_movk_i32 s2, 0x1ff
	v_cmp_lt_i32_e32 vcc, s2, v0
	s_and_saveexec_b64 s[8:9], vcc
	s_xor_b64 s[8:9], exec, s[8:9]
	s_cbranch_execz .LBB0_618
	s_movk_i32 s2, 0x9ff
	v_cmp_lt_u32_e32 vcc, s2, v0
	s_and_saveexec_b64 s[12:13], vcc
	s_xor_b64 s[20:21], exec, s[12:13]
	s_cbranch_execz .LBB0_615
	v_and_b32_e32 v0, 0x7fffffc0, v35
	v_add_u32_e32 v20, 0xffffec00, v0
	v_and_b32_e32 v26, 0x3e0, v18
	v_or_b32_e32 v24, v20, v28
	v_lshlrev_b32_e32 v0, 2, v26
	v_mov_b32_e32 v25, v1
	v_lshl_add_u64 v[22:23], v[2:3], 0, v[0:1]
	v_lshlrev_b64 v[36:37], 12, v[24:25]
	v_lshl_add_u64 v[36:37], v[22:23], 0, v[36:37]
	v_or_b32_e32 v0, 2, v24
	global_load_dword v21, v[36:37], off nt
	v_lshlrev_b64 v[36:37], 12, v[0:1]
	v_lshl_add_u64 v[36:37], v[22:23], 0, v[36:37]
	v_or_b32_e32 v0, 4, v24
	global_load_dword v27, v[36:37], off nt
	v_lshlrev_b64 v[36:37], 12, v[0:1]
	v_lshl_add_u64 v[36:37], v[22:23], 0, v[36:37]
	v_or_b32_e32 v0, 6, v24
	global_load_dword v38, v[36:37], off nt
	v_lshlrev_b64 v[36:37], 12, v[0:1]
	v_lshl_add_u64 v[36:37], v[22:23], 0, v[36:37]
	v_or_b32_e32 v0, 8, v24
	global_load_dword v39, v[36:37], off nt
	v_lshlrev_b64 v[36:37], 12, v[0:1]
	v_lshl_add_u64 v[36:37], v[22:23], 0, v[36:37]
	v_or_b32_e32 v0, 10, v24
	global_load_dword v40, v[36:37], off nt
	v_lshlrev_b64 v[36:37], 12, v[0:1]
	v_lshl_add_u64 v[36:37], v[22:23], 0, v[36:37]
	v_or_b32_e32 v0, 12, v24
	global_load_dword v41, v[36:37], off nt
	v_lshlrev_b64 v[36:37], 12, v[0:1]
	v_lshl_add_u64 v[36:37], v[22:23], 0, v[36:37]
	v_or_b32_e32 v0, 14, v24
	global_load_dword v42, v[36:37], off nt
	v_lshlrev_b64 v[36:37], 12, v[0:1]
	v_lshl_add_u64 v[36:37], v[22:23], 0, v[36:37]
	v_or_b32_e32 v0, 16, v24
	global_load_dword v43, v[36:37], off nt
	v_lshlrev_b64 v[36:37], 12, v[0:1]
	v_lshl_add_u64 v[36:37], v[22:23], 0, v[36:37]
	v_or_b32_e32 v0, 18, v24
	global_load_dword v44, v[36:37], off nt
	v_lshlrev_b64 v[36:37], 12, v[0:1]
	v_lshl_add_u64 v[36:37], v[22:23], 0, v[36:37]
	v_or_b32_e32 v0, 20, v24
	global_load_dword v45, v[36:37], off nt
	v_lshlrev_b64 v[36:37], 12, v[0:1]
	v_lshl_add_u64 v[36:37], v[22:23], 0, v[36:37]
	v_or_b32_e32 v0, 22, v24
	global_load_dword v46, v[36:37], off nt
	v_lshlrev_b64 v[36:37], 12, v[0:1]
	v_lshl_add_u64 v[36:37], v[22:23], 0, v[36:37]
	v_or_b32_e32 v0, 24, v24
	global_load_dword v47, v[36:37], off nt
	v_lshlrev_b64 v[36:37], 12, v[0:1]
	v_lshl_add_u64 v[36:37], v[22:23], 0, v[36:37]
	v_or_b32_e32 v0, 26, v24
	global_load_dword v48, v[36:37], off nt
	v_lshlrev_b64 v[36:37], 12, v[0:1]
	v_lshl_add_u64 v[36:37], v[22:23], 0, v[36:37]
	v_or_b32_e32 v0, 28, v24
	global_load_dword v49, v[36:37], off nt
	v_lshlrev_b64 v[36:37], 12, v[0:1]
	v_lshl_add_u64 v[36:37], v[22:23], 0, v[36:37]
	v_or_b32_e32 v0, 30, v24
	global_load_dword v50, v[36:37], off nt
	v_lshlrev_b64 v[36:37], 12, v[0:1]
	v_lshl_add_u64 v[36:37], v[22:23], 0, v[36:37]
	v_or_b32_e32 v0, 32, v24
	global_load_dword v51, v[36:37], off nt
	v_lshlrev_b64 v[36:37], 12, v[0:1]
	v_lshl_add_u64 v[36:37], v[22:23], 0, v[36:37]
	v_or_b32_e32 v0, 34, v24
	global_load_dword v52, v[36:37], off nt
	v_lshlrev_b64 v[36:37], 12, v[0:1]
	v_lshl_add_u64 v[36:37], v[22:23], 0, v[36:37]
	v_or_b32_e32 v0, 36, v24
	global_load_dword v53, v[36:37], off nt
	v_lshlrev_b64 v[36:37], 12, v[0:1]
	v_lshl_add_u64 v[36:37], v[22:23], 0, v[36:37]
	v_or_b32_e32 v0, 38, v24
	global_load_dword v54, v[36:37], off nt
	v_lshlrev_b64 v[36:37], 12, v[0:1]
	v_lshl_add_u64 v[36:37], v[22:23], 0, v[36:37]
	v_or_b32_e32 v0, 40, v24
	global_load_dword v55, v[36:37], off nt
	v_lshlrev_b64 v[36:37], 12, v[0:1]
	v_lshl_add_u64 v[36:37], v[22:23], 0, v[36:37]
	v_or_b32_e32 v0, 42, v24
	global_load_dword v56, v[36:37], off nt
	v_lshlrev_b64 v[36:37], 12, v[0:1]
	v_lshl_add_u64 v[36:37], v[22:23], 0, v[36:37]
	v_or_b32_e32 v0, 44, v24
	global_load_dword v57, v[36:37], off nt
	v_lshlrev_b64 v[36:37], 12, v[0:1]
	v_lshl_add_u64 v[36:37], v[22:23], 0, v[36:37]
	v_or_b32_e32 v0, 46, v24
	global_load_dword v58, v[36:37], off nt
	v_lshlrev_b64 v[36:37], 12, v[0:1]
	v_lshl_add_u64 v[36:37], v[22:23], 0, v[36:37]
	v_or_b32_e32 v0, 48, v24
	global_load_dword v59, v[36:37], off nt
	v_lshlrev_b64 v[36:37], 12, v[0:1]
	v_lshl_add_u64 v[36:37], v[22:23], 0, v[36:37]
	v_or_b32_e32 v0, 50, v24
	global_load_dword v60, v[36:37], off nt
	v_lshlrev_b64 v[36:37], 12, v[0:1]
	v_lshl_add_u64 v[36:37], v[22:23], 0, v[36:37]
	v_or_b32_e32 v0, 52, v24
	global_load_dword v61, v[36:37], off nt
	v_lshlrev_b64 v[36:37], 12, v[0:1]
	v_lshl_add_u64 v[36:37], v[22:23], 0, v[36:37]
	v_or_b32_e32 v0, 54, v24
	global_load_dword v62, v[36:37], off nt
	v_lshlrev_b64 v[36:37], 12, v[0:1]
	v_lshl_add_u64 v[36:37], v[22:23], 0, v[36:37]
	v_or_b32_e32 v0, 56, v24
	global_load_dword v63, v[36:37], off nt
	v_lshlrev_b64 v[36:37], 12, v[0:1]
	v_lshl_add_u64 v[36:37], v[22:23], 0, v[36:37]
	v_or_b32_e32 v0, 58, v24
	global_load_dword v64, v[36:37], off nt
	v_lshlrev_b64 v[36:37], 12, v[0:1]
	v_lshl_add_u64 v[36:37], v[22:23], 0, v[36:37]
	v_or_b32_e32 v0, 60, v24
	global_load_dword v65, v[36:37], off nt
	v_lshlrev_b64 v[36:37], 12, v[0:1]
	v_or_b32_e32 v0, 62, v24
	v_lshlrev_b64 v[24:25], 12, v[0:1]
	v_lshl_add_u64 v[36:37], v[22:23], 0, v[36:37]
	v_lshl_add_u64 v[22:23], v[22:23], 0, v[24:25]
	global_load_dword v36, v[36:37], off nt
	s_nop 0
	global_load_dword v0, v[22:23], off nt
	s_waitcnt vmcnt(30)
	ds_write2_b32 v29, v21, v27 offset1:66
	s_waitcnt vmcnt(28)
	ds_write2_b32 v29, v38, v39 offset0:132 offset1:198
	v_add_u32_e32 v21, 0x400, v29
	s_waitcnt vmcnt(26)
; #define LAS __attribute__((address_space(3)))
; DI unsigned pk2(float lo, float hi) { f32x2 f = {lo, hi}; bf2_t v = __builtin_convertvector(f, bf2_t); return __builtin_bit_cast(unsigned, v); }
; #define scr (p.ws + opq_off(SCR_OFF))
; DI void transpose_item(const float* W, int K, int ldw, int nblk, bf16_t* WT, LAS float* scr, int item, int lane) {
;     const int kb = item / nblk, nb = item % nblk, k0 = 64 * kb, n0 = 32 * nb;
;     float wv_[32];
; #pragma unroll
;     for (int i = 0; i < 32; ++i) { const int kk = 2 * i + (lane >> 5); wv_[i] = W[(size_t)(k0 + kk) * ldw + n0 + (lane & 31)]; }
; #pragma unroll
;     for (int i = 0; i < 32; ++i) { const int kk = 2 * i + (lane >> 5); scr[kk * 33 + (lane & 31)] = wv_[i]; }
;     asm volatile("s_waitcnt lgkmcnt(0)" ::: "memory");
;     const int c = lane & 7;
; #pragma unroll
;     for (int j = 0; j < 4; ++j) { const int n = (lane >> 3) + 8 * j; const LAS float* s = scr + (8 * c) * 33 + n;
;         u32x4 o; o.x = pk2(s[0 * 33], s[1 * 33]); o.y = pk2(s[2 * 33], s[3 * 33]); o.z = pk2(s[4 * 33], s[5 * 33]); o.w = pk2(s[6 * 33], s[7 * 33]);
;         *(u32x4*)(WT + (size_t)(n0 + n) * K + k0 + 8 * c) = o; }
;     asm volatile("s_waitcnt lgkmcnt(0)" ::: "memory");
	ds_write2_b32 v21, v40, v41 offset0:8 offset1:74
	s_waitcnt vmcnt(24)
	ds_write2_b32 v21, v42, v43 offset0:140 offset1:206
	v_add_u32_e32 v21, 0x800, v29
	s_waitcnt vmcnt(22)
	ds_write2_b32 v21, v44, v45 offset0:16 offset1:82
	s_waitcnt vmcnt(20)
	ds_write2_b32 v21, v46, v47 offset0:148 offset1:214
	v_add_u32_e32 v21, 0xc00, v29
	s_waitcnt vmcnt(18)
	ds_write2_b32 v21, v48, v49 offset0:24 offset1:90
	s_waitcnt vmcnt(16)
	ds_write2_b32 v21, v50, v51 offset0:156 offset1:222
	v_add_u32_e32 v21, 0x1000, v29
	s_waitcnt vmcnt(14)
	ds_write2_b32 v21, v52, v53 offset0:32 offset1:98
	s_waitcnt vmcnt(12)
	ds_write2_b32 v21, v54, v55 offset0:164 offset1:230
	v_add_u32_e32 v21, 0x1400, v29
	s_waitcnt vmcnt(10)
	ds_write2_b32 v21, v56, v57 offset0:40 offset1:106
	s_waitcnt vmcnt(8)
	ds_write2_b32 v21, v58, v59 offset0:172 offset1:238
	v_add_u32_e32 v21, 0x1800, v29
	s_waitcnt vmcnt(6)
	ds_write2_b32 v21, v60, v61 offset0:48 offset1:114
	s_waitcnt vmcnt(4)
	ds_write2_b32 v21, v62, v63 offset0:180 offset1:246
	v_add_u32_e32 v21, 0x1c00, v29
	s_waitcnt vmcnt(2)
	ds_write2_b32 v21, v64, v65 offset0:56 offset1:122
	s_waitcnt vmcnt(0)
	ds_write2_b32 v21, v36, v0 offset0:188 offset1:254
	s_waitcnt lgkmcnt(0)
	ds_read2_b32 v[36:37], v31 offset0:33 offset1:41
	ds_read2_b32 v[38:39], v31 offset1:8
	ds_read2_b32 v[40:41], v31 offset0:66 offset1:74
	ds_read2_b32 v[42:43], v31 offset0:99 offset1:107
	ds_read2_b32 v[44:45], v31 offset0:132 offset1:140
	ds_read2_b32 v[46:47], v31 offset0:165 offset1:173
	ds_read2_b32 v[48:49], v31 offset0:198 offset1:206
	ds_read2_b32 v[50:51], v31 offset0:231 offset1:239
	v_mov_b32_e32 v21, v1
	v_or_b32_e32 v0, v26, v30
	v_lshl_add_u64 v[24:25], v[20:21], 1, v[6:7]
	v_lshlrev_b32_e32 v0, 13, v0
	v_lshl_add_u64 v[52:53], v[24:25], 0, v[0:1]
	v_or_b32_e32 v0, v26, v32
	s_waitcnt lgkmcnt(6)
	v_cvt_pk_bf16_f32 v20, v38, v36
	s_waitcnt lgkmcnt(4)
	v_cvt_pk_bf16_f32 v21, v40, v42
	s_waitcnt lgkmcnt(2)
	v_cvt_pk_bf16_f32 v22, v44, v46
	s_waitcnt lgkmcnt(0)
	v_cvt_pk_bf16_f32 v23, v48, v50
	v_lshlrev_b32_e32 v0, 13, v0
	global_store_dwordx4 v[52:53], v[20:23], off
	s_nop 1
	v_cvt_pk_bf16_f32 v20, v39, v37
	v_cvt_pk_bf16_f32 v21, v41, v43
	v_cvt_pk_bf16_f32 v22, v45, v47
	v_cvt_pk_bf16_f32 v23, v49, v51
	v_lshl_add_u64 v[36:37], v[24:25], 0, v[0:1]
	global_store_dwordx4 v[36:37], v[20:23], off
	ds_read2_b32 v[36:37], v31 offset0:49 offset1:57
	ds_read2_b32 v[38:39], v31 offset0:16 offset1:24
	ds_read2_b32 v[40:41], v31 offset0:82 offset1:90
	ds_read2_b32 v[42:43], v31 offset0:115 offset1:123
	ds_read2_b32 v[44:45], v31 offset0:148 offset1:156
	ds_read2_b32 v[46:47], v31 offset0:181 offset1:189
	ds_read2_b32 v[48:49], v31 offset0:214 offset1:222
	ds_read2_b32 v[50:51], v31 offset0:247 offset1:255
	v_or_b32_e32 v0, v26, v33
	v_lshlrev_b32_e32 v0, 13, v0
	v_lshl_add_u64 v[52:53], v[24:25], 0, v[0:1]
	v_or_b32_e32 v0, v26, v34
	s_waitcnt lgkmcnt(6)
	v_cvt_pk_bf16_f32 v20, v38, v36
	s_waitcnt lgkmcnt(4)
	v_cvt_pk_bf16_f32 v21, v40, v42
	s_waitcnt lgkmcnt(2)
	v_cvt_pk_bf16_f32 v22, v44, v46
	s_waitcnt lgkmcnt(0)
	v_cvt_pk_bf16_f32 v23, v48, v50
	v_lshlrev_b32_e32 v0, 13, v0
	global_store_dwordx4 v[52:53], v[20:23], off
	v_lshl_add_u64 v[24:25], v[24:25], 0, v[0:1]
	s_nop 0
	v_cvt_pk_bf16_f32 v20, v39, v37
	v_cvt_pk_bf16_f32 v21, v41, v43
	v_cvt_pk_bf16_f32 v22, v45, v47
	v_cvt_pk_bf16_f32 v23, v49, v51
	global_store_dwordx4 v[24:25], v[20:23], off
	s_waitcnt lgkmcnt(0)
.LBB0_615:
	s_andn2_saveexec_b64 s[20:21], s[20:21]
	s_cbranch_execz .LBB0_617
	v_add_u32_e32 v0, 0xfe00, v0
	v_lshrrev_b32_e32 v0, 1, v0
	v_and_b32_e32 v23, 0x7fc0, v0
	v_and_b32_e32 v22, 0xfe0, v18
	v_or_b32_e32 v24, v23, v28
	v_lshlrev_b32_e32 v0, 2, v22
	v_lshl_add_u64 v[20:21], v[8:9], 0, v[0:1]
	v_lshlrev_b32_e32 v0, 14, v24
	v_lshl_add_u64 v[20:21], v[20:21], 0, v[0:1]
	v_add_co_u32_e32 v24, vcc, 0x8000, v20
	s_mov_b32 s2, 0x10000
	s_nop 0
	v_addc_co_u32_e32 v25, vcc, 0, v21, vcc
	global_load_dword v0, v[20:21], off nt
	global_load_dword v26, v[24:25], off nt
	v_add_co_u32_e32 v24, vcc, s2, v20
	s_mov_b32 s2, 0x18000
	s_nop 0
	v_addc_co_u32_e32 v25, vcc, 0, v21, vcc
	global_load_dword v27, v[24:25], off nt
	v_add_co_u32_e32 v24, vcc, s2, v20
	s_mov_b32 s2, 0x48000
	s_nop 0
	v_addc_co_u32_e32 v25, vcc, 0, v21, vcc
	global_load_dword v36, v[24:25], off nt
	v_add_co_u32_e32 v24, vcc, 0x20000, v20
	s_nop 1
	v_addc_co_u32_e32 v25, vcc, 0, v21, vcc
	global_load_dword v37, v[24:25], off nt
	v_add_co_u32_e32 v24, vcc, 0x28000, v20
	s_nop 1
	v_addc_co_u32_e32 v25, vcc, 0, v21, vcc
	global_load_dword v38, v[24:25], off nt
	v_add_co_u32_e32 v24, vcc, 0x30000, v20
	s_nop 1
	v_addc_co_u32_e32 v25, vcc, 0, v21, vcc
	global_load_dword v39, v[24:25], off nt
	v_add_co_u32_e32 v24, vcc, 0x38000, v20
	s_nop 1
	v_addc_co_u32_e32 v25, vcc, 0, v21, vcc
	global_load_dword v40, v[24:25], off nt
	v_add_co_u32_e32 v24, vcc, s94, v20
	s_nop 1
	v_addc_co_u32_e32 v25, vcc, 0, v21, vcc
	global_load_dword v41, v[24:25], off nt
	v_add_co_u32_e32 v24, vcc, s2, v20
	s_mov_b32 s2, 0x50000
	s_nop 0
	v_addc_co_u32_e32 v25, vcc, 0, v21, vcc
	global_load_dword v42, v[24:25], off nt
	v_add_co_u32_e32 v24, vcc, s2, v20
	s_mov_b32 s2, 0x58000
	s_nop 0
	v_addc_co_u32_e32 v25, vcc, 0, v21, vcc
	global_load_dword v43, v[24:25], off nt
	v_add_co_u32_e32 v24, vcc, s2, v20
	s_mov_b32 s2, 0x60000
	s_nop 0
	v_addc_co_u32_e32 v25, vcc, 0, v21, vcc
	global_load_dword v44, v[24:25], off nt
	v_add_co_u32_e32 v24, vcc, s2, v20
	s_mov_b32 s2, 0x68000
	s_nop 0
	v_addc_co_u32_e32 v25, vcc, 0, v21, vcc
	global_load_dword v45, v[24:25], off nt
	v_add_co_u32_e32 v24, vcc, s2, v20
	s_mov_b32 s2, 0x70000
	s_nop 0
; #define LAS __attribute__((address_space(3)))
; DI unsigned pk2(float lo, float hi) { f32x2 f = {lo, hi}; bf2_t v = __builtin_convertvector(f, bf2_t); return __builtin_bit_cast(unsigned, v); }
; #define scr (p.ws + opq_off(SCR_OFF))
; DI void transpose_item(const float* W, int K, int ldw, int nblk, bf16_t* WT, LAS float* scr, int item, int lane) {
;     const int kb = item / nblk, nb = item % nblk, k0 = 64 * kb, n0 = 32 * nb;
;     float wv_[32];
; #pragma unroll
;     for (int i = 0; i < 32; ++i) { const int kk = 2 * i + (lane >> 5); wv_[i] = W[(size_t)(k0 + kk) * ldw + n0 + (lane & 31)]; }
; #pragma unroll
;     for (int i = 0; i < 32; ++i) { const int kk = 2 * i + (lane >> 5); scr[kk * 33 + (lane & 31)] = wv_[i]; }
;     asm volatile("s_waitcnt lgkmcnt(0)" ::: "memory");
;     const int c = lane & 7;
; #pragma unroll
;     for (int j = 0; j < 4; ++j) { const int n = (lane >> 3) + 8 * j; const LAS float* s = scr + (8 * c) * 33 + n;
;         u32x4 o; o.x = pk2(s[0 * 33], s[1 * 33]); o.y = pk2(s[2 * 33], s[3 * 33]); o.z = pk2(s[4 * 33], s[5 * 33]); o.w = pk2(s[6 * 33], s[7 * 33]);
;         *(u32x4*)(WT + (size_t)(n0 + n) * K + k0 + 8 * c) = o; }
;     asm volatile("s_waitcnt lgkmcnt(0)" ::: "memory");
	v_addc_co_u32_e32 v25, vcc, 0, v21, vcc
	global_load_dword v46, v[24:25], off nt
	v_add_co_u32_e32 v24, vcc, s2, v20
	s_mov_b32 s2, 0x78000
	s_nop 0
	v_addc_co_u32_e32 v25, vcc, 0, v21, vcc
	global_load_dword v47, v[24:25], off nt
	v_add_co_u32_e32 v24, vcc, s2, v20
	s_mov_b32 s2, 0x80000
	s_nop 0
	v_addc_co_u32_e32 v25, vcc, 0, v21, vcc
	global_load_dword v48, v[24:25], off nt
	v_add_co_u32_e32 v24, vcc, s2, v20
	s_mov_b32 s2, 0x88000
	s_nop 0
	v_addc_co_u32_e32 v25, vcc, 0, v21, vcc
	global_load_dword v49, v[24:25], off nt
	v_add_co_u32_e32 v24, vcc, s2, v20
	s_mov_b32 s2, 0x90000
	s_nop 0
	v_addc_co_u32_e32 v25, vcc, 0, v21, vcc
	global_load_dword v50, v[24:25], off nt
	v_add_co_u32_e32 v24, vcc, s2, v20
	s_mov_b32 s2, 0x98000
	s_nop 0
	v_addc_co_u32_e32 v25, vcc, 0, v21, vcc
	global_load_dword v51, v[24:25], off nt
	v_add_co_u32_e32 v24, vcc, s2, v20
	s_mov_b32 s2, 0xa0000
	s_nop 0
	v_addc_co_u32_e32 v25, vcc, 0, v21, vcc
	global_load_dword v52, v[24:25], off nt
	v_add_co_u32_e32 v24, vcc, s2, v20
	s_mov_b32 s2, 0xa8000
	s_nop 0
	v_addc_co_u32_e32 v25, vcc, 0, v21, vcc
	global_load_dword v53, v[24:25], off nt
	v_add_co_u32_e32 v24, vcc, s2, v20
	s_mov_b32 s2, 0xb0000
	s_nop 0
	v_addc_co_u32_e32 v25, vcc, 0, v21, vcc
	global_load_dword v54, v[24:25], off nt
	v_add_co_u32_e32 v24, vcc, s2, v20
	s_mov_b32 s2, 0xb8000
	s_nop 0
	v_addc_co_u32_e32 v25, vcc, 0, v21, vcc
	global_load_dword v55, v[24:25], off nt
	v_add_co_u32_e32 v24, vcc, s2, v20
	s_mov_b32 s2, 0xc0000
	s_nop 0
	v_addc_co_u32_e32 v25, vcc, 0, v21, vcc
	global_load_dword v56, v[24:25], off nt
	v_add_co_u32_e32 v24, vcc, s2, v20
	s_mov_b32 s2, 0xc8000
	s_nop 0
	v_addc_co_u32_e32 v25, vcc, 0, v21, vcc
	global_load_dword v57, v[24:25], off nt
	v_add_co_u32_e32 v24, vcc, s2, v20
	s_mov_b32 s2, 0xd0000
	s_nop 0
	v_addc_co_u32_e32 v25, vcc, 0, v21, vcc
	global_load_dword v58, v[24:25], off nt
	v_add_co_u32_e32 v24, vcc, s2, v20
	s_mov_b32 s2, 0xd8000
	s_nop 0
	v_addc_co_u32_e32 v25, vcc, 0, v21, vcc
	global_load_dword v59, v[24:25], off nt
	v_add_co_u32_e32 v24, vcc, s2, v20
	s_mov_b32 s2, 0xe0000
	s_nop 0
	v_addc_co_u32_e32 v25, vcc, 0, v21, vcc
	global_load_dword v60, v[24:25], off nt
	v_add_co_u32_e32 v24, vcc, s2, v20
	s_mov_b32 s2, 0xe8000
	s_nop 0
	v_addc_co_u32_e32 v25, vcc, 0, v21, vcc
	global_load_dword v61, v[24:25], off nt
	v_add_co_u32_e32 v24, vcc, s2, v20
	s_mov_b32 s2, 0xf0000
	s_nop 0
	v_addc_co_u32_e32 v25, vcc, 0, v21, vcc
	global_load_dword v62, v[24:25], off nt
	v_add_co_u32_e32 v24, vcc, s2, v20
	s_mov_b32 s2, 0xf8000
	s_nop 0
	v_addc_co_u32_e32 v25, vcc, 0, v21, vcc
	v_add_co_u32_e32 v20, vcc, s2, v20
	global_load_dword v24, v[24:25], off nt
	s_nop 0
	v_addc_co_u32_e32 v21, vcc, 0, v21, vcc
	global_load_dword v20, v[20:21], off nt
	s_waitcnt vmcnt(30)
	ds_write2_b32 v29, v0, v26 offset1:66
	s_waitcnt vmcnt(28)
	ds_write2_b32 v29, v27, v36 offset0:132 offset1:198
	v_add_u32_e32 v0, 0x400, v29
	s_waitcnt vmcnt(26)
	ds_write2_b32 v0, v37, v38 offset0:8 offset1:74
	s_waitcnt vmcnt(24)
	ds_write2_b32 v0, v39, v40 offset0:140 offset1:206
	v_add_u32_e32 v0, 0x800, v29
	s_waitcnt vmcnt(22)
	ds_write2_b32 v0, v41, v42 offset0:16 offset1:82
	s_waitcnt vmcnt(20)
	ds_write2_b32 v0, v43, v44 offset0:148 offset1:214
	v_add_u32_e32 v0, 0xc00, v29
	s_waitcnt vmcnt(18)
	ds_write2_b32 v0, v45, v46 offset0:24 offset1:90
	s_waitcnt vmcnt(16)
	ds_write2_b32 v0, v47, v48 offset0:156 offset1:222
	v_add_u32_e32 v0, 0x1000, v29
	s_waitcnt vmcnt(14)
	ds_write2_b32 v0, v49, v50 offset0:32 offset1:98
	s_waitcnt vmcnt(12)
	ds_write2_b32 v0, v51, v52 offset0:164 offset1:230
	v_add_u32_e32 v0, 0x1400, v29
	s_waitcnt vmcnt(10)
	ds_write2_b32 v0, v53, v54 offset0:40 offset1:106
	s_waitcnt vmcnt(8)
	ds_write2_b32 v0, v55, v56 offset0:172 offset1:238
	v_add_u32_e32 v0, 0x1800, v29
	s_waitcnt vmcnt(6)
	ds_write2_b32 v0, v57, v58 offset0:48 offset1:114
	s_waitcnt vmcnt(4)
	ds_write2_b32 v0, v59, v60 offset0:180 offset1:246
	v_add_u32_e32 v0, 0x1c00, v29
	s_waitcnt vmcnt(2)
	ds_write2_b32 v0, v61, v62 offset0:56 offset1:122
	s_waitcnt vmcnt(0)
	ds_write2_b32 v0, v24, v20 offset0:188 offset1:254
	s_waitcnt lgkmcnt(0)
	ds_read2_b32 v[36:37], v31 offset0:33 offset1:41
	ds_read2_b32 v[38:39], v31 offset1:8
	ds_read2_b32 v[40:41], v31 offset0:66 offset1:74
	ds_read2_b32 v[42:43], v31 offset0:99 offset1:107
	ds_read2_b32 v[44:45], v31 offset0:132 offset1:140
	ds_read2_b32 v[46:47], v31 offset0:165 offset1:173
	ds_read2_b32 v[48:49], v31 offset0:198 offset1:206
	ds_read2_b32 v[50:51], v31 offset0:231 offset1:239
	v_lshlrev_b32_e32 v0, 1, v23
	v_lshl_add_u64 v[20:21], v[10:11], 0, v[0:1]
	v_or_b32_e32 v0, v22, v30
	v_lshlrev_b32_e32 v0, 11, v0
	v_lshl_add_u64 v[52:53], v[20:21], 0, v[0:1]
	v_or_b32_e32 v0, v22, v32
	s_waitcnt lgkmcnt(6)
	v_cvt_pk_bf16_f32 v24, v38, v36
	s_waitcnt lgkmcnt(4)
	v_cvt_pk_bf16_f32 v25, v40, v42
	s_waitcnt lgkmcnt(2)
	v_cvt_pk_bf16_f32 v26, v44, v46
	s_waitcnt lgkmcnt(0)
	v_cvt_pk_bf16_f32 v27, v48, v50
	v_lshlrev_b32_e32 v0, 11, v0
	global_store_dwordx4 v[52:53], v[24:27], off
	s_nop 1
	v_cvt_pk_bf16_f32 v24, v39, v37
	v_cvt_pk_bf16_f32 v25, v41, v43
	v_cvt_pk_bf16_f32 v26, v45, v47
	v_cvt_pk_bf16_f32 v27, v49, v51
	v_lshl_add_u64 v[36:37], v[20:21], 0, v[0:1]
	global_store_dwordx4 v[36:37], v[24:27], off
	ds_read2_b32 v[36:37], v31 offset0:49 offset1:57
	ds_read2_b32 v[38:39], v31 offset0:16 offset1:24
	ds_read2_b32 v[40:41], v31 offset0:82 offset1:90
	ds_read2_b32 v[42:43], v31 offset0:115 offset1:123
	ds_read2_b32 v[44:45], v31 offset0:148 offset1:156
	ds_read2_b32 v[46:47], v31 offset0:181 offset1:189
	ds_read2_b32 v[48:49], v31 offset0:214 offset1:222
	ds_read2_b32 v[50:51], v31 offset0:247 offset1:255
	v_or_b32_e32 v0, v22, v33
	v_lshlrev_b32_e32 v0, 11, v0
	v_lshl_add_u64 v[52:53], v[20:21], 0, v[0:1]
	v_or_b32_e32 v0, v22, v34
	s_waitcnt lgkmcnt(6)
	v_cvt_pk_bf16_f32 v24, v38, v36
	s_waitcnt lgkmcnt(4)
	v_cvt_pk_bf16_f32 v25, v40, v42
	s_waitcnt lgkmcnt(2)
	v_cvt_pk_bf16_f32 v26, v44, v46
	s_waitcnt lgkmcnt(0)
	v_cvt_pk_bf16_f32 v27, v48, v50
	v_lshlrev_b32_e32 v0, 11, v0
	global_store_dwordx4 v[52:53], v[24:27], off
	v_lshl_add_u64 v[20:21], v[20:21], 0, v[0:1]
	s_nop 0
	v_cvt_pk_bf16_f32 v24, v39, v37
	v_cvt_pk_bf16_f32 v25, v41, v43
	v_cvt_pk_bf16_f32 v26, v45, v47
	v_cvt_pk_bf16_f32 v27, v49, v51
	global_store_dwordx4 v[20:21], v[24:27], off
	s_waitcnt lgkmcnt(0)

; #define LAS __attribute__((address_space(3)))
; #define scr (p.ws + opq_off(SCR_OFF))
; DI void transpose_item(const float* W, int K, int ldw, int nblk, bf16_t* WT, LAS float* scr, int item, int lane) {
;     const int kb = item / nblk, nb = item % nblk, k0 = 64 * kb, n0 = 32 * nb;
;     float wv_[32];
; #pragma unroll
;     for (int i = 0; i < 32; ++i) { const int kk = 2 * i + (lane >> 5); wv_[i] = W[(size_t)(k0 + kk) * ldw + n0 + (lane & 31)]; }
; #pragma unroll
;     for (int i = 0; i < 32; ++i) { const int kk = 2 * i + (lane >> 5); scr[kk * 33 + (lane & 31)] = wv_[i]; }
; DI void wprep_layer(int wv, LAS unsigned char* lds, const Params& p, int layer, bf16_t* wb) {
;     ...
;         if (r < I0) { transpose_item(w_in, 1024, ldw_in, nin / 32, wb, scr, r, lane); continue; } r -= I0;
;         if (r < I1) { transpose_item(w_out, 1024, 1024, 32, wb_out, scr, r, lane); continue; } r -= I1;
.LBB0_618:
	s_andn2_saveexec_b64 s[8:9], s[8:9]
	s_cbranch_execz .LBB0_620
	v_ashrrev_i32_e32 v20, 31, v0
	v_lshrrev_b32_e32 v20, 27, v20
	v_add_u32_e32 v20, v0, v20
	v_and_b32_e32 v21, 0x7ffffe0, v20
	v_lshlrev_b32_e32 v20, 1, v20
	v_sub_u32_e32 v0, v0, v21
	v_and_b32_e32 v22, 0xffffffc0, v20
	v_lshlrev_b32_e32 v20, 5, v0
	v_or_b32_e32 v26, v22, v28
	v_ashrrev_i32_e32 v21, 31, v20
	v_ashrrev_i32_e32 v27, 31, v26
	v_lshl_add_u64 v[24:25], v[20:21], 2, v[12:13]
	v_lshlrev_b64 v[36:37], 12, v[26:27]
	v_lshl_add_u64 v[36:37], v[24:25], 0, v[36:37]
	global_load_dword v0, v[36:37], off nt
	v_or_b32_e32 v36, 2, v26
	v_ashrrev_i32_e32 v37, 31, v36
	v_lshlrev_b64 v[36:37], 12, v[36:37]
	v_lshl_add_u64 v[36:37], v[24:25], 0, v[36:37]
	global_load_dword v21, v[36:37], off nt
	v_or_b32_e32 v36, 4, v26
	v_ashrrev_i32_e32 v37, 31, v36
	v_lshlrev_b64 v[36:37], 12, v[36:37]
	v_lshl_add_u64 v[36:37], v[24:25], 0, v[36:37]
	global_load_dword v23, v[36:37], off nt
	v_or_b32_e32 v36, 6, v26
	v_ashrrev_i32_e32 v37, 31, v36
	v_lshlrev_b64 v[36:37], 12, v[36:37]
	v_lshl_add_u64 v[36:37], v[24:25], 0, v[36:37]
	global_load_dword v38, v[36:37], off nt
	v_or_b32_e32 v36, 8, v26
	v_ashrrev_i32_e32 v37, 31, v36
	v_lshlrev_b64 v[36:37], 12, v[36:37]
	v_lshl_add_u64 v[36:37], v[24:25], 0, v[36:37]
	global_load_dword v39, v[36:37], off nt
	v_or_b32_e32 v36, 10, v26
	v_ashrrev_i32_e32 v37, 31, v36
	v_lshlrev_b64 v[36:37], 12, v[36:37]
	v_lshl_add_u64 v[36:37], v[24:25], 0, v[36:37]
	global_load_dword v40, v[36:37], off nt
	v_or_b32_e32 v36, 12, v26
	v_ashrrev_i32_e32 v37, 31, v36
	v_lshlrev_b64 v[36:37], 12, v[36:37]
	v_lshl_add_u64 v[36:37], v[24:25], 0, v[36:37]
	global_load_dword v41, v[36:37], off nt
	v_or_b32_e32 v36, 14, v26
	v_ashrrev_i32_e32 v37, 31, v36
	v_lshlrev_b64 v[36:37], 12, v[36:37]
	v_lshl_add_u64 v[36:37], v[24:25], 0, v[36:37]
	global_load_dword v42, v[36:37], off nt
	v_or_b32_e32 v36, 16, v26
	v_ashrrev_i32_e32 v37, 31, v36
	v_lshlrev_b64 v[36:37], 12, v[36:37]
	v_lshl_add_u64 v[36:37], v[24:25], 0, v[36:37]
	global_load_dword v43, v[36:37], off nt
	v_or_b32_e32 v36, 18, v26
	v_ashrrev_i32_e32 v37, 31, v36
	v_lshlrev_b64 v[36:37], 12, v[36:37]
	v_lshl_add_u64 v[36:37], v[24:25], 0, v[36:37]
	global_load_dword v44, v[36:37], off nt
	v_or_b32_e32 v36, 20, v26
	v_ashrrev_i32_e32 v37, 31, v36
	v_lshlrev_b64 v[36:37], 12, v[36:37]
	v_lshl_add_u64 v[36:37], v[24:25], 0, v[36:37]
	global_load_dword v45, v[36:37], off nt
	v_or_b32_e32 v36, 22, v26
	v_ashrrev_i32_e32 v37, 31, v36
	v_lshlrev_b64 v[36:37], 12, v[36:37]
	v_lshl_add_u64 v[36:37], v[24:25], 0, v[36:37]
	global_load_dword v46, v[36:37], off nt
	v_or_b32_e32 v36, 24, v26
	v_ashrrev_i32_e32 v37, 31, v36
	v_lshlrev_b64 v[36:37], 12, v[36:37]
	v_lshl_add_u64 v[36:37], v[24:25], 0, v[36:37]
	global_load_dword v47, v[36:37], off nt
	v_or_b32_e32 v36, 26, v26
	v_ashrrev_i32_e32 v37, 31, v36
	v_lshlrev_b64 v[36:37], 12, v[36:37]
	v_lshl_add_u64 v[36:37], v[24:25], 0, v[36:37]
	global_load_dword v48, v[36:37], off nt
	v_or_b32_e32 v36, 28, v26
	v_ashrrev_i32_e32 v37, 31, v36
	v_lshlrev_b64 v[36:37], 12, v[36:37]
	v_lshl_add_u64 v[36:37], v[24:25], 0, v[36:37]
	global_load_dword v49, v[36:37], off nt
	v_or_b32_e32 v36, 30, v26
	v_ashrrev_i32_e32 v37, 31, v36
	v_lshlrev_b64 v[36:37], 12, v[36:37]
	v_lshl_add_u64 v[36:37], v[24:25], 0, v[36:37]
	global_load_dword v50, v[36:37], off nt
	v_or_b32_e32 v36, 32, v26
	v_ashrrev_i32_e32 v37, 31, v36
	v_lshlrev_b64 v[36:37], 12, v[36:37]
	v_lshl_add_u64 v[36:37], v[24:25], 0, v[36:37]
	global_load_dword v51, v[36:37], off nt
	v_or_b32_e32 v36, 34, v26
	v_ashrrev_i32_e32 v37, 31, v36
	v_lshlrev_b64 v[36:37], 12, v[36:37]
	v_lshl_add_u64 v[36:37], v[24:25], 0, v[36:37]
	global_load_dword v52, v[36:37], off nt
	v_or_b32_e32 v36, 36, v26
	v_ashrrev_i32_e32 v37, 31, v36
	v_lshlrev_b64 v[36:37], 12, v[36:37]
	v_lshl_add_u64 v[36:37], v[24:25], 0, v[36:37]
	global_load_dword v53, v[36:37], off nt
	v_or_b32_e32 v36, 38, v26
	v_ashrrev_i32_e32 v37, 31, v36
	v_lshlrev_b64 v[36:37], 12, v[36:37]
	v_lshl_add_u64 v[36:37], v[24:25], 0, v[36:37]
	global_load_dword v54, v[36:37], off nt
	v_or_b32_e32 v36, 40, v26
	v_ashrrev_i32_e32 v37, 31, v36
	v_lshlrev_b64 v[36:37], 12, v[36:37]
	v_lshl_add_u64 v[36:37], v[24:25], 0, v[36:37]
	global_load_dword v55, v[36:37], off nt
	v_or_b32_e32 v36, 42, v26
	v_ashrrev_i32_e32 v37, 31, v36
	v_lshlrev_b64 v[36:37], 12, v[36:37]
	v_lshl_add_u64 v[36:37], v[24:25], 0, v[36:37]
	global_load_dword v56, v[36:37], off nt
	v_or_b32_e32 v36, 44, v26
	v_ashrrev_i32_e32 v37, 31, v36
	v_lshlrev_b64 v[36:37], 12, v[36:37]
	v_lshl_add_u64 v[36:37], v[24:25], 0, v[36:37]
	global_load_dword v57, v[36:37], off nt
	v_or_b32_e32 v36, 46, v26
	v_ashrrev_i32_e32 v37, 31, v36
	v_lshlrev_b64 v[36:37], 12, v[36:37]
	v_lshl_add_u64 v[36:37], v[24:25], 0, v[36:37]
	global_load_dword v58, v[36:37], off nt
	v_or_b32_e32 v36, 48, v26
	v_ashrrev_i32_e32 v37, 31, v36
	v_lshlrev_b64 v[36:37], 12, v[36:37]
	v_lshl_add_u64 v[36:37], v[24:25], 0, v[36:37]
	global_load_dword v59, v[36:37], off nt
	v_or_b32_e32 v36, 50, v26
	v_ashrrev_i32_e32 v37, 31, v36
	v_lshlrev_b64 v[36:37], 12, v[36:37]
	v_lshl_add_u64 v[36:37], v[24:25], 0, v[36:37]
	global_load_dword v60, v[36:37], off nt
	v_or_b32_e32 v36, 52, v26
	v_ashrrev_i32_e32 v37, 31, v36
	v_lshlrev_b64 v[36:37], 12, v[36:37]
	v_lshl_add_u64 v[36:37], v[24:25], 0, v[36:37]
	global_load_dword v61, v[36:37], off nt
	v_or_b32_e32 v36, 54, v26
	v_ashrrev_i32_e32 v37, 31, v36
	v_lshlrev_b64 v[36:37], 12, v[36:37]
	v_lshl_add_u64 v[36:37], v[24:25], 0, v[36:37]
	global_load_dword v62, v[36:37], off nt
	v_or_b32_e32 v36, 56, v26
	v_ashrrev_i32_e32 v37, 31, v36
	v_lshlrev_b64 v[36:37], 12, v[36:37]
	v_lshl_add_u64 v[36:37], v[24:25], 0, v[36:37]
	global_load_dword v63, v[36:37], off nt
	v_or_b32_e32 v36, 58, v26
	v_ashrrev_i32_e32 v37, 31, v36
	v_lshlrev_b64 v[36:37], 12, v[36:37]
	v_lshl_add_u64 v[36:37], v[24:25], 0, v[36:37]
	global_load_dword v64, v[36:37], off nt
	v_or_b32_e32 v36, 60, v26
	v_or_b32_e32 v26, 62, v26
	v_ashrrev_i32_e32 v37, 31, v36
	v_ashrrev_i32_e32 v27, 31, v26
	v_lshlrev_b64 v[36:37], 12, v[36:37]
	v_lshlrev_b64 v[26:27], 12, v[26:27]
	v_lshl_add_u64 v[36:37], v[24:25], 0, v[36:37]
	v_lshl_add_u64 v[24:25], v[24:25], 0, v[26:27]
	global_load_dword v36, v[36:37], off nt
	s_nop 0
	global_load_dword v24, v[24:25], off nt
	s_waitcnt vmcnt(30)
; #define LAS __attribute__((address_space(3)))
; DI unsigned pk2(float lo, float hi) { f32x2 f = {lo, hi}; bf2_t v = __builtin_convertvector(f, bf2_t); return __builtin_bit_cast(unsigned, v); }
; #define scr (p.ws + opq_off(SCR_OFF))
; DI void transpose_item(const float* W, int K, int ldw, int nblk, bf16_t* WT, LAS float* scr, int item, int lane) {
;     ...
;     for (int i = 0; i < 32; ++i) { const int kk = 2 * i + (lane >> 5); scr[kk * 33 + (lane & 31)] = wv_[i]; }
;     asm volatile("s_waitcnt lgkmcnt(0)" ::: "memory");
;     const int c = lane & 7;
; #pragma unroll
;     for (int j = 0; j < 4; ++j) { const int n = (lane >> 3) + 8 * j; const LAS float* s = scr + (8 * c) * 33 + n;
;         u32x4 o; o.x = pk2(s[0 * 33], s[1 * 33]); o.y = pk2(s[2 * 33], s[3 * 33]); o.z = pk2(s[4 * 33], s[5 * 33]); o.w = pk2(s[6 * 33], s[7 * 33]);
;         *(u32x4*)(WT + (size_t)(n0 + n) * K + k0 + 8 * c) = o; }
;     asm volatile("s_waitcnt lgkmcnt(0)" ::: "memory");
	ds_write2_b32 v29, v0, v21 offset1:66
	s_waitcnt vmcnt(28)
	ds_write2_b32 v29, v23, v38 offset0:132 offset1:198
	v_add_u32_e32 v0, 0x400, v29
	s_waitcnt vmcnt(26)
	ds_write2_b32 v0, v39, v40 offset0:8 offset1:74
	s_waitcnt vmcnt(24)
	ds_write2_b32 v0, v41, v42 offset0:140 offset1:206
	v_add_u32_e32 v0, 0x800, v29
	s_waitcnt vmcnt(22)
	ds_write2_b32 v0, v43, v44 offset0:16 offset1:82
	s_waitcnt vmcnt(20)
	ds_write2_b32 v0, v45, v46 offset0:148 offset1:214
	v_add_u32_e32 v0, 0xc00, v29
	s_waitcnt vmcnt(18)
	ds_write2_b32 v0, v47, v48 offset0:24 offset1:90
	s_waitcnt vmcnt(16)
	ds_write2_b32 v0, v49, v50 offset0:156 offset1:222
	v_add_u32_e32 v0, 0x1000, v29
	s_waitcnt vmcnt(14)
	ds_write2_b32 v0, v51, v52 offset0:32 offset1:98
	s_waitcnt vmcnt(12)
	ds_write2_b32 v0, v53, v54 offset0:164 offset1:230
	v_add_u32_e32 v0, 0x1400, v29
	s_waitcnt vmcnt(10)
	ds_write2_b32 v0, v55, v56 offset0:40 offset1:106
	s_waitcnt vmcnt(8)
	ds_write2_b32 v0, v57, v58 offset0:172 offset1:238
	v_add_u32_e32 v0, 0x1800, v29
	s_waitcnt vmcnt(6)
	ds_write2_b32 v0, v59, v60 offset0:48 offset1:114
	s_waitcnt vmcnt(4)
	ds_write2_b32 v0, v61, v62 offset0:180 offset1:246
	v_add_u32_e32 v0, 0x1c00, v29
	s_waitcnt vmcnt(2)
	ds_write2_b32 v0, v63, v64 offset0:56 offset1:122
	s_waitcnt vmcnt(0)
	ds_write2_b32 v0, v36, v24 offset0:188 offset1:254
	s_waitcnt lgkmcnt(0)
	ds_read2_b32 v[36:37], v31 offset0:33 offset1:41
	ds_read2_b32 v[38:39], v31 offset1:8
	ds_read2_b32 v[40:41], v31 offset0:66 offset1:74
	ds_read2_b32 v[42:43], v31 offset0:99 offset1:107
	ds_read2_b32 v[44:45], v31 offset0:132 offset1:140
	ds_read2_b32 v[46:47], v31 offset0:165 offset1:173
	ds_read2_b32 v[48:49], v31 offset0:198 offset1:206
	ds_read2_b32 v[50:51], v31 offset0:231 offset1:239
	v_or_b32_e32 v52, v20, v30
	v_ashrrev_i32_e32 v23, 31, v22
	v_ashrrev_i32_e32 v53, 31, v52
	v_lshl_add_u64 v[26:27], v[22:23], 1, v[4:5]
	v_lshlrev_b64 v[52:53], 11, v[52:53]
	s_waitcnt lgkmcnt(6)
	v_cvt_pk_bf16_f32 v22, v38, v36
	s_waitcnt lgkmcnt(4)
	v_cvt_pk_bf16_f32 v23, v40, v42
	s_waitcnt lgkmcnt(2)
	v_cvt_pk_bf16_f32 v24, v44, v46
	s_waitcnt lgkmcnt(0)
	v_cvt_pk_bf16_f32 v25, v48, v50
	v_lshl_add_u64 v[52:53], v[26:27], 0, v[52:53]
	v_or_b32_e32 v36, v20, v32
	global_store_dwordx4 v[52:53], v[22:25], off
	v_or_b32_e32 v52, v20, v33
	v_ashrrev_i32_e32 v53, 31, v52
	v_cvt_pk_bf16_f32 v22, v39, v37
	v_ashrrev_i32_e32 v37, 31, v36
	v_lshlrev_b64 v[36:37], 11, v[36:37]
	v_cvt_pk_bf16_f32 v23, v41, v43
	v_cvt_pk_bf16_f32 v24, v45, v47
	v_cvt_pk_bf16_f32 v25, v49, v51
	v_lshl_add_u64 v[36:37], v[26:27], 0, v[36:37]
	global_store_dwordx4 v[36:37], v[22:25], off
	ds_read2_b32 v[36:37], v31 offset0:49 offset1:57
	ds_read2_b32 v[38:39], v31 offset0:16 offset1:24
	ds_read2_b32 v[40:41], v31 offset0:82 offset1:90
	ds_read2_b32 v[42:43], v31 offset0:115 offset1:123
	ds_read2_b32 v[44:45], v31 offset0:148 offset1:156
	ds_read2_b32 v[46:47], v31 offset0:181 offset1:189
	ds_read2_b32 v[48:49], v31 offset0:214 offset1:222
	ds_read2_b32 v[50:51], v31 offset0:247 offset1:255
	v_or_b32_e32 v20, v20, v34
	v_lshlrev_b64 v[52:53], 11, v[52:53]
	v_ashrrev_i32_e32 v21, 31, v20
	s_waitcnt lgkmcnt(6)
	v_cvt_pk_bf16_f32 v22, v38, v36
	s_waitcnt lgkmcnt(4)
	v_cvt_pk_bf16_f32 v23, v40, v42
	s_waitcnt lgkmcnt(2)
	v_cvt_pk_bf16_f32 v24, v44, v46
	s_waitcnt lgkmcnt(0)
	v_cvt_pk_bf16_f32 v25, v48, v50
	v_lshl_add_u64 v[52:53], v[26:27], 0, v[52:53]
	v_lshlrev_b64 v[20:21], 11, v[20:21]
	global_store_dwordx4 v[52:53], v[22:25], off
	v_lshl_add_u64 v[20:21], v[26:27], 0, v[20:21]
	s_nop 0
	v_cvt_pk_bf16_f32 v22, v39, v37
	v_cvt_pk_bf16_f32 v23, v41, v43
	v_cvt_pk_bf16_f32 v24, v45, v47
	v_cvt_pk_bf16_f32 v25, v49, v51
	global_store_dwordx4 v[20:21], v[22:25], off
	s_waitcnt lgkmcnt(0)

; #define LAS __attribute__((address_space(3)))
; #define scr (p.ws + opq_off(SCR_OFF))
; DI void transpose_item(const float* W, int K, int ldw, int nblk, bf16_t* WT, LAS float* scr, int item, int lane) {
;     const int kb = item / nblk, nb = item % nblk, k0 = 64 * kb, n0 = 32 * nb;
;     float wv_[32];
; #pragma unroll
;     for (int i = 0; i < 32; ++i) { const int kk = 2 * i + (lane >> 5); wv_[i] = W[(size_t)(k0 + kk) * ldw + n0 + (lane & 31)]; }
; #pragma unroll
;     for (int i = 0; i < 32; ++i) { const int kk = 2 * i + (lane >> 5); scr[kk * 33 + (lane & 31)] = wv_[i]; }
; DI void wprep_layer(int wv, LAS unsigned char* lds, const Params& p, int layer, bf16_t* wb) {
;     ...
;         if (r < I0) { transpose_item(w_in, 1024, ldw_in, nin / 32, wb, scr, r, lane); continue; } r -= I0;
.LBB0_621:
	s_andn2_saveexec_b64 s[6:7], s[6:7]
	s_cbranch_execz .LBB0_610
	v_sub_u32_e32 v20, 0, v19
	v_max_i32_e32 v20, v19, v20
	v_mul_hi_u32 v21, v20, v142
	v_mul_lo_u32 v22, v21, s43
	v_sub_u32_e32 v20, v20, v22
	v_cmp_le_u32_e32 vcc, s43, v20
	v_add_u32_e32 v22, 1, v21
	v_ashrrev_i32_e32 v0, 31, v19
	v_cndmask_b32_e32 v21, v21, v22, vcc
	v_subrev_u32_e32 v22, s43, v20
	v_cndmask_b32_e32 v20, v20, v22, vcc
	v_cmp_le_u32_e32 vcc, s43, v20
	v_add_u32_e32 v20, 1, v21
	s_nop 0
	v_cndmask_b32_e32 v20, v21, v20, vcc
	v_xor_b32_e32 v20, v20, v0
	v_sub_u32_e32 v0, v20, v0
	v_lshlrev_b32_e32 v22, 6, v0
	v_mad_u64_u32 v[20:21], s[8:9], s72, v0, v[18:19]
	v_or_b32_e32 v0, v22, v28
	v_ashrrev_i32_e32 v21, 31, v20
	v_lshl_add_u64 v[24:25], v[20:21], 2, v[14:15]
	v_mad_i64_i32 v[26:27], s[8:9], s42, v0, 0
	v_lshl_add_u64 v[26:27], v[26:27], 2, v[24:25]
	v_or_b32_e32 v23, 2, v0
	global_load_dword v21, v[26:27], off nt
	v_mad_i64_i32 v[26:27], s[8:9], s42, v23, 0
	v_lshl_add_u64 v[26:27], v[26:27], 2, v[24:25]
	global_load_dword v23, v[26:27], off nt
	v_or_b32_e32 v26, 4, v0
	v_mad_i64_i32 v[26:27], s[8:9], s42, v26, 0
	v_lshl_add_u64 v[26:27], v[26:27], 2, v[24:25]
	global_load_dword v36, v[26:27], off nt
	v_or_b32_e32 v26, 6, v0
	v_mad_i64_i32 v[26:27], s[8:9], s42, v26, 0
	v_lshl_add_u64 v[26:27], v[26:27], 2, v[24:25]
	global_load_dword v37, v[26:27], off nt
	v_or_b32_e32 v26, 8, v0
	v_mad_i64_i32 v[26:27], s[8:9], s42, v26, 0
	v_lshl_add_u64 v[26:27], v[26:27], 2, v[24:25]
	global_load_dword v38, v[26:27], off nt
	v_or_b32_e32 v26, 10, v0
	v_mad_i64_i32 v[26:27], s[8:9], s42, v26, 0
	v_lshl_add_u64 v[26:27], v[26:27], 2, v[24:25]
	global_load_dword v39, v[26:27], off nt
	v_or_b32_e32 v26, 12, v0
	v_mad_i64_i32 v[26:27], s[8:9], s42, v26, 0
	v_lshl_add_u64 v[26:27], v[26:27], 2, v[24:25]
	global_load_dword v40, v[26:27], off nt
	v_or_b32_e32 v26, 14, v0
	v_mad_i64_i32 v[26:27], s[8:9], s42, v26, 0
	v_lshl_add_u64 v[26:27], v[26:27], 2, v[24:25]
	global_load_dword v41, v[26:27], off nt
	v_or_b32_e32 v26, 16, v0
	v_mad_i64_i32 v[26:27], s[8:9], s42, v26, 0
	v_lshl_add_u64 v[26:27], v[26:27], 2, v[24:25]
	global_load_dword v42, v[26:27], off nt
	v_or_b32_e32 v26, 18, v0
	v_mad_i64_i32 v[26:27], s[8:9], s42, v26, 0
	v_lshl_add_u64 v[26:27], v[26:27], 2, v[24:25]
	global_load_dword v43, v[26:27], off nt
	v_or_b32_e32 v26, 20, v0
	v_mad_i64_i32 v[26:27], s[8:9], s42, v26, 0
	v_lshl_add_u64 v[26:27], v[26:27], 2, v[24:25]
	global_load_dword v44, v[26:27], off nt
	v_or_b32_e32 v26, 22, v0
	v_mad_i64_i32 v[26:27], s[8:9], s42, v26, 0
	v_lshl_add_u64 v[26:27], v[26:27], 2, v[24:25]
	global_load_dword v45, v[26:27], off nt
	v_or_b32_e32 v26, 24, v0
	v_mad_i64_i32 v[26:27], s[8:9], s42, v26, 0
	v_lshl_add_u64 v[26:27], v[26:27], 2, v[24:25]
	global_load_dword v46, v[26:27], off nt
	v_or_b32_e32 v26, 26, v0
	v_mad_i64_i32 v[26:27], s[8:9], s42, v26, 0
	v_lshl_add_u64 v[26:27], v[26:27], 2, v[24:25]
	global_load_dword v47, v[26:27], off nt
	v_or_b32_e32 v26, 28, v0
	v_mad_i64_i32 v[26:27], s[8:9], s42, v26, 0
	v_lshl_add_u64 v[26:27], v[26:27], 2, v[24:25]
	global_load_dword v48, v[26:27], off nt
	v_or_b32_e32 v26, 30, v0
	v_mad_i64_i32 v[26:27], s[8:9], s42, v26, 0
	v_lshl_add_u64 v[26:27], v[26:27], 2, v[24:25]
	global_load_dword v49, v[26:27], off nt
	v_or_b32_e32 v26, 32, v0
	v_mad_i64_i32 v[26:27], s[8:9], s42, v26, 0
	v_lshl_add_u64 v[26:27], v[26:27], 2, v[24:25]
	global_load_dword v50, v[26:27], off nt
	v_or_b32_e32 v26, 34, v0
	v_mad_i64_i32 v[26:27], s[8:9], s42, v26, 0
	v_lshl_add_u64 v[26:27], v[26:27], 2, v[24:25]
	global_load_dword v51, v[26:27], off nt
	v_or_b32_e32 v26, 36, v0
	v_mad_i64_i32 v[26:27], s[8:9], s42, v26, 0
	v_lshl_add_u64 v[26:27], v[26:27], 2, v[24:25]
	global_load_dword v52, v[26:27], off nt
	v_or_b32_e32 v26, 38, v0
	v_mad_i64_i32 v[26:27], s[8:9], s42, v26, 0
	v_lshl_add_u64 v[26:27], v[26:27], 2, v[24:25]
	global_load_dword v53, v[26:27], off nt
	v_or_b32_e32 v26, 40, v0
	v_mad_i64_i32 v[26:27], s[8:9], s42, v26, 0
	v_lshl_add_u64 v[26:27], v[26:27], 2, v[24:25]
	global_load_dword v54, v[26:27], off nt
	v_or_b32_e32 v26, 42, v0
	v_mad_i64_i32 v[26:27], s[8:9], s42, v26, 0
	v_lshl_add_u64 v[26:27], v[26:27], 2, v[24:25]
	global_load_dword v55, v[26:27], off nt
	v_or_b32_e32 v26, 44, v0
	v_mad_i64_i32 v[26:27], s[8:9], s42, v26, 0
	v_lshl_add_u64 v[26:27], v[26:27], 2, v[24:25]
	global_load_dword v56, v[26:27], off nt
	v_or_b32_e32 v26, 46, v0
	v_mad_i64_i32 v[26:27], s[8:9], s42, v26, 0
	v_lshl_add_u64 v[26:27], v[26:27], 2, v[24:25]
	global_load_dword v57, v[26:27], off nt
	v_or_b32_e32 v26, 48, v0
	v_mad_i64_i32 v[26:27], s[8:9], s42, v26, 0
	v_lshl_add_u64 v[26:27], v[26:27], 2, v[24:25]
	global_load_dword v58, v[26:27], off nt
	v_or_b32_e32 v26, 50, v0
	v_mad_i64_i32 v[26:27], s[8:9], s42, v26, 0
	v_lshl_add_u64 v[26:27], v[26:27], 2, v[24:25]
	global_load_dword v59, v[26:27], off nt
	v_or_b32_e32 v26, 52, v0
	v_mad_i64_i32 v[26:27], s[8:9], s42, v26, 0
	v_lshl_add_u64 v[26:27], v[26:27], 2, v[24:25]
	global_load_dword v60, v[26:27], off nt
	v_or_b32_e32 v26, 54, v0
	v_mad_i64_i32 v[26:27], s[8:9], s42, v26, 0
	v_lshl_add_u64 v[26:27], v[26:27], 2, v[24:25]
	global_load_dword v61, v[26:27], off nt
	v_or_b32_e32 v26, 56, v0
	v_mad_i64_i32 v[26:27], s[8:9], s42, v26, 0
	v_lshl_add_u64 v[26:27], v[26:27], 2, v[24:25]
	global_load_dword v62, v[26:27], off nt
	v_or_b32_e32 v26, 58, v0
	v_mad_i64_i32 v[26:27], s[8:9], s42, v26, 0
	v_lshl_add_u64 v[26:27], v[26:27], 2, v[24:25]
	global_load_dword v63, v[26:27], off nt
	v_or_b32_e32 v26, 60, v0
	v_mad_i64_i32 v[26:27], s[8:9], s42, v26, 0
	v_lshl_add_u64 v[26:27], v[26:27], 2, v[24:25]
	v_or_b32_e32 v0, 62, v0
	global_load_dword v64, v[26:27], off nt
	v_mad_i64_i32 v[26:27], s[8:9], s42, v0, 0
	v_lshl_add_u64 v[24:25], v[26:27], 2, v[24:25]
	global_load_dword v0, v[24:25], off nt
	s_waitcnt vmcnt(30)
; #define LAS __attribute__((address_space(3)))
; DI unsigned pk2(float lo, float hi) { f32x2 f = {lo, hi}; bf2_t v = __builtin_convertvector(f, bf2_t); return __builtin_bit_cast(unsigned, v); }
; #define scr (p.ws + opq_off(SCR_OFF))
; DI void transpose_item(const float* W, int K, int ldw, int nblk, bf16_t* WT, LAS float* scr, int item, int lane) {
;     ...
;     for (int i = 0; i < 32; ++i) { const int kk = 2 * i + (lane >> 5); scr[kk * 33 + (lane & 31)] = wv_[i]; }
;     asm volatile("s_waitcnt lgkmcnt(0)" ::: "memory");
;     const int c = lane & 7;
; #pragma unroll
;     for (int j = 0; j < 4; ++j) { const int n = (lane >> 3) + 8 * j; const LAS float* s = scr + (8 * c) * 33 + n;
;         u32x4 o; o.x = pk2(s[0 * 33], s[1 * 33]); o.y = pk2(s[2 * 33], s[3 * 33]); o.z = pk2(s[4 * 33], s[5 * 33]); o.w = pk2(s[6 * 33], s[7 * 33]);
;         *(u32x4*)(WT + (size_t)(n0 + n) * K + k0 + 8 * c) = o; }
;     asm volatile("s_waitcnt lgkmcnt(0)" ::: "memory");
	ds_write2_b32 v29, v21, v23 offset1:66
	s_waitcnt vmcnt(28)
	ds_write2_b32 v29, v36, v37 offset0:132 offset1:198
	v_add_u32_e32 v21, 0x400, v29
	s_waitcnt vmcnt(26)
	ds_write2_b32 v21, v38, v39 offset0:8 offset1:74
	s_waitcnt vmcnt(24)
	ds_write2_b32 v21, v40, v41 offset0:140 offset1:206
	v_add_u32_e32 v21, 0x800, v29
	s_waitcnt vmcnt(22)
	ds_write2_b32 v21, v42, v43 offset0:16 offset1:82
	s_waitcnt vmcnt(20)
	ds_write2_b32 v21, v44, v45 offset0:148 offset1:214
	v_add_u32_e32 v21, 0xc00, v29
	s_waitcnt vmcnt(18)
	ds_write2_b32 v21, v46, v47 offset0:24 offset1:90
	s_waitcnt vmcnt(16)
	ds_write2_b32 v21, v48, v49 offset0:156 offset1:222
	v_add_u32_e32 v21, 0x1000, v29
	s_waitcnt vmcnt(14)
	ds_write2_b32 v21, v50, v51 offset0:32 offset1:98
	s_waitcnt vmcnt(12)
	ds_write2_b32 v21, v52, v53 offset0:164 offset1:230
	v_add_u32_e32 v21, 0x1400, v29
	s_waitcnt vmcnt(10)
	ds_write2_b32 v21, v54, v55 offset0:40 offset1:106
	s_waitcnt vmcnt(8)
	ds_write2_b32 v21, v56, v57 offset0:172 offset1:238
	v_add_u32_e32 v21, 0x1800, v29
	s_waitcnt vmcnt(6)
	ds_write2_b32 v21, v58, v59 offset0:48 offset1:114
	s_waitcnt vmcnt(4)
	ds_write2_b32 v21, v60, v61 offset0:180 offset1:246
	v_add_u32_e32 v21, 0x1c00, v29
	s_waitcnt vmcnt(2)
	ds_write2_b32 v21, v62, v63 offset0:56 offset1:122
	s_waitcnt vmcnt(0)
	ds_write2_b32 v21, v64, v0 offset0:188 offset1:254
	s_waitcnt lgkmcnt(0)
	ds_read2_b32 v[36:37], v31 offset0:33 offset1:41
	ds_read2_b32 v[38:39], v31 offset1:8
	ds_read2_b32 v[40:41], v31 offset0:66 offset1:74
	ds_read2_b32 v[42:43], v31 offset0:99 offset1:107
	ds_read2_b32 v[44:45], v31 offset0:132 offset1:140
	ds_read2_b32 v[46:47], v31 offset0:165 offset1:173
	ds_read2_b32 v[48:49], v31 offset0:198 offset1:206
	ds_read2_b32 v[50:51], v31 offset0:231 offset1:239
	v_add_u32_e32 v52, v20, v30
	v_ashrrev_i32_e32 v23, 31, v22
	v_ashrrev_i32_e32 v53, 31, v52
	v_lshl_add_u64 v[26:27], v[22:23], 1, v[16:17]
	v_lshlrev_b64 v[20:21], 11, v[52:53]
	s_waitcnt lgkmcnt(6)
	v_cvt_pk_bf16_f32 v22, v38, v36
	s_waitcnt lgkmcnt(4)
	v_cvt_pk_bf16_f32 v23, v40, v42
	s_waitcnt lgkmcnt(2)
	v_cvt_pk_bf16_f32 v24, v44, v46
	s_waitcnt lgkmcnt(0)
	v_cvt_pk_bf16_f32 v25, v48, v50
	v_lshl_add_u64 v[20:21], v[26:27], 0, v[20:21]
	global_store_dwordx4 v[20:21], v[22:25], off
	v_cvt_pk_bf16_f32 v20, v39, v37
	v_cvt_pk_bf16_f32 v21, v41, v43
	v_add_u32_e32 v24, 8, v52
	v_ashrrev_i32_e32 v25, 31, v24
	v_lshlrev_b64 v[24:25], 11, v[24:25]
	v_cvt_pk_bf16_f32 v22, v45, v47
	v_cvt_pk_bf16_f32 v23, v49, v51
	v_lshl_add_u64 v[24:25], v[26:27], 0, v[24:25]
	global_store_dwordx4 v[24:25], v[20:23], off
	ds_read2_b32 v[24:25], v31 offset0:49 offset1:57
	ds_read2_b32 v[36:37], v31 offset0:16 offset1:24
	ds_read2_b32 v[38:39], v31 offset0:82 offset1:90
	ds_read2_b32 v[40:41], v31 offset0:115 offset1:123
	ds_read2_b32 v[42:43], v31 offset0:148 offset1:156
	ds_read2_b32 v[44:45], v31 offset0:181 offset1:189
	ds_read2_b32 v[46:47], v31 offset0:214 offset1:222
	ds_read2_b32 v[48:49], v31 offset0:247 offset1:255
	v_add_u32_e32 v50, 16, v52
	v_ashrrev_i32_e32 v51, 31, v50
	v_lshlrev_b64 v[50:51], 11, v[50:51]
	s_waitcnt lgkmcnt(6)
	v_cvt_pk_bf16_f32 v20, v36, v24
	s_waitcnt lgkmcnt(4)
	v_cvt_pk_bf16_f32 v21, v38, v40
	s_waitcnt lgkmcnt(2)
	v_cvt_pk_bf16_f32 v22, v42, v44
	s_waitcnt lgkmcnt(0)
	v_cvt_pk_bf16_f32 v23, v46, v48
	v_lshl_add_u64 v[50:51], v[26:27], 0, v[50:51]
	v_add_u32_e32 v24, 24, v52
	global_store_dwordx4 v[50:51], v[20:23], off
	s_nop 1
	v_cvt_pk_bf16_f32 v20, v37, v25
	v_ashrrev_i32_e32 v25, 31, v24
	v_lshlrev_b64 v[24:25], 11, v[24:25]
	v_cvt_pk_bf16_f32 v21, v39, v41
	v_cvt_pk_bf16_f32 v22, v43, v45
	v_cvt_pk_bf16_f32 v23, v47, v49
	v_lshl_add_u64 v[24:25], v[26:27], 0, v[24:25]
	global_store_dwordx4 v[24:25], v[20:23], off
	s_waitcnt lgkmcnt(0)
	s_branch .LBB0_610
